# 16-byte GEMM epilogue stores of P1 P5 P6 P8 made write-through (sc1) so the grid barrier's L2 writeback has less to flush
# speedup vs baseline: 1.0343x; 1.0065x over previous
; __device__ __forceinline__ unsigned cvt_pk_bf16(float lo, float hi) { unsigned r; asm volatile("v_cvt_pk_bf16_f32 %0, %1, %2" : "=v"(r) : "v"(lo), "v"(hi)); return r; }
;     __device__ __forceinline__ void operator()(const f32x4 (&acc)[2][2][4][2], const Unit& u, int wr, int wc, int fr, int fq) const {
;     ...
;                 const int r = u.pm * BM + ai * HALF + wr * 64 + m * 16 + fr;
; #pragma unroll
;                 for (int bj = 0; bj < 2; ++bj) {
;                     const int c8 = u.pn * BM + bj * HALF + wc * 32 + 8 * fq;
;                     const f32x4 v0 = acc[ai][bj][m][0], v1 = acc[ai][bj][m][1];
;                     u32x4 w; w.x = cvt_pk_bf16(v0[0], v0[1]); w.y = cvt_pk_bf16(v0[2], v0[3]); w.z = cvt_pk_bf16(v1[0], v1[1]); w.w = cvt_pk_bf16(v1[2], v1[3]);
;                     if (reg == 0) { *(u32x4*)(Qb + (size_t)r * SBW + c8) = w; }
;                     else if (reg == 1) { const int c = c8 - O_SB_K; *(u32x4*)(Kb + (size_t)r * SBW + c) = w; float* o = outK + (size_t)r * SBW + c; __builtin_nontemporal_store(v0, (f32x4*)o); __builtin_nontemporal_store(v1, (f32x4*)(o + 4)); }
;                     else if (reg == 2) { const int c = c8 - O_SB_V; *(u32x4*)(Vb + (size_t)r * SBW + c) = w; float* o = outV + (size_t)r * SBW + c; __builtin_nontemporal_store(v0, (f32x4*)o); __builtin_nontemporal_store(v1, (f32x4*)(o + 4)); }
;                     else if (reg < 6) { const int c = c8 - O_GQKV; *(u32x4*)(CIN + (size_t)r * CONVCH + c) = w;
;                         const int t = r & (T - 1); if (t >= T - 3) { float* o = outGconv + ((size_t)(r >> 12) * 3 + (t - (T - 3))) * CONVCH + c; *(f32x4*)o = v0; *(f32x4*)(o + 4) = v1; } }
.LBB0_183:
	s_ashr_i32 s46, s47, 2
	s_cmp_gt_u32 s47, 3
	s_cselect_b64 s[18:19], -1, 0
	s_cmp_gt_i32 s46, 5
	s_cselect_b64 s[80:81], -1, 0
	s_cmp_eq_u32 s46, 6
	s_cselect_b64 s[78:79], -1, 0
	s_cmp_lg_u32 s46, 6
	s_cselect_b64 s[82:83], -1, 0
	s_lshl_b32 s2, s14, 8
	v_mov_b32_e32 v130, v1
	v_mov_b32_e32 v132, v174
	s_add_i32 s2, s2, s4
	s_and_b64 vcc, exec, s[18:19]
	v_add_u32_e32 v162, s2, v130
	v_ashrrev_i32_e32 v130, 12, v162
	v_and_b32_e32 v133, 0xfff, v162
	v_mul_i32_i24_e32 v130, 3, v130
	v_ashrrev_i32_e32 v131, 31, v130
	v_add_u32_e32 v150, 0xfffff003, v133
	v_lshl_add_u64 v[130:131], v[130:131], 0, v[150:151]
	s_lshl_b32 s2, s47, 8
	v_ashrrev_i32_e32 v163, 31, v162
	v_mad_i64_i32 v[166:167], s[14:15], v162, s31, 0
	v_mad_u64_u32 v[168:169], s[14:15], v130, s29, 0
	s_or_b32 s2, s2, s5
	v_cmp_gt_i32_e64 s[12:13], 2, v132
	v_cmp_eq_u32_e64 s[10:11], 0, v132
	v_cmp_ne_u32_e64 s[8:9], 0, v132
	v_lshlrev_b64 v[164:165], 10, v[162:163]
	v_lshlrev_b64 v[170:171], 11, v[162:163]
	v_cmp_lt_u32_e64 s[16:17], s28, v133
	v_mad_i32_i24 v169, v131, s29, v169
	v_lshl_add_u32 v160, v132, 3, s2
	s_mov_b64 s[14:15], -1
	v_cvt_pk_bf16_f32 v130, v122, v123
	v_cvt_pk_bf16_f32 v131, v124, v125
	v_cvt_pk_bf16_f32 v132, v126, v127
	v_cvt_pk_bf16_f32 v133, v128, v129
	s_cbranch_vccz .LBB0_241
	s_mov_b64 s[86:87], -1
	s_mov_b64 s[14:15], 0
	s_cmp_lt_i32 s46, 2
	s_mov_b64 s[84:85], 0
	s_cbranch_scc1 .LBB0_236
	s_cmp_eq_u32 s46, 2
	s_mov_b64 s[84:85], -1
	s_cbranch_scc0 .LBB0_187
	v_lshl_add_u64 v[134:135], v[164:165], 1, s[52:53]
	v_ashrrev_i32_e32 v161, 31, v160
	v_lshl_add_u64 v[134:135], v[160:161], 1, v[134:135]
	global_store_dwordx4 v[134:135], v[130:133], off offset:-4096 sc1
	v_lshl_add_u64 v[134:135], v[164:165], 2, s[60:61]
	s_movk_i32 s84, 0xe000
	v_lshl_add_u64 v[134:135], v[160:161], 2, v[134:135]
	s_mov_b32 s85, -1
	v_lshl_add_u64 v[136:137], v[134:135], 0, s[84:85]
	v_add_co_u32_e32 v134, vcc, 0xffffe000, v134
	s_mov_b64 s[84:85], 0
	s_nop 0
	v_addc_co_u32_e32 v135, vcc, -1, v135, vcc
	global_store_dwordx4 v[134:135], v[122:125], off nt
	global_store_dwordx4 v[136:137], v[126:129], off offset:16 nt

;     __device__ __forceinline__ void operator()(const f32x4 (&acc)[2][2][4][2], const Unit& u, int wr, int wc, int fr, int fq) const {
;     ...
;                     else if (bj == 0 && wc == 0 && fq < 2 && u.pn == 28) {
;                         float x[8] = {v0[0], v0[1], v0[2], v0[3], v1[0], v1[1], v1[2], v1[3]}; float y[8];
; #pragma unroll
;                         for (int h = 0; h < 8; ++h) {
;                             const float xb = x[h] + (fq == 0 ? dt_bias[h] : 0.f), e = __expf(-fabsf(xb));
;                             const float sp = fmaxf(xb, 0.f) + __logf(1.0f + e), sg = (xb >= 0.f ? 1.f : e) * __builtin_amdgcn_rcpf(1.0f + e);
;                             y[h] = (fq == 0) ? -__expf(a_log[h]) * sp : sg; }
;                         float* o = (fq == 0 ? G : BETA) + (size_t)r * NH; *(f32x4*)o = (f32x4){y[0], y[1], y[2], y[3]}; *(f32x4*)(o + 4) = (f32x4){y[4], y[5], y[6], y[7]};
.LBB0_226:
	s_or_b64 exec, exec, s[14:15]
	v_lshlrev_b64 v[180:181], 5, v[162:163]
	v_lshl_add_u64 v[172:173], s[26:27], 0, v[172:173]
	v_lshl_add_u64 v[172:173], v[172:173], 0, v[180:181]
	global_store_dwordx4 v[172:173], v[134:137], off sc1
	global_store_dwordx4 v[172:173], v[138:141], off offset:16 sc1

;     __device__ __forceinline__ void operator()(const f32x4 (&acc)[2][2][4][2], const Unit& u, int wr, int wc, int fr, int fq) const {
;     ...
;                     else if (reg == 6) { const int c = c8 - O_GZ; *(u32x4*)(Zb + (size_t)r * GW + c) = w; }
.LBB0_228:
	s_andn2_b64 vcc, exec, s[14:15]
	s_cbranch_vccnz .LBB0_230
	v_lshl_add_u64 v[134:135], s[56:57], 0, v[170:171]
	v_ashrrev_i32_e32 v161, 31, v160
	v_lshl_add_u64 v[134:135], v[160:161], 1, v[134:135]
	v_add_co_u32_e32 v134, vcc, 0xffffd000, v134
	s_nop 1
	v_addc_co_u32_e32 v135, vcc, -1, v135, vcc
	global_store_dwordx4 v[134:135], v[130:133], off sc1

;     __device__ __forceinline__ void operator()(const f32x4 (&acc)[2][2][4][2], const Unit& u, int wr, int wc, int fr, int fq) const {
;     ...
;                     else if (reg < 6) { const int c = c8 - O_GQKV; *(u32x4*)(CIN + (size_t)r * CONVCH + c) = w;
;                         const int t = r & (T - 1); if (t >= T - 3) { float* o = outGconv + ((size_t)(r >> 12) * 3 + (t - (T - 3))) * CONVCH + c; *(f32x4*)o = v0; *(f32x4*)(o + 4) = v1; } }
.LBB0_231:
	s_andn2_b64 vcc, exec, s[14:15]
	s_cbranch_vccnz .LBB0_235
	v_add_u32_e32 v134, 0xfffff400, v160
	v_lshl_add_u64 v[136:137], s[54:55], 0, v[166:167]
	v_ashrrev_i32_e32 v135, 31, v134
	v_lshl_add_u64 v[136:137], v[134:135], 1, v[136:137]
	global_store_dwordx4 v[136:137], v[130:133], off sc1
	s_and_saveexec_b64 s[14:15], s[16:17]
	s_cbranch_execz .LBB0_234
	v_lshl_add_u64 v[136:137], s[62:63], 0, v[168:169]
	v_lshl_add_u64 v[134:135], v[134:135], 2, v[136:137]
	global_store_dwordx4 v[134:135], v[122:125], off sc1
	global_store_dwordx4 v[134:135], v[126:129], off offset:16 sc1

;     __device__ __forceinline__ void operator()(const f32x4 (&acc)[2][2][4][2], const Unit& u, int wr, int wc, int fr, int fq) const {
;     ...
;                     else if (reg == 1) { const int c = c8 - O_SB_K; *(u32x4*)(Kb + (size_t)r * SBW + c) = w; float* o = outK + (size_t)r * SBW + c; __builtin_nontemporal_store(v0, (f32x4*)o); __builtin_nontemporal_store(v1, (f32x4*)(o + 4)); }
.LBB0_239:
	v_lshl_add_u64 v[134:135], v[164:165], 1, s[50:51]
	v_ashrrev_i32_e32 v161, 31, v160
	v_lshl_add_u64 v[134:135], v[160:161], 1, v[134:135]
	global_store_dwordx4 v[134:135], v[130:133], off offset:-2048 sc1
	v_lshl_add_u64 v[134:135], v[164:165], 2, s[58:59]
	v_lshl_add_u64 v[134:135], v[160:161], 2, v[134:135]
	global_store_dwordx4 v[134:135], v[122:125], off offset:-4096 nt
	global_store_dwordx4 v[134:135], v[126:129], off offset:-4080 nt

;     __device__ __forceinline__ void operator()(const f32x4 (&acc)[2][2][4][2], const Unit& u, int wr, int wc, int fr, int fq) const {
;     ...
;                     if (reg == 0) { *(u32x4*)(Qb + (size_t)r * SBW + c8) = w; }
;                     else if (reg == 1) { const int c = c8 - O_SB_K; *(u32x4*)(Kb + (size_t)r * SBW + c) = w; float* o = outK + (size_t)r * SBW + c; __builtin_nontemporal_store(v0, (f32x4*)o); __builtin_nontemporal_store(v1, (f32x4*)(o + 4)); }
;                     else if (reg == 2) { const int c = c8 - O_SB_V; *(u32x4*)(Vb + (size_t)r * SBW + c) = w; float* o = outV + (size_t)r * SBW + c; __builtin_nontemporal_store(v0, (f32x4*)o); __builtin_nontemporal_store(v1, (f32x4*)(o + 4)); }
.LBB0_241:
	s_and_b64 vcc, exec, s[14:15]
	v_lshl_add_u64 v[128:129], s[48:49], 0, v[170:171]
	v_ashrrev_i32_e32 v161, 31, v160
	s_cbranch_vccz .LBB0_243
	v_lshl_add_u64 v[122:123], v[160:161], 1, v[128:129]
	global_store_dwordx4 v[122:123], v[130:133], off sc1
.LBB0_243:
	v_cndmask_b32_e64 v127, 0, 1, s[18:19]
	v_add_u32_e32 v126, 0x80, v160
	v_cmp_ne_u32_e64 s[14:15], 1, v127
	s_andn2_b64 vcc, exec, s[18:19]
	s_mov_b64 s[18:19], -1
	v_cvt_pk_bf16_f32 v122, v118, v119
	v_cvt_pk_bf16_f32 v123, v120, v121
	v_cvt_pk_bf16_f32 v124, v114, v115
	v_cvt_pk_bf16_f32 v125, v116, v117
	s_cbranch_vccnz .LBB0_263
	s_mov_b64 s[86:87], -1
	s_mov_b64 s[18:19], 0
	s_cmp_lt_i32 s46, 2
	s_mov_b64 s[84:85], 0
	s_cbranch_scc1 .LBB0_258
	s_cmp_eq_u32 s46, 2
	s_mov_b64 s[84:85], -1
	s_cbranch_scc0 .LBB0_247
	v_add_u32_e32 v130, 0xfffff880, v160
	v_lshl_add_u64 v[132:133], v[164:165], 1, s[52:53]
	v_ashrrev_i32_e32 v131, 31, v130
	v_lshl_add_u64 v[132:133], v[130:131], 1, v[132:133]
	global_store_dwordx4 v[132:133], v[122:125], off sc1
	v_lshl_add_u64 v[132:133], v[164:165], 2, s[60:61]
	v_lshl_add_u64 v[130:131], v[130:131], 2, v[132:133]
	global_store_dwordx4 v[130:131], v[118:121], off nt
	global_store_dwordx4 v[130:131], v[114:117], off offset:16 nt
	s_mov_b64 s[84:85], 0

;     __device__ __forceinline__ void operator()(const f32x4 (&acc)[2][2][4][2], const Unit& u, int wr, int wc, int fr, int fq) const {
;     ...
;                     else if (reg == 6) { const int c = c8 - O_GZ; *(u32x4*)(Zb + (size_t)r * GW + c) = w; }
.LBB0_249:
	s_andn2_b64 vcc, exec, s[80:81]
	s_mov_b64 s[18:19], -1
	s_cbranch_vccnz .LBB0_253
	s_andn2_b64 vcc, exec, s[78:79]
	s_cbranch_vccnz .LBB0_252
	v_lshl_add_u64 v[130:131], s[56:57], 0, v[170:171]
	v_ashrrev_i32_e32 v127, 31, v126
	v_lshl_add_u64 v[130:131], v[126:127], 1, v[130:131]
	v_add_co_u32_e32 v130, vcc, 0xffffd000, v130
	s_nop 1
	v_addc_co_u32_e32 v131, vcc, -1, v131, vcc
	global_store_dwordx4 v[130:131], v[122:125], off sc1

;     __device__ __forceinline__ void operator()(const f32x4 (&acc)[2][2][4][2], const Unit& u, int wr, int wc, int fr, int fq) const {
;     ...
;                     else if (reg < 6) { const int c = c8 - O_GQKV; *(u32x4*)(CIN + (size_t)r * CONVCH + c) = w;
;                         const int t = r & (T - 1); if (t >= T - 3) { float* o = outGconv + ((size_t)(r >> 12) * 3 + (t - (T - 3))) * CONVCH + c; *(f32x4*)o = v0; *(f32x4*)(o + 4) = v1; } }
.LBB0_253:
	s_andn2_b64 vcc, exec, s[18:19]
	s_cbranch_vccnz .LBB0_257
	v_add_u32_e32 v130, 0xfffff480, v160
	v_lshl_add_u64 v[132:133], s[54:55], 0, v[166:167]
	v_ashrrev_i32_e32 v131, 31, v130
	v_lshl_add_u64 v[132:133], v[130:131], 1, v[132:133]
	global_store_dwordx4 v[132:133], v[122:125], off sc1
	s_and_saveexec_b64 s[18:19], s[16:17]
	s_cbranch_execz .LBB0_256
	v_lshl_add_u64 v[132:133], s[62:63], 0, v[168:169]
	v_lshl_add_u64 v[130:131], v[130:131], 2, v[132:133]
	global_store_dwordx4 v[130:131], v[118:121], off sc1
	global_store_dwordx4 v[130:131], v[114:117], off offset:16 sc1

;     __device__ __forceinline__ void operator()(const f32x4 (&acc)[2][2][4][2], const Unit& u, int wr, int wc, int fr, int fq) const {
;     ...
;                     else if (reg == 1) { const int c = c8 - O_SB_K; *(u32x4*)(Kb + (size_t)r * SBW + c) = w; float* o = outK + (size_t)r * SBW + c; __builtin_nontemporal_store(v0, (f32x4*)o); __builtin_nontemporal_store(v1, (f32x4*)(o + 4)); }
.LBB0_261:
	v_add_u32_e32 v130, 0xfffffc80, v160
	v_lshl_add_u64 v[132:133], v[164:165], 1, s[50:51]
	v_ashrrev_i32_e32 v131, 31, v130
	v_lshl_add_u64 v[132:133], v[130:131], 1, v[132:133]
	global_store_dwordx4 v[132:133], v[122:125], off sc1
	v_lshl_add_u64 v[132:133], v[164:165], 2, s[58:59]
	v_lshl_add_u64 v[130:131], v[130:131], 2, v[132:133]
	global_store_dwordx4 v[130:131], v[118:121], off nt
	global_store_dwordx4 v[130:131], v[114:117], off offset:16 nt

; __device__ __forceinline__ unsigned cvt_pk_bf16(float lo, float hi) { unsigned r; asm volatile("v_cvt_pk_bf16_f32 %0, %1, %2" : "=v"(r) : "v"(lo), "v"(hi)); return r; }
;     __device__ __forceinline__ void operator()(const f32x4 (&acc)[2][2][4][2], const Unit& u, int wr, int wc, int fr, int fq) const {
;     ...
;                 const int r = u.pm * BM + ai * HALF + wr * 64 + m * 16 + fr;
; #pragma unroll
;                 for (int bj = 0; bj < 2; ++bj) {
;                     const int c8 = u.pn * BM + bj * HALF + wc * 32 + 8 * fq;
;                     const f32x4 v0 = acc[ai][bj][m][0], v1 = acc[ai][bj][m][1];
;                     u32x4 w; w.x = cvt_pk_bf16(v0[0], v0[1]); w.y = cvt_pk_bf16(v0[2], v0[3]); w.z = cvt_pk_bf16(v1[0], v1[1]); w.w = cvt_pk_bf16(v1[2], v1[3]);
;                     if (reg == 0) { *(u32x4*)(Qb + (size_t)r * SBW + c8) = w; }
;                     else if (reg == 1) { const int c = c8 - O_SB_K; *(u32x4*)(Kb + (size_t)r * SBW + c) = w; float* o = outK + (size_t)r * SBW + c; __builtin_nontemporal_store(v0, (f32x4*)o); __builtin_nontemporal_store(v1, (f32x4*)(o + 4)); }
;                     else if (reg == 2) { const int c = c8 - O_SB_V; *(u32x4*)(Vb + (size_t)r * SBW + c) = w; float* o = outV + (size_t)r * SBW + c; __builtin_nontemporal_store(v0, (f32x4*)o); __builtin_nontemporal_store(v1, (f32x4*)(o + 4)); }
.LBB0_263:
	s_and_b64 vcc, exec, s[18:19]
	s_cbranch_vccz .LBB0_265
	v_lshl_add_u64 v[114:115], v[160:161], 1, v[128:129]
	global_store_dwordx4 v[114:115], v[122:125], off offset:256 sc1
.LBB0_265:
	v_add_u32_e32 v136, 16, v162
	v_ashrrev_i32_e32 v114, 12, v136
	v_and_b32_e32 v116, 0xfff, v136
	v_mul_i32_i24_e32 v114, 3, v114
	v_ashrrev_i32_e32 v115, 31, v114
	v_add_u32_e32 v150, 0xfffff003, v116
	v_lshl_add_u64 v[114:115], v[114:115], 0, v[150:151]
	v_ashrrev_i32_e32 v137, 31, v136
	v_mad_i64_i32 v[130:131], s[16:17], v136, s31, 0
	v_mad_u64_u32 v[132:133], s[18:19], v114, s29, 0
	v_lshlrev_b64 v[128:129], 10, v[136:137]
	v_lshlrev_b64 v[134:135], 11, v[136:137]
	v_cmp_lt_u32_e64 s[16:17], s28, v116
	v_mad_i32_i24 v133, v115, s29, v133
	s_and_b64 vcc, exec, s[14:15]
	s_mov_b64 s[18:19], -1
	v_cvt_pk_bf16_f32 v114, v110, v111
	v_cvt_pk_bf16_f32 v115, v112, v113
	v_cvt_pk_bf16_f32 v116, v106, v107
	v_cvt_pk_bf16_f32 v117, v108, v109
	s_cbranch_vccnz .LBB0_323
	s_mov_b64 s[86:87], -1
	s_mov_b64 s[18:19], 0
	s_cmp_lt_i32 s46, 2
	s_mov_b64 s[84:85], 0
	s_cbranch_scc1 .LBB0_318
	s_cmp_eq_u32 s46, 2
	s_mov_b64 s[84:85], -1
	s_cbranch_scc0 .LBB0_269
	v_lshl_add_u64 v[118:119], v[128:129], 1, s[52:53]
	v_lshl_add_u64 v[118:119], v[160:161], 1, v[118:119]
	global_store_dwordx4 v[118:119], v[114:117], off offset:-4096 sc1
	v_lshl_add_u64 v[118:119], v[128:129], 2, s[60:61]
	s_movk_i32 s84, 0xe000
	v_lshl_add_u64 v[118:119], v[160:161], 2, v[118:119]
	s_mov_b32 s85, -1
	v_lshl_add_u64 v[120:121], v[118:119], 0, s[84:85]
	v_add_co_u32_e32 v118, vcc, 0xffffe000, v118
	s_mov_b64 s[84:85], 0
	s_nop 0
	v_addc_co_u32_e32 v119, vcc, -1, v119, vcc
	global_store_dwordx4 v[118:119], v[110:113], off nt
	global_store_dwordx4 v[120:121], v[106:109], off offset:16 nt

;     __device__ __forceinline__ void operator()(const f32x4 (&acc)[2][2][4][2], const Unit& u, int wr, int wc, int fr, int fq) const {
;     ...
;                     else if (bj == 0 && wc == 0 && fq < 2 && u.pn == 28) {
;                         float x[8] = {v0[0], v0[1], v0[2], v0[3], v1[0], v1[1], v1[2], v1[3]}; float y[8];
; #pragma unroll
;                         for (int h = 0; h < 8; ++h) {
;                             const float xb = x[h] + (fq == 0 ? dt_bias[h] : 0.f), e = __expf(-fabsf(xb));
;                             const float sp = fmaxf(xb, 0.f) + __logf(1.0f + e), sg = (xb >= 0.f ? 1.f : e) * __builtin_amdgcn_rcpf(1.0f + e);
;                             y[h] = (fq == 0) ? -__expf(a_log[h]) * sp : sg; }
;                         float* o = (fq == 0 ? G : BETA) + (size_t)r * NH; *(f32x4*)o = (f32x4){y[0], y[1], y[2], y[3]}; *(f32x4*)(o + 4) = (f32x4){y[4], y[5], y[6], y[7]};
.LBB0_308:
	s_or_b64 exec, exec, s[18:19]
	v_lshlrev_b64 v[136:137], 5, v[136:137]
	v_lshl_add_u64 v[138:139], s[26:27], 0, v[138:139]
	v_lshl_add_u64 v[136:137], v[138:139], 0, v[136:137]
	global_store_dwordx4 v[136:137], v[118:121], off sc1
	global_store_dwordx4 v[136:137], v[122:125], off offset:16 sc1

;     __device__ __forceinline__ void operator()(const f32x4 (&acc)[2][2][4][2], const Unit& u, int wr, int wc, int fr, int fq) const {
;     ...
;                     else if (reg == 6) { const int c = c8 - O_GZ; *(u32x4*)(Zb + (size_t)r * GW + c) = w; }
.LBB0_310:
	s_andn2_b64 vcc, exec, s[18:19]
	s_cbranch_vccnz .LBB0_312
	v_lshl_add_u64 v[118:119], s[56:57], 0, v[134:135]
	v_lshl_add_u64 v[118:119], v[160:161], 1, v[118:119]
	v_add_co_u32_e32 v118, vcc, 0xffffd000, v118
	s_nop 1
	v_addc_co_u32_e32 v119, vcc, -1, v119, vcc
	global_store_dwordx4 v[118:119], v[114:117], off sc1

;     __device__ __forceinline__ void operator()(const f32x4 (&acc)[2][2][4][2], const Unit& u, int wr, int wc, int fr, int fq) const {
;     ...
;                     else if (reg < 6) { const int c = c8 - O_GQKV; *(u32x4*)(CIN + (size_t)r * CONVCH + c) = w;
;                         const int t = r & (T - 1); if (t >= T - 3) { float* o = outGconv + ((size_t)(r >> 12) * 3 + (t - (T - 3))) * CONVCH + c; *(f32x4*)o = v0; *(f32x4*)(o + 4) = v1; } }
.LBB0_313:
	s_andn2_b64 vcc, exec, s[18:19]
	s_cbranch_vccnz .LBB0_317
	v_add_u32_e32 v118, 0xfffff400, v160
	v_lshl_add_u64 v[120:121], s[54:55], 0, v[130:131]
	v_ashrrev_i32_e32 v119, 31, v118
	v_lshl_add_u64 v[120:121], v[118:119], 1, v[120:121]
	global_store_dwordx4 v[120:121], v[114:117], off sc1
	s_and_saveexec_b64 s[18:19], s[16:17]
	s_cbranch_execz .LBB0_316
	v_lshl_add_u64 v[120:121], s[62:63], 0, v[132:133]
	v_lshl_add_u64 v[118:119], v[118:119], 2, v[120:121]
	global_store_dwordx4 v[118:119], v[110:113], off sc1
	global_store_dwordx4 v[118:119], v[106:109], off offset:16 sc1

;     __device__ __forceinline__ void operator()(const f32x4 (&acc)[2][2][4][2], const Unit& u, int wr, int wc, int fr, int fq) const {
;     ...
;                     else if (reg == 1) { const int c = c8 - O_SB_K; *(u32x4*)(Kb + (size_t)r * SBW + c) = w; float* o = outK + (size_t)r * SBW + c; __builtin_nontemporal_store(v0, (f32x4*)o); __builtin_nontemporal_store(v1, (f32x4*)(o + 4)); }
.LBB0_321:
	v_lshl_add_u64 v[118:119], v[128:129], 1, s[50:51]
	v_lshl_add_u64 v[118:119], v[160:161], 1, v[118:119]
	global_store_dwordx4 v[118:119], v[114:117], off offset:-2048 sc1
	v_lshl_add_u64 v[118:119], v[128:129], 2, s[58:59]
	v_lshl_add_u64 v[118:119], v[160:161], 2, v[118:119]
	global_store_dwordx4 v[118:119], v[110:113], off offset:-4096 nt
	global_store_dwordx4 v[118:119], v[106:109], off offset:-4080 nt

;     __device__ __forceinline__ void operator()(const f32x4 (&acc)[2][2][4][2], const Unit& u, int wr, int wc, int fr, int fq) const {
;     ...
;                     if (reg == 0) { *(u32x4*)(Qb + (size_t)r * SBW + c8) = w; }
;                     else if (reg == 1) { const int c = c8 - O_SB_K; *(u32x4*)(Kb + (size_t)r * SBW + c) = w; float* o = outK + (size_t)r * SBW + c; __builtin_nontemporal_store(v0, (f32x4*)o); __builtin_nontemporal_store(v1, (f32x4*)(o + 4)); }
;                     else if (reg == 2) { const int c = c8 - O_SB_V; *(u32x4*)(Vb + (size_t)r * SBW + c) = w; float* o = outV + (size_t)r * SBW + c; __builtin_nontemporal_store(v0, (f32x4*)o); __builtin_nontemporal_store(v1, (f32x4*)(o + 4)); }
.LBB0_323:
	s_and_b64 vcc, exec, s[18:19]
	v_lshl_add_u64 v[110:111], s[48:49], 0, v[134:135]
	s_cbranch_vccz .LBB0_325
	v_lshl_add_u64 v[106:107], v[160:161], 1, v[110:111]
	global_store_dwordx4 v[106:107], v[114:117], off sc1
.LBB0_325:
	s_and_b64 vcc, exec, s[14:15]
	s_mov_b64 s[18:19], -1
	v_cvt_pk_bf16_f32 v106, v102, v103
	v_cvt_pk_bf16_f32 v107, v104, v105
	v_cvt_pk_bf16_f32 v108, v98, v99
	v_cvt_pk_bf16_f32 v109, v100, v101
	s_cbranch_vccnz .LBB0_345
	s_mov_b64 s[86:87], -1
	s_mov_b64 s[18:19], 0
	s_cmp_lt_i32 s46, 2
	s_mov_b64 s[84:85], 0
	s_cbranch_scc1 .LBB0_340
	s_cmp_eq_u32 s46, 2
	s_mov_b64 s[84:85], -1
	s_cbranch_scc0 .LBB0_329
	v_add_u32_e32 v112, 0xfffff880, v160
	v_lshl_add_u64 v[114:115], v[128:129], 1, s[52:53]
	v_ashrrev_i32_e32 v113, 31, v112
	v_lshl_add_u64 v[114:115], v[112:113], 1, v[114:115]
	global_store_dwordx4 v[114:115], v[106:109], off sc1
	v_lshl_add_u64 v[114:115], v[128:129], 2, s[60:61]
	v_lshl_add_u64 v[112:113], v[112:113], 2, v[114:115]
	global_store_dwordx4 v[112:113], v[102:105], off nt
	global_store_dwordx4 v[112:113], v[98:101], off offset:16 nt
	s_mov_b64 s[84:85], 0

;     __device__ __forceinline__ void operator()(const f32x4 (&acc)[2][2][4][2], const Unit& u, int wr, int wc, int fr, int fq) const {
;     ...
;                     else if (reg == 6) { const int c = c8 - O_GZ; *(u32x4*)(Zb + (size_t)r * GW + c) = w; }
.LBB0_331:
	s_andn2_b64 vcc, exec, s[80:81]
	s_mov_b64 s[18:19], -1
	s_cbranch_vccnz .LBB0_335
	s_andn2_b64 vcc, exec, s[78:79]
	s_cbranch_vccnz .LBB0_334
	v_lshl_add_u64 v[112:113], s[56:57], 0, v[134:135]
	v_ashrrev_i32_e32 v127, 31, v126
	v_lshl_add_u64 v[112:113], v[126:127], 1, v[112:113]
	v_add_co_u32_e32 v112, vcc, 0xffffd000, v112
	s_nop 1
	v_addc_co_u32_e32 v113, vcc, -1, v113, vcc
	global_store_dwordx4 v[112:113], v[106:109], off sc1

;     __device__ __forceinline__ void operator()(const f32x4 (&acc)[2][2][4][2], const Unit& u, int wr, int wc, int fr, int fq) const {
;     ...
;                     else if (reg < 6) { const int c = c8 - O_GQKV; *(u32x4*)(CIN + (size_t)r * CONVCH + c) = w;
;                         const int t = r & (T - 1); if (t >= T - 3) { float* o = outGconv + ((size_t)(r >> 12) * 3 + (t - (T - 3))) * CONVCH + c; *(f32x4*)o = v0; *(f32x4*)(o + 4) = v1; } }
.LBB0_335:
	s_andn2_b64 vcc, exec, s[18:19]
	s_cbranch_vccnz .LBB0_339
	v_add_u32_e32 v112, 0xfffff480, v160
	v_lshl_add_u64 v[114:115], s[54:55], 0, v[130:131]
	v_ashrrev_i32_e32 v113, 31, v112
	v_lshl_add_u64 v[114:115], v[112:113], 1, v[114:115]
	global_store_dwordx4 v[114:115], v[106:109], off sc1
	s_and_saveexec_b64 s[18:19], s[16:17]
	s_cbranch_execz .LBB0_338
	v_lshl_add_u64 v[114:115], s[62:63], 0, v[132:133]
	v_lshl_add_u64 v[112:113], v[112:113], 2, v[114:115]
	global_store_dwordx4 v[112:113], v[102:105], off sc1
	global_store_dwordx4 v[112:113], v[98:101], off offset:16 sc1

;     __device__ __forceinline__ void operator()(const f32x4 (&acc)[2][2][4][2], const Unit& u, int wr, int wc, int fr, int fq) const {
;     ...
;                     else if (reg == 1) { const int c = c8 - O_SB_K; *(u32x4*)(Kb + (size_t)r * SBW + c) = w; float* o = outK + (size_t)r * SBW + c; __builtin_nontemporal_store(v0, (f32x4*)o); __builtin_nontemporal_store(v1, (f32x4*)(o + 4)); }
.LBB0_343:
	v_add_u32_e32 v112, 0xfffffc80, v160
	v_lshl_add_u64 v[114:115], v[128:129], 1, s[50:51]
	v_ashrrev_i32_e32 v113, 31, v112
	v_lshl_add_u64 v[114:115], v[112:113], 1, v[114:115]
	global_store_dwordx4 v[114:115], v[106:109], off sc1
	v_lshl_add_u64 v[114:115], v[128:129], 2, s[58:59]
	v_lshl_add_u64 v[112:113], v[112:113], 2, v[114:115]
	global_store_dwordx4 v[112:113], v[102:105], off nt
	global_store_dwordx4 v[112:113], v[98:101], off offset:16 nt

; __device__ __forceinline__ unsigned cvt_pk_bf16(float lo, float hi) { unsigned r; asm volatile("v_cvt_pk_bf16_f32 %0, %1, %2" : "=v"(r) : "v"(lo), "v"(hi)); return r; }
;     __device__ __forceinline__ void operator()(const f32x4 (&acc)[2][2][4][2], const Unit& u, int wr, int wc, int fr, int fq) const {
;     ...
;                 const int r = u.pm * BM + ai * HALF + wr * 64 + m * 16 + fr;
; #pragma unroll
;                 for (int bj = 0; bj < 2; ++bj) {
;                     const int c8 = u.pn * BM + bj * HALF + wc * 32 + 8 * fq;
;                     const f32x4 v0 = acc[ai][bj][m][0], v1 = acc[ai][bj][m][1];
;                     u32x4 w; w.x = cvt_pk_bf16(v0[0], v0[1]); w.y = cvt_pk_bf16(v0[2], v0[3]); w.z = cvt_pk_bf16(v1[0], v1[1]); w.w = cvt_pk_bf16(v1[2], v1[3]);
;                     if (reg == 0) { *(u32x4*)(Qb + (size_t)r * SBW + c8) = w; }
;                     else if (reg == 1) { const int c = c8 - O_SB_K; *(u32x4*)(Kb + (size_t)r * SBW + c) = w; float* o = outK + (size_t)r * SBW + c; __builtin_nontemporal_store(v0, (f32x4*)o); __builtin_nontemporal_store(v1, (f32x4*)(o + 4)); }
;                     else if (reg == 2) { const int c = c8 - O_SB_V; *(u32x4*)(Vb + (size_t)r * SBW + c) = w; float* o = outV + (size_t)r * SBW + c; __builtin_nontemporal_store(v0, (f32x4*)o); __builtin_nontemporal_store(v1, (f32x4*)(o + 4)); }
.LBB0_345:
	s_and_b64 vcc, exec, s[18:19]
	s_cbranch_vccz .LBB0_347
	v_lshl_add_u64 v[98:99], v[160:161], 1, v[110:111]
	global_store_dwordx4 v[98:99], v[106:109], off offset:256 sc1
.LBB0_347:
	v_add_u32_e32 v118, 32, v162
	v_ashrrev_i32_e32 v98, 12, v118
	v_and_b32_e32 v100, 0xfff, v118
	v_mul_i32_i24_e32 v98, 3, v98
	v_ashrrev_i32_e32 v99, 31, v98
	v_add_u32_e32 v150, 0xfffff003, v100
	v_lshl_add_u64 v[98:99], v[98:99], 0, v[150:151]
	v_ashrrev_i32_e32 v119, 31, v118
	v_mad_i64_i32 v[112:113], s[16:17], v118, s31, 0
	v_mad_u64_u32 v[114:115], s[18:19], v98, s29, 0
	v_lshlrev_b64 v[110:111], 10, v[118:119]
	v_lshlrev_b64 v[116:117], 11, v[118:119]
	v_cmp_lt_u32_e64 s[16:17], s28, v100
	v_mad_i32_i24 v115, v99, s29, v115
	s_and_b64 vcc, exec, s[14:15]
	s_mov_b64 s[18:19], -1
	v_cvt_pk_bf16_f32 v98, v94, v95
	v_cvt_pk_bf16_f32 v99, v96, v97
	v_cvt_pk_bf16_f32 v100, v90, v91
	v_cvt_pk_bf16_f32 v101, v92, v93
	s_cbranch_vccnz .LBB0_405
	s_mov_b64 s[86:87], -1
	s_mov_b64 s[18:19], 0
	s_cmp_lt_i32 s46, 2
	s_mov_b64 s[84:85], 0
	s_cbranch_scc1 .LBB0_400
	s_cmp_eq_u32 s46, 2
	s_mov_b64 s[84:85], -1
	s_cbranch_scc0 .LBB0_351
	v_lshl_add_u64 v[102:103], v[110:111], 1, s[52:53]
	v_lshl_add_u64 v[102:103], v[160:161], 1, v[102:103]
	global_store_dwordx4 v[102:103], v[98:101], off offset:-4096 sc1
	v_lshl_add_u64 v[102:103], v[110:111], 2, s[60:61]
	s_movk_i32 s84, 0xe000
	v_lshl_add_u64 v[102:103], v[160:161], 2, v[102:103]
	s_mov_b32 s85, -1
	v_lshl_add_u64 v[104:105], v[102:103], 0, s[84:85]
	v_add_co_u32_e32 v102, vcc, 0xffffe000, v102
	s_mov_b64 s[84:85], 0
	s_nop 0
	v_addc_co_u32_e32 v103, vcc, -1, v103, vcc
	global_store_dwordx4 v[102:103], v[94:97], off nt
	global_store_dwordx4 v[104:105], v[90:93], off offset:16 nt

;     __device__ __forceinline__ void operator()(const f32x4 (&acc)[2][2][4][2], const Unit& u, int wr, int wc, int fr, int fq) const {
;     ...
;                     else if (bj == 0 && wc == 0 && fq < 2 && u.pn == 28) {
;                         float x[8] = {v0[0], v0[1], v0[2], v0[3], v1[0], v1[1], v1[2], v1[3]}; float y[8];
; #pragma unroll
;                         for (int h = 0; h < 8; ++h) {
;                             const float xb = x[h] + (fq == 0 ? dt_bias[h] : 0.f), e = __expf(-fabsf(xb));
;                             const float sp = fmaxf(xb, 0.f) + __logf(1.0f + e), sg = (xb >= 0.f ? 1.f : e) * __builtin_amdgcn_rcpf(1.0f + e);
;                             y[h] = (fq == 0) ? -__expf(a_log[h]) * sp : sg; }
;                         float* o = (fq == 0 ? G : BETA) + (size_t)r * NH; *(f32x4*)o = (f32x4){y[0], y[1], y[2], y[3]}; *(f32x4*)(o + 4) = (f32x4){y[4], y[5], y[6], y[7]};
.LBB0_390:
	s_or_b64 exec, exec, s[18:19]
	v_lshlrev_b64 v[118:119], 5, v[118:119]
	v_lshl_add_u64 v[120:121], s[26:27], 0, v[120:121]
	v_lshl_add_u64 v[118:119], v[120:121], 0, v[118:119]
	global_store_dwordx4 v[118:119], v[102:105], off sc1
	global_store_dwordx4 v[118:119], v[106:109], off offset:16 sc1

;     __device__ __forceinline__ void operator()(const f32x4 (&acc)[2][2][4][2], const Unit& u, int wr, int wc, int fr, int fq) const {
;     ...
;                     else if (reg == 6) { const int c = c8 - O_GZ; *(u32x4*)(Zb + (size_t)r * GW + c) = w; }
.LBB0_392:
	s_andn2_b64 vcc, exec, s[18:19]
	s_cbranch_vccnz .LBB0_394
	v_lshl_add_u64 v[102:103], s[56:57], 0, v[116:117]
	v_lshl_add_u64 v[102:103], v[160:161], 1, v[102:103]
	v_add_co_u32_e32 v102, vcc, 0xffffd000, v102
	s_nop 1
	v_addc_co_u32_e32 v103, vcc, -1, v103, vcc
	global_store_dwordx4 v[102:103], v[98:101], off sc1

;     __device__ __forceinline__ void operator()(const f32x4 (&acc)[2][2][4][2], const Unit& u, int wr, int wc, int fr, int fq) const {
;     ...
;                     else if (reg < 6) { const int c = c8 - O_GQKV; *(u32x4*)(CIN + (size_t)r * CONVCH + c) = w;
;                         const int t = r & (T - 1); if (t >= T - 3) { float* o = outGconv + ((size_t)(r >> 12) * 3 + (t - (T - 3))) * CONVCH + c; *(f32x4*)o = v0; *(f32x4*)(o + 4) = v1; } }
.LBB0_395:
	s_andn2_b64 vcc, exec, s[18:19]
	s_cbranch_vccnz .LBB0_399
	v_add_u32_e32 v102, 0xfffff400, v160
	v_lshl_add_u64 v[104:105], s[54:55], 0, v[112:113]
	v_ashrrev_i32_e32 v103, 31, v102
	v_lshl_add_u64 v[104:105], v[102:103], 1, v[104:105]
	global_store_dwordx4 v[104:105], v[98:101], off sc1
	s_and_saveexec_b64 s[18:19], s[16:17]
	s_cbranch_execz .LBB0_398
	v_lshl_add_u64 v[104:105], s[62:63], 0, v[114:115]
	v_lshl_add_u64 v[102:103], v[102:103], 2, v[104:105]
	global_store_dwordx4 v[102:103], v[94:97], off sc1
	global_store_dwordx4 v[102:103], v[90:93], off offset:16 sc1

;     __device__ __forceinline__ void operator()(const f32x4 (&acc)[2][2][4][2], const Unit& u, int wr, int wc, int fr, int fq) const {
;     ...
;                     else if (reg == 1) { const int c = c8 - O_SB_K; *(u32x4*)(Kb + (size_t)r * SBW + c) = w; float* o = outK + (size_t)r * SBW + c; __builtin_nontemporal_store(v0, (f32x4*)o); __builtin_nontemporal_store(v1, (f32x4*)(o + 4)); }
.LBB0_403:
	v_lshl_add_u64 v[102:103], v[110:111], 1, s[50:51]
	v_lshl_add_u64 v[102:103], v[160:161], 1, v[102:103]
	global_store_dwordx4 v[102:103], v[98:101], off offset:-2048 sc1
	v_lshl_add_u64 v[102:103], v[110:111], 2, s[58:59]
	v_lshl_add_u64 v[102:103], v[160:161], 2, v[102:103]
	global_store_dwordx4 v[102:103], v[94:97], off offset:-4096 nt
	global_store_dwordx4 v[102:103], v[90:93], off offset:-4080 nt

;     __device__ __forceinline__ void operator()(const f32x4 (&acc)[2][2][4][2], const Unit& u, int wr, int wc, int fr, int fq) const {
;     ...
;                     if (reg == 0) { *(u32x4*)(Qb + (size_t)r * SBW + c8) = w; }
;                     else if (reg == 1) { const int c = c8 - O_SB_K; *(u32x4*)(Kb + (size_t)r * SBW + c) = w; float* o = outK + (size_t)r * SBW + c; __builtin_nontemporal_store(v0, (f32x4*)o); __builtin_nontemporal_store(v1, (f32x4*)(o + 4)); }
;                     else if (reg == 2) { const int c = c8 - O_SB_V; *(u32x4*)(Vb + (size_t)r * SBW + c) = w; float* o = outV + (size_t)r * SBW + c; __builtin_nontemporal_store(v0, (f32x4*)o); __builtin_nontemporal_store(v1, (f32x4*)(o + 4)); }
.LBB0_405:
	s_and_b64 vcc, exec, s[18:19]
	v_lshl_add_u64 v[94:95], s[48:49], 0, v[116:117]
	s_cbranch_vccz .LBB0_407
	v_lshl_add_u64 v[90:91], v[160:161], 1, v[94:95]
	global_store_dwordx4 v[90:91], v[98:101], off sc1
.LBB0_407:
	s_and_b64 vcc, exec, s[14:15]
	s_mov_b64 s[18:19], -1
	v_cvt_pk_bf16_f32 v90, v86, v87
	v_cvt_pk_bf16_f32 v91, v88, v89
	v_cvt_pk_bf16_f32 v92, v82, v83
	v_cvt_pk_bf16_f32 v93, v84, v85
	s_cbranch_vccnz .LBB0_427
	s_mov_b64 s[86:87], -1
	s_mov_b64 s[18:19], 0
	s_cmp_lt_i32 s46, 2
	s_mov_b64 s[84:85], 0
	s_cbranch_scc1 .LBB0_422
	s_cmp_eq_u32 s46, 2
	s_mov_b64 s[84:85], -1
	s_cbranch_scc0 .LBB0_411
	v_add_u32_e32 v96, 0xfffff880, v160
	v_lshl_add_u64 v[98:99], v[110:111], 1, s[52:53]
	v_ashrrev_i32_e32 v97, 31, v96
	v_lshl_add_u64 v[98:99], v[96:97], 1, v[98:99]
	global_store_dwordx4 v[98:99], v[90:93], off sc1
	v_lshl_add_u64 v[98:99], v[110:111], 2, s[60:61]
	v_lshl_add_u64 v[96:97], v[96:97], 2, v[98:99]
	global_store_dwordx4 v[96:97], v[86:89], off nt
	global_store_dwordx4 v[96:97], v[82:85], off offset:16 nt
	s_mov_b64 s[84:85], 0

;     __device__ __forceinline__ void operator()(const f32x4 (&acc)[2][2][4][2], const Unit& u, int wr, int wc, int fr, int fq) const {
;     ...
;                     else if (reg == 6) { const int c = c8 - O_GZ; *(u32x4*)(Zb + (size_t)r * GW + c) = w; }
.LBB0_413:
	s_andn2_b64 vcc, exec, s[80:81]
	s_mov_b64 s[18:19], -1
	s_cbranch_vccnz .LBB0_417
	s_andn2_b64 vcc, exec, s[78:79]
	s_cbranch_vccnz .LBB0_416
	v_lshl_add_u64 v[96:97], s[56:57], 0, v[116:117]
	v_ashrrev_i32_e32 v127, 31, v126
	v_lshl_add_u64 v[96:97], v[126:127], 1, v[96:97]
	v_add_co_u32_e32 v96, vcc, 0xffffd000, v96
	s_nop 1
	v_addc_co_u32_e32 v97, vcc, -1, v97, vcc
	global_store_dwordx4 v[96:97], v[90:93], off sc1

;     __device__ __forceinline__ void operator()(const f32x4 (&acc)[2][2][4][2], const Unit& u, int wr, int wc, int fr, int fq) const {
;     ...
;                     else if (reg < 6) { const int c = c8 - O_GQKV; *(u32x4*)(CIN + (size_t)r * CONVCH + c) = w;
;                         const int t = r & (T - 1); if (t >= T - 3) { float* o = outGconv + ((size_t)(r >> 12) * 3 + (t - (T - 3))) * CONVCH + c; *(f32x4*)o = v0; *(f32x4*)(o + 4) = v1; } }
.LBB0_417:
	s_andn2_b64 vcc, exec, s[18:19]
	s_cbranch_vccnz .LBB0_421
	v_add_u32_e32 v96, 0xfffff480, v160
	v_lshl_add_u64 v[98:99], s[54:55], 0, v[112:113]
	v_ashrrev_i32_e32 v97, 31, v96
	v_lshl_add_u64 v[98:99], v[96:97], 1, v[98:99]
	global_store_dwordx4 v[98:99], v[90:93], off sc1
	s_and_saveexec_b64 s[18:19], s[16:17]
	s_cbranch_execz .LBB0_420
	v_lshl_add_u64 v[98:99], s[62:63], 0, v[114:115]
	v_lshl_add_u64 v[96:97], v[96:97], 2, v[98:99]
	global_store_dwordx4 v[96:97], v[86:89], off sc1
	global_store_dwordx4 v[96:97], v[82:85], off offset:16 sc1

;     __device__ __forceinline__ void operator()(const f32x4 (&acc)[2][2][4][2], const Unit& u, int wr, int wc, int fr, int fq) const {
;     ...
;                     else if (reg == 1) { const int c = c8 - O_SB_K; *(u32x4*)(Kb + (size_t)r * SBW + c) = w; float* o = outK + (size_t)r * SBW + c; __builtin_nontemporal_store(v0, (f32x4*)o); __builtin_nontemporal_store(v1, (f32x4*)(o + 4)); }
.LBB0_425:
	v_add_u32_e32 v96, 0xfffffc80, v160
	v_lshl_add_u64 v[98:99], v[110:111], 1, s[50:51]
	v_ashrrev_i32_e32 v97, 31, v96
	v_lshl_add_u64 v[98:99], v[96:97], 1, v[98:99]
	global_store_dwordx4 v[98:99], v[90:93], off sc1
	v_lshl_add_u64 v[98:99], v[110:111], 2, s[58:59]
	v_lshl_add_u64 v[96:97], v[96:97], 2, v[98:99]
	global_store_dwordx4 v[96:97], v[86:89], off nt
	global_store_dwordx4 v[96:97], v[82:85], off offset:16 nt

; __device__ __forceinline__ unsigned cvt_pk_bf16(float lo, float hi) { unsigned r; asm volatile("v_cvt_pk_bf16_f32 %0, %1, %2" : "=v"(r) : "v"(lo), "v"(hi)); return r; }
;     __device__ __forceinline__ void operator()(const f32x4 (&acc)[2][2][4][2], const Unit& u, int wr, int wc, int fr, int fq) const {
;     ...
;                 const int r = u.pm * BM + ai * HALF + wr * 64 + m * 16 + fr;
; #pragma unroll
;                 for (int bj = 0; bj < 2; ++bj) {
;                     const int c8 = u.pn * BM + bj * HALF + wc * 32 + 8 * fq;
;                     const f32x4 v0 = acc[ai][bj][m][0], v1 = acc[ai][bj][m][1];
;                     u32x4 w; w.x = cvt_pk_bf16(v0[0], v0[1]); w.y = cvt_pk_bf16(v0[2], v0[3]); w.z = cvt_pk_bf16(v1[0], v1[1]); w.w = cvt_pk_bf16(v1[2], v1[3]);
;                     if (reg == 0) { *(u32x4*)(Qb + (size_t)r * SBW + c8) = w; }
;                     else if (reg == 1) { const int c = c8 - O_SB_K; *(u32x4*)(Kb + (size_t)r * SBW + c) = w; float* o = outK + (size_t)r * SBW + c; __builtin_nontemporal_store(v0, (f32x4*)o); __builtin_nontemporal_store(v1, (f32x4*)(o + 4)); }
;                     else if (reg == 2) { const int c = c8 - O_SB_V; *(u32x4*)(Vb + (size_t)r * SBW + c) = w; float* o = outV + (size_t)r * SBW + c; __builtin_nontemporal_store(v0, (f32x4*)o); __builtin_nontemporal_store(v1, (f32x4*)(o + 4)); }
.LBB0_427:
	s_and_b64 vcc, exec, s[18:19]
	s_cbranch_vccz .LBB0_429
	v_lshl_add_u64 v[82:83], v[160:161], 1, v[94:95]
	global_store_dwordx4 v[82:83], v[90:93], off offset:256 sc1
.LBB0_429:
	v_add_u32_e32 v102, 48, v162
	v_ashrrev_i32_e32 v82, 12, v102
	v_and_b32_e32 v84, 0xfff, v102
	v_mul_i32_i24_e32 v82, 3, v82
	v_ashrrev_i32_e32 v83, 31, v82
	v_add_u32_e32 v150, 0xfffff003, v84
	v_lshl_add_u64 v[82:83], v[82:83], 0, v[150:151]
	v_ashrrev_i32_e32 v103, 31, v102
	v_mad_i64_i32 v[96:97], s[16:17], v102, s31, 0
	v_mad_u64_u32 v[98:99], s[18:19], v82, s29, 0
	v_lshlrev_b64 v[94:95], 10, v[102:103]
	v_lshlrev_b64 v[100:101], 11, v[102:103]
	v_cmp_lt_u32_e64 s[16:17], s28, v84
	v_mad_i32_i24 v99, v83, s29, v99
	s_and_b64 vcc, exec, s[14:15]
	s_mov_b64 s[18:19], -1
	v_cvt_pk_bf16_f32 v82, v78, v79
	v_cvt_pk_bf16_f32 v83, v80, v81
	v_cvt_pk_bf16_f32 v84, v74, v75
	v_cvt_pk_bf16_f32 v85, v76, v77
	s_cbranch_vccnz .LBB0_487
	s_mov_b64 s[86:87], -1
	s_mov_b64 s[18:19], 0
	s_cmp_lt_i32 s46, 2
	s_mov_b64 s[84:85], 0
	s_cbranch_scc1 .LBB0_482
	s_cmp_eq_u32 s46, 2
	s_mov_b64 s[84:85], -1
	s_cbranch_scc0 .LBB0_433
	v_lshl_add_u64 v[86:87], v[94:95], 1, s[52:53]
	v_lshl_add_u64 v[86:87], v[160:161], 1, v[86:87]
	global_store_dwordx4 v[86:87], v[82:85], off offset:-4096 sc1
	v_lshl_add_u64 v[86:87], v[94:95], 2, s[60:61]
	s_movk_i32 s84, 0xe000
	v_lshl_add_u64 v[86:87], v[160:161], 2, v[86:87]
	s_mov_b32 s85, -1
	v_lshl_add_u64 v[88:89], v[86:87], 0, s[84:85]
	v_add_co_u32_e32 v86, vcc, 0xffffe000, v86
	s_mov_b64 s[84:85], 0
	s_nop 0
	v_addc_co_u32_e32 v87, vcc, -1, v87, vcc
	global_store_dwordx4 v[86:87], v[78:81], off nt
	global_store_dwordx4 v[88:89], v[74:77], off offset:16 nt

;     __device__ __forceinline__ void operator()(const f32x4 (&acc)[2][2][4][2], const Unit& u, int wr, int wc, int fr, int fq) const {
;     ...
;                     else if (bj == 0 && wc == 0 && fq < 2 && u.pn == 28) {
;                         float x[8] = {v0[0], v0[1], v0[2], v0[3], v1[0], v1[1], v1[2], v1[3]}; float y[8];
; #pragma unroll
;                         for (int h = 0; h < 8; ++h) {
;                             const float xb = x[h] + (fq == 0 ? dt_bias[h] : 0.f), e = __expf(-fabsf(xb));
;                             const float sp = fmaxf(xb, 0.f) + __logf(1.0f + e), sg = (xb >= 0.f ? 1.f : e) * __builtin_amdgcn_rcpf(1.0f + e);
;                             y[h] = (fq == 0) ? -__expf(a_log[h]) * sp : sg; }
;                         float* o = (fq == 0 ? G : BETA) + (size_t)r * NH; *(f32x4*)o = (f32x4){y[0], y[1], y[2], y[3]}; *(f32x4*)(o + 4) = (f32x4){y[4], y[5], y[6], y[7]};
.LBB0_472:
	s_or_b64 exec, exec, s[18:19]
	v_lshlrev_b64 v[102:103], 5, v[102:103]
	v_lshl_add_u64 v[104:105], s[26:27], 0, v[104:105]
	v_lshl_add_u64 v[102:103], v[104:105], 0, v[102:103]
	global_store_dwordx4 v[102:103], v[86:89], off sc1
	global_store_dwordx4 v[102:103], v[90:93], off offset:16 sc1

;     __device__ __forceinline__ void operator()(const f32x4 (&acc)[2][2][4][2], const Unit& u, int wr, int wc, int fr, int fq) const {
;     ...
;                     else if (reg == 6) { const int c = c8 - O_GZ; *(u32x4*)(Zb + (size_t)r * GW + c) = w; }
.LBB0_474:
	s_andn2_b64 vcc, exec, s[18:19]
	s_cbranch_vccnz .LBB0_476
	v_lshl_add_u64 v[86:87], s[56:57], 0, v[100:101]
	v_lshl_add_u64 v[86:87], v[160:161], 1, v[86:87]
	v_add_co_u32_e32 v86, vcc, 0xffffd000, v86
	s_nop 1
	v_addc_co_u32_e32 v87, vcc, -1, v87, vcc
	global_store_dwordx4 v[86:87], v[82:85], off sc1

;     __device__ __forceinline__ void operator()(const f32x4 (&acc)[2][2][4][2], const Unit& u, int wr, int wc, int fr, int fq) const {
;     ...
;                     else if (reg < 6) { const int c = c8 - O_GQKV; *(u32x4*)(CIN + (size_t)r * CONVCH + c) = w;
;                         const int t = r & (T - 1); if (t >= T - 3) { float* o = outGconv + ((size_t)(r >> 12) * 3 + (t - (T - 3))) * CONVCH + c; *(f32x4*)o = v0; *(f32x4*)(o + 4) = v1; } }
.LBB0_477:
	s_andn2_b64 vcc, exec, s[18:19]
	s_cbranch_vccnz .LBB0_481
	v_add_u32_e32 v86, 0xfffff400, v160
	v_lshl_add_u64 v[88:89], s[54:55], 0, v[96:97]
	v_ashrrev_i32_e32 v87, 31, v86
	v_lshl_add_u64 v[88:89], v[86:87], 1, v[88:89]
	global_store_dwordx4 v[88:89], v[82:85], off sc1
	s_and_saveexec_b64 s[18:19], s[16:17]
	s_cbranch_execz .LBB0_480
	v_lshl_add_u64 v[88:89], s[62:63], 0, v[98:99]
	v_lshl_add_u64 v[86:87], v[86:87], 2, v[88:89]
	global_store_dwordx4 v[86:87], v[78:81], off sc1
	global_store_dwordx4 v[86:87], v[74:77], off offset:16 sc1

;     __device__ __forceinline__ void operator()(const f32x4 (&acc)[2][2][4][2], const Unit& u, int wr, int wc, int fr, int fq) const {
;     ...
;                     else if (reg == 1) { const int c = c8 - O_SB_K; *(u32x4*)(Kb + (size_t)r * SBW + c) = w; float* o = outK + (size_t)r * SBW + c; __builtin_nontemporal_store(v0, (f32x4*)o); __builtin_nontemporal_store(v1, (f32x4*)(o + 4)); }
.LBB0_485:
	v_lshl_add_u64 v[86:87], v[94:95], 1, s[50:51]
	v_lshl_add_u64 v[86:87], v[160:161], 1, v[86:87]
	global_store_dwordx4 v[86:87], v[82:85], off offset:-2048 sc1
	v_lshl_add_u64 v[86:87], v[94:95], 2, s[58:59]
	v_lshl_add_u64 v[86:87], v[160:161], 2, v[86:87]
	global_store_dwordx4 v[86:87], v[78:81], off offset:-4096 nt
	global_store_dwordx4 v[86:87], v[74:77], off offset:-4080 nt

;     __device__ __forceinline__ void operator()(const f32x4 (&acc)[2][2][4][2], const Unit& u, int wr, int wc, int fr, int fq) const {
;     ...
;                     if (reg == 0) { *(u32x4*)(Qb + (size_t)r * SBW + c8) = w; }
;                     else if (reg == 1) { const int c = c8 - O_SB_K; *(u32x4*)(Kb + (size_t)r * SBW + c) = w; float* o = outK + (size_t)r * SBW + c; __builtin_nontemporal_store(v0, (f32x4*)o); __builtin_nontemporal_store(v1, (f32x4*)(o + 4)); }
;                     else if (reg == 2) { const int c = c8 - O_SB_V; *(u32x4*)(Vb + (size_t)r * SBW + c) = w; float* o = outV + (size_t)r * SBW + c; __builtin_nontemporal_store(v0, (f32x4*)o); __builtin_nontemporal_store(v1, (f32x4*)(o + 4)); }
.LBB0_487:
	s_and_b64 vcc, exec, s[18:19]
	v_lshl_add_u64 v[78:79], s[48:49], 0, v[100:101]
	s_cbranch_vccz .LBB0_489
	v_lshl_add_u64 v[74:75], v[160:161], 1, v[78:79]
	global_store_dwordx4 v[74:75], v[82:85], off sc1
.LBB0_489:
	s_and_b64 vcc, exec, s[14:15]
	s_mov_b64 s[18:19], -1
	v_cvt_pk_bf16_f32 v74, v70, v71
	v_cvt_pk_bf16_f32 v75, v72, v73
	v_cvt_pk_bf16_f32 v76, v66, v67
	v_cvt_pk_bf16_f32 v77, v68, v69
	s_cbranch_vccnz .LBB0_509
	s_mov_b64 s[86:87], -1
	s_mov_b64 s[18:19], 0
	s_cmp_lt_i32 s46, 2
	s_mov_b64 s[84:85], 0
	s_cbranch_scc1 .LBB0_504
	s_cmp_eq_u32 s46, 2
	s_mov_b64 s[84:85], -1
	s_cbranch_scc0 .LBB0_493
	v_add_u32_e32 v80, 0xfffff880, v160
	v_lshl_add_u64 v[82:83], v[94:95], 1, s[52:53]
	v_ashrrev_i32_e32 v81, 31, v80
	v_lshl_add_u64 v[82:83], v[80:81], 1, v[82:83]
	global_store_dwordx4 v[82:83], v[74:77], off sc1
	v_lshl_add_u64 v[82:83], v[94:95], 2, s[60:61]
	v_lshl_add_u64 v[80:81], v[80:81], 2, v[82:83]
	global_store_dwordx4 v[80:81], v[70:73], off nt
	global_store_dwordx4 v[80:81], v[66:69], off offset:16 nt
	s_mov_b64 s[84:85], 0

;     __device__ __forceinline__ void operator()(const f32x4 (&acc)[2][2][4][2], const Unit& u, int wr, int wc, int fr, int fq) const {
;     ...
;                     else if (reg == 6) { const int c = c8 - O_GZ; *(u32x4*)(Zb + (size_t)r * GW + c) = w; }
.LBB0_495:
	s_andn2_b64 vcc, exec, s[80:81]
	s_mov_b64 s[18:19], -1
	s_cbranch_vccnz .LBB0_499
	s_andn2_b64 vcc, exec, s[78:79]
	s_cbranch_vccnz .LBB0_498
	v_lshl_add_u64 v[80:81], s[56:57], 0, v[100:101]
	v_ashrrev_i32_e32 v127, 31, v126
	v_lshl_add_u64 v[80:81], v[126:127], 1, v[80:81]
	v_add_co_u32_e32 v80, vcc, 0xffffd000, v80
	s_nop 1
	v_addc_co_u32_e32 v81, vcc, -1, v81, vcc
	global_store_dwordx4 v[80:81], v[74:77], off sc1

;     __device__ __forceinline__ void operator()(const f32x4 (&acc)[2][2][4][2], const Unit& u, int wr, int wc, int fr, int fq) const {
;     ...
;                     else if (reg < 6) { const int c = c8 - O_GQKV; *(u32x4*)(CIN + (size_t)r * CONVCH + c) = w;
;                         const int t = r & (T - 1); if (t >= T - 3) { float* o = outGconv + ((size_t)(r >> 12) * 3 + (t - (T - 3))) * CONVCH + c; *(f32x4*)o = v0; *(f32x4*)(o + 4) = v1; } }
.LBB0_499:
	s_andn2_b64 vcc, exec, s[18:19]
	s_cbranch_vccnz .LBB0_503
	v_add_u32_e32 v80, 0xfffff480, v160
	v_lshl_add_u64 v[82:83], s[54:55], 0, v[96:97]
	v_ashrrev_i32_e32 v81, 31, v80
	v_lshl_add_u64 v[82:83], v[80:81], 1, v[82:83]
	global_store_dwordx4 v[82:83], v[74:77], off sc1
	s_and_saveexec_b64 s[18:19], s[16:17]
	s_cbranch_execz .LBB0_502
	v_lshl_add_u64 v[82:83], s[62:63], 0, v[98:99]
	v_lshl_add_u64 v[80:81], v[80:81], 2, v[82:83]
	global_store_dwordx4 v[80:81], v[70:73], off sc1
	global_store_dwordx4 v[80:81], v[66:69], off offset:16 sc1

;     __device__ __forceinline__ void operator()(const f32x4 (&acc)[2][2][4][2], const Unit& u, int wr, int wc, int fr, int fq) const {
;     ...
;                     else if (reg == 1) { const int c = c8 - O_SB_K; *(u32x4*)(Kb + (size_t)r * SBW + c) = w; float* o = outK + (size_t)r * SBW + c; __builtin_nontemporal_store(v0, (f32x4*)o); __builtin_nontemporal_store(v1, (f32x4*)(o + 4)); }
.LBB0_507:
	v_add_u32_e32 v80, 0xfffffc80, v160
	v_lshl_add_u64 v[82:83], v[94:95], 1, s[50:51]
	v_ashrrev_i32_e32 v81, 31, v80
	v_lshl_add_u64 v[82:83], v[80:81], 1, v[82:83]
	global_store_dwordx4 v[82:83], v[74:77], off sc1
	v_lshl_add_u64 v[82:83], v[94:95], 2, s[58:59]
	v_lshl_add_u64 v[80:81], v[80:81], 2, v[82:83]
	global_store_dwordx4 v[80:81], v[70:73], off nt
	global_store_dwordx4 v[80:81], v[66:69], off offset:16 nt

; __device__ __forceinline__ unsigned cvt_pk_bf16(float lo, float hi) { unsigned r; asm volatile("v_cvt_pk_bf16_f32 %0, %1, %2" : "=v"(r) : "v"(lo), "v"(hi)); return r; }
;     __device__ __forceinline__ void operator()(const f32x4 (&acc)[2][2][4][2], const Unit& u, int wr, int wc, int fr, int fq) const {
;     ...
;                 const int r = u.pm * BM + ai * HALF + wr * 64 + m * 16 + fr;
; #pragma unroll
;                 for (int bj = 0; bj < 2; ++bj) {
;                     const int c8 = u.pn * BM + bj * HALF + wc * 32 + 8 * fq;
;                     const f32x4 v0 = acc[ai][bj][m][0], v1 = acc[ai][bj][m][1];
;                     u32x4 w; w.x = cvt_pk_bf16(v0[0], v0[1]); w.y = cvt_pk_bf16(v0[2], v0[3]); w.z = cvt_pk_bf16(v1[0], v1[1]); w.w = cvt_pk_bf16(v1[2], v1[3]);
;                     if (reg == 0) { *(u32x4*)(Qb + (size_t)r * SBW + c8) = w; }
;                     else if (reg == 1) { const int c = c8 - O_SB_K; *(u32x4*)(Kb + (size_t)r * SBW + c) = w; float* o = outK + (size_t)r * SBW + c; __builtin_nontemporal_store(v0, (f32x4*)o); __builtin_nontemporal_store(v1, (f32x4*)(o + 4)); }
;                     else if (reg == 2) { const int c = c8 - O_SB_V; *(u32x4*)(Vb + (size_t)r * SBW + c) = w; float* o = outV + (size_t)r * SBW + c; __builtin_nontemporal_store(v0, (f32x4*)o); __builtin_nontemporal_store(v1, (f32x4*)(o + 4)); }
.LBB0_509:
	s_and_b64 vcc, exec, s[18:19]
	s_cbranch_vccz .LBB0_511
	v_lshl_add_u64 v[66:67], v[160:161], 1, v[78:79]
	global_store_dwordx4 v[66:67], v[74:77], off offset:256 sc1
.LBB0_511:
	v_add_u32_e32 v86, 0x80, v162
	v_ashrrev_i32_e32 v66, 12, v86
	v_and_b32_e32 v68, 0xfff, v86
	v_mul_i32_i24_e32 v66, 3, v66
	v_ashrrev_i32_e32 v67, 31, v66
	v_add_u32_e32 v150, 0xfffff003, v68
	v_lshl_add_u64 v[66:67], v[66:67], 0, v[150:151]
	v_ashrrev_i32_e32 v87, 31, v86
	v_mad_i64_i32 v[80:81], s[16:17], v86, s31, 0
	v_mad_u64_u32 v[82:83], s[18:19], v66, s29, 0
	v_lshlrev_b64 v[78:79], 10, v[86:87]
	v_lshlrev_b64 v[84:85], 11, v[86:87]
	v_cmp_lt_u32_e64 s[16:17], s28, v68
	v_mad_i32_i24 v83, v67, s29, v83
	s_and_b64 vcc, exec, s[14:15]
	s_mov_b64 s[18:19], -1
	v_cvt_pk_bf16_f32 v66, v62, v63
	v_cvt_pk_bf16_f32 v67, v64, v65
	v_cvt_pk_bf16_f32 v68, v58, v59
	v_cvt_pk_bf16_f32 v69, v60, v61
	s_cbranch_vccnz .LBB0_569
	s_mov_b64 s[86:87], -1
	s_mov_b64 s[18:19], 0
	s_cmp_lt_i32 s46, 2
	s_mov_b64 s[84:85], 0
	s_cbranch_scc1 .LBB0_564
	s_cmp_eq_u32 s46, 2
	s_mov_b64 s[84:85], -1
	s_cbranch_scc0 .LBB0_515
	v_lshl_add_u64 v[70:71], v[78:79], 1, s[52:53]
	v_lshl_add_u64 v[70:71], v[160:161], 1, v[70:71]
	global_store_dwordx4 v[70:71], v[66:69], off offset:-4096 sc1
	v_lshl_add_u64 v[70:71], v[78:79], 2, s[60:61]
	s_movk_i32 s84, 0xe000
	v_lshl_add_u64 v[70:71], v[160:161], 2, v[70:71]
	s_mov_b32 s85, -1
	v_lshl_add_u64 v[72:73], v[70:71], 0, s[84:85]
	v_add_co_u32_e32 v70, vcc, 0xffffe000, v70
	s_mov_b64 s[84:85], 0
	s_nop 0
	v_addc_co_u32_e32 v71, vcc, -1, v71, vcc
	global_store_dwordx4 v[70:71], v[62:65], off nt
	global_store_dwordx4 v[72:73], v[58:61], off offset:16 nt

;     __device__ __forceinline__ void operator()(const f32x4 (&acc)[2][2][4][2], const Unit& u, int wr, int wc, int fr, int fq) const {
;     ...
;                     else if (bj == 0 && wc == 0 && fq < 2 && u.pn == 28) {
;                         float x[8] = {v0[0], v0[1], v0[2], v0[3], v1[0], v1[1], v1[2], v1[3]}; float y[8];
; #pragma unroll
;                         for (int h = 0; h < 8; ++h) {
;                             const float xb = x[h] + (fq == 0 ? dt_bias[h] : 0.f), e = __expf(-fabsf(xb));
;                             const float sp = fmaxf(xb, 0.f) + __logf(1.0f + e), sg = (xb >= 0.f ? 1.f : e) * __builtin_amdgcn_rcpf(1.0f + e);
;                             y[h] = (fq == 0) ? -__expf(a_log[h]) * sp : sg; }
;                         float* o = (fq == 0 ? G : BETA) + (size_t)r * NH; *(f32x4*)o = (f32x4){y[0], y[1], y[2], y[3]}; *(f32x4*)(o + 4) = (f32x4){y[4], y[5], y[6], y[7]};
.LBB0_554:
	s_or_b64 exec, exec, s[18:19]
	v_lshlrev_b64 v[86:87], 5, v[86:87]
	v_lshl_add_u64 v[88:89], s[26:27], 0, v[88:89]
	v_lshl_add_u64 v[86:87], v[88:89], 0, v[86:87]
	global_store_dwordx4 v[86:87], v[70:73], off sc1
	global_store_dwordx4 v[86:87], v[74:77], off offset:16 sc1

;     __device__ __forceinline__ void operator()(const f32x4 (&acc)[2][2][4][2], const Unit& u, int wr, int wc, int fr, int fq) const {
;     ...
;                     else if (reg == 6) { const int c = c8 - O_GZ; *(u32x4*)(Zb + (size_t)r * GW + c) = w; }
.LBB0_556:
	s_andn2_b64 vcc, exec, s[18:19]
	s_cbranch_vccnz .LBB0_558
	v_lshl_add_u64 v[70:71], s[56:57], 0, v[84:85]
	v_lshl_add_u64 v[70:71], v[160:161], 1, v[70:71]
	v_add_co_u32_e32 v70, vcc, 0xffffd000, v70
	s_nop 1
	v_addc_co_u32_e32 v71, vcc, -1, v71, vcc
	global_store_dwordx4 v[70:71], v[66:69], off sc1

;     __device__ __forceinline__ void operator()(const f32x4 (&acc)[2][2][4][2], const Unit& u, int wr, int wc, int fr, int fq) const {
;     ...
;                     else if (reg < 6) { const int c = c8 - O_GQKV; *(u32x4*)(CIN + (size_t)r * CONVCH + c) = w;
;                         const int t = r & (T - 1); if (t >= T - 3) { float* o = outGconv + ((size_t)(r >> 12) * 3 + (t - (T - 3))) * CONVCH + c; *(f32x4*)o = v0; *(f32x4*)(o + 4) = v1; } }
.LBB0_559:
	s_andn2_b64 vcc, exec, s[18:19]
	s_cbranch_vccnz .LBB0_563
	v_add_u32_e32 v70, 0xfffff400, v160
	v_lshl_add_u64 v[72:73], s[54:55], 0, v[80:81]
	v_ashrrev_i32_e32 v71, 31, v70
	v_lshl_add_u64 v[72:73], v[70:71], 1, v[72:73]
	global_store_dwordx4 v[72:73], v[66:69], off sc1
	s_and_saveexec_b64 s[18:19], s[16:17]
	s_cbranch_execz .LBB0_562
	v_lshl_add_u64 v[72:73], s[62:63], 0, v[82:83]
	v_lshl_add_u64 v[70:71], v[70:71], 2, v[72:73]
	global_store_dwordx4 v[70:71], v[62:65], off sc1
	global_store_dwordx4 v[70:71], v[58:61], off offset:16 sc1

;     __device__ __forceinline__ void operator()(const f32x4 (&acc)[2][2][4][2], const Unit& u, int wr, int wc, int fr, int fq) const {
;     ...
;                     else if (reg == 1) { const int c = c8 - O_SB_K; *(u32x4*)(Kb + (size_t)r * SBW + c) = w; float* o = outK + (size_t)r * SBW + c; __builtin_nontemporal_store(v0, (f32x4*)o); __builtin_nontemporal_store(v1, (f32x4*)(o + 4)); }
.LBB0_567:
	v_lshl_add_u64 v[70:71], v[78:79], 1, s[50:51]
	v_lshl_add_u64 v[70:71], v[160:161], 1, v[70:71]
	global_store_dwordx4 v[70:71], v[66:69], off offset:-2048 sc1
	v_lshl_add_u64 v[70:71], v[78:79], 2, s[58:59]
	v_lshl_add_u64 v[70:71], v[160:161], 2, v[70:71]
	global_store_dwordx4 v[70:71], v[62:65], off offset:-4096 nt
	global_store_dwordx4 v[70:71], v[58:61], off offset:-4080 nt

;     __device__ __forceinline__ void operator()(const f32x4 (&acc)[2][2][4][2], const Unit& u, int wr, int wc, int fr, int fq) const {
;     ...
;                     if (reg == 0) { *(u32x4*)(Qb + (size_t)r * SBW + c8) = w; }
;                     else if (reg == 1) { const int c = c8 - O_SB_K; *(u32x4*)(Kb + (size_t)r * SBW + c) = w; float* o = outK + (size_t)r * SBW + c; __builtin_nontemporal_store(v0, (f32x4*)o); __builtin_nontemporal_store(v1, (f32x4*)(o + 4)); }
;                     else if (reg == 2) { const int c = c8 - O_SB_V; *(u32x4*)(Vb + (size_t)r * SBW + c) = w; float* o = outV + (size_t)r * SBW + c; __builtin_nontemporal_store(v0, (f32x4*)o); __builtin_nontemporal_store(v1, (f32x4*)(o + 4)); }
.LBB0_569:
	s_and_b64 vcc, exec, s[18:19]
	v_lshl_add_u64 v[62:63], s[48:49], 0, v[84:85]
	s_cbranch_vccz .LBB0_571
	v_lshl_add_u64 v[58:59], v[160:161], 1, v[62:63]
	global_store_dwordx4 v[58:59], v[66:69], off sc1
.LBB0_571:
	s_and_b64 vcc, exec, s[14:15]
	s_mov_b64 s[18:19], -1
	v_cvt_pk_bf16_f32 v58, v54, v55
	v_cvt_pk_bf16_f32 v59, v56, v57
	v_cvt_pk_bf16_f32 v60, v50, v51
	v_cvt_pk_bf16_f32 v61, v52, v53
	s_cbranch_vccnz .LBB0_591
	s_mov_b64 s[86:87], -1
	s_mov_b64 s[18:19], 0
	s_cmp_lt_i32 s46, 2
	s_mov_b64 s[84:85], 0
	s_cbranch_scc1 .LBB0_586
	s_cmp_eq_u32 s46, 2
	s_mov_b64 s[84:85], -1
	s_cbranch_scc0 .LBB0_575
	v_add_u32_e32 v64, 0xfffff880, v160
	v_lshl_add_u64 v[66:67], v[78:79], 1, s[52:53]
	v_ashrrev_i32_e32 v65, 31, v64
	v_lshl_add_u64 v[66:67], v[64:65], 1, v[66:67]
	global_store_dwordx4 v[66:67], v[58:61], off sc1
	v_lshl_add_u64 v[66:67], v[78:79], 2, s[60:61]
	v_lshl_add_u64 v[64:65], v[64:65], 2, v[66:67]
	global_store_dwordx4 v[64:65], v[54:57], off nt
	global_store_dwordx4 v[64:65], v[50:53], off offset:16 nt
	s_mov_b64 s[84:85], 0

;     __device__ __forceinline__ void operator()(const f32x4 (&acc)[2][2][4][2], const Unit& u, int wr, int wc, int fr, int fq) const {
;     ...
;                     else if (reg == 6) { const int c = c8 - O_GZ; *(u32x4*)(Zb + (size_t)r * GW + c) = w; }
.LBB0_577:
	s_andn2_b64 vcc, exec, s[80:81]
	s_mov_b64 s[18:19], -1
	s_cbranch_vccnz .LBB0_581
	s_andn2_b64 vcc, exec, s[78:79]
	s_cbranch_vccnz .LBB0_580
	v_lshl_add_u64 v[64:65], s[56:57], 0, v[84:85]
	v_ashrrev_i32_e32 v127, 31, v126
	v_lshl_add_u64 v[64:65], v[126:127], 1, v[64:65]
	v_add_co_u32_e32 v64, vcc, 0xffffd000, v64
	s_nop 1
	v_addc_co_u32_e32 v65, vcc, -1, v65, vcc
	global_store_dwordx4 v[64:65], v[58:61], off sc1

;     __device__ __forceinline__ void operator()(const f32x4 (&acc)[2][2][4][2], const Unit& u, int wr, int wc, int fr, int fq) const {
;     ...
;                     else if (reg < 6) { const int c = c8 - O_GQKV; *(u32x4*)(CIN + (size_t)r * CONVCH + c) = w;
;                         const int t = r & (T - 1); if (t >= T - 3) { float* o = outGconv + ((size_t)(r >> 12) * 3 + (t - (T - 3))) * CONVCH + c; *(f32x4*)o = v0; *(f32x4*)(o + 4) = v1; } }
.LBB0_581:
	s_andn2_b64 vcc, exec, s[18:19]
	s_cbranch_vccnz .LBB0_585
	v_add_u32_e32 v64, 0xfffff480, v160
	v_lshl_add_u64 v[66:67], s[54:55], 0, v[80:81]
	v_ashrrev_i32_e32 v65, 31, v64
	v_lshl_add_u64 v[66:67], v[64:65], 1, v[66:67]
	global_store_dwordx4 v[66:67], v[58:61], off sc1
	s_and_saveexec_b64 s[18:19], s[16:17]
	s_cbranch_execz .LBB0_584
	v_lshl_add_u64 v[66:67], s[62:63], 0, v[82:83]
	v_lshl_add_u64 v[64:65], v[64:65], 2, v[66:67]
	global_store_dwordx4 v[64:65], v[54:57], off sc1
	global_store_dwordx4 v[64:65], v[50:53], off offset:16 sc1

;     __device__ __forceinline__ void operator()(const f32x4 (&acc)[2][2][4][2], const Unit& u, int wr, int wc, int fr, int fq) const {
;     ...
;                     else if (reg == 1) { const int c = c8 - O_SB_K; *(u32x4*)(Kb + (size_t)r * SBW + c) = w; float* o = outK + (size_t)r * SBW + c; __builtin_nontemporal_store(v0, (f32x4*)o); __builtin_nontemporal_store(v1, (f32x4*)(o + 4)); }
.LBB0_589:
	v_add_u32_e32 v64, 0xfffffc80, v160
	v_lshl_add_u64 v[66:67], v[78:79], 1, s[50:51]
	v_ashrrev_i32_e32 v65, 31, v64
	v_lshl_add_u64 v[66:67], v[64:65], 1, v[66:67]
	global_store_dwordx4 v[66:67], v[58:61], off sc1
	v_lshl_add_u64 v[66:67], v[78:79], 2, s[58:59]
	v_lshl_add_u64 v[64:65], v[64:65], 2, v[66:67]
	global_store_dwordx4 v[64:65], v[54:57], off nt
	global_store_dwordx4 v[64:65], v[50:53], off offset:16 nt

; __device__ __forceinline__ unsigned cvt_pk_bf16(float lo, float hi) { unsigned r; asm volatile("v_cvt_pk_bf16_f32 %0, %1, %2" : "=v"(r) : "v"(lo), "v"(hi)); return r; }
;     __device__ __forceinline__ void operator()(const f32x4 (&acc)[2][2][4][2], const Unit& u, int wr, int wc, int fr, int fq) const {
;     ...
;                 const int r = u.pm * BM + ai * HALF + wr * 64 + m * 16 + fr;
; #pragma unroll
;                 for (int bj = 0; bj < 2; ++bj) {
;                     const int c8 = u.pn * BM + bj * HALF + wc * 32 + 8 * fq;
;                     const f32x4 v0 = acc[ai][bj][m][0], v1 = acc[ai][bj][m][1];
;                     u32x4 w; w.x = cvt_pk_bf16(v0[0], v0[1]); w.y = cvt_pk_bf16(v0[2], v0[3]); w.z = cvt_pk_bf16(v1[0], v1[1]); w.w = cvt_pk_bf16(v1[2], v1[3]);
;                     if (reg == 0) { *(u32x4*)(Qb + (size_t)r * SBW + c8) = w; }
;                     else if (reg == 1) { const int c = c8 - O_SB_K; *(u32x4*)(Kb + (size_t)r * SBW + c) = w; float* o = outK + (size_t)r * SBW + c; __builtin_nontemporal_store(v0, (f32x4*)o); __builtin_nontemporal_store(v1, (f32x4*)(o + 4)); }
;                     else if (reg == 2) { const int c = c8 - O_SB_V; *(u32x4*)(Vb + (size_t)r * SBW + c) = w; float* o = outV + (size_t)r * SBW + c; __builtin_nontemporal_store(v0, (f32x4*)o); __builtin_nontemporal_store(v1, (f32x4*)(o + 4)); }
.LBB0_591:
	s_and_b64 vcc, exec, s[18:19]
	s_cbranch_vccz .LBB0_593
	v_lshl_add_u64 v[50:51], v[160:161], 1, v[62:63]
	global_store_dwordx4 v[50:51], v[58:61], off offset:256 sc1
.LBB0_593:
	v_add_u32_e32 v70, 0x90, v162
	v_ashrrev_i32_e32 v50, 12, v70
	v_and_b32_e32 v52, 0xfff, v70
	v_mul_i32_i24_e32 v50, 3, v50
	v_ashrrev_i32_e32 v51, 31, v50
	v_add_u32_e32 v150, 0xfffff003, v52
	v_lshl_add_u64 v[50:51], v[50:51], 0, v[150:151]
	v_ashrrev_i32_e32 v71, 31, v70
	v_mad_i64_i32 v[64:65], s[16:17], v70, s31, 0
	v_mad_u64_u32 v[66:67], s[18:19], v50, s29, 0
	v_lshlrev_b64 v[62:63], 10, v[70:71]
	v_lshlrev_b64 v[68:69], 11, v[70:71]
	v_cmp_lt_u32_e64 s[16:17], s28, v52
	v_mad_i32_i24 v67, v51, s29, v67
	s_and_b64 vcc, exec, s[14:15]
	s_mov_b64 s[18:19], -1
	v_cvt_pk_bf16_f32 v50, v46, v47
	v_cvt_pk_bf16_f32 v51, v48, v49
	v_cvt_pk_bf16_f32 v52, v42, v43
	v_cvt_pk_bf16_f32 v53, v44, v45
	s_cbranch_vccnz .LBB0_651
	s_mov_b64 s[86:87], -1
	s_mov_b64 s[18:19], 0
	s_cmp_lt_i32 s46, 2
	s_mov_b64 s[84:85], 0
	s_cbranch_scc1 .LBB0_646
	s_cmp_eq_u32 s46, 2
	s_mov_b64 s[84:85], -1
	s_cbranch_scc0 .LBB0_597
	v_lshl_add_u64 v[54:55], v[62:63], 1, s[52:53]
	v_lshl_add_u64 v[54:55], v[160:161], 1, v[54:55]
	global_store_dwordx4 v[54:55], v[50:53], off offset:-4096 sc1
	v_lshl_add_u64 v[54:55], v[62:63], 2, s[60:61]
	s_movk_i32 s84, 0xe000
	v_lshl_add_u64 v[54:55], v[160:161], 2, v[54:55]
	s_mov_b32 s85, -1
	v_lshl_add_u64 v[56:57], v[54:55], 0, s[84:85]
	v_add_co_u32_e32 v54, vcc, 0xffffe000, v54
	s_mov_b64 s[84:85], 0
	s_nop 0
	v_addc_co_u32_e32 v55, vcc, -1, v55, vcc
	global_store_dwordx4 v[54:55], v[46:49], off nt
	global_store_dwordx4 v[56:57], v[42:45], off offset:16 nt

;     __device__ __forceinline__ void operator()(const f32x4 (&acc)[2][2][4][2], const Unit& u, int wr, int wc, int fr, int fq) const {
;     ...
;                     else if (bj == 0 && wc == 0 && fq < 2 && u.pn == 28) {
;                         float x[8] = {v0[0], v0[1], v0[2], v0[3], v1[0], v1[1], v1[2], v1[3]}; float y[8];
; #pragma unroll
;                         for (int h = 0; h < 8; ++h) {
;                             const float xb = x[h] + (fq == 0 ? dt_bias[h] : 0.f), e = __expf(-fabsf(xb));
;                             const float sp = fmaxf(xb, 0.f) + __logf(1.0f + e), sg = (xb >= 0.f ? 1.f : e) * __builtin_amdgcn_rcpf(1.0f + e);
;                             y[h] = (fq == 0) ? -__expf(a_log[h]) * sp : sg; }
;                         float* o = (fq == 0 ? G : BETA) + (size_t)r * NH; *(f32x4*)o = (f32x4){y[0], y[1], y[2], y[3]}; *(f32x4*)(o + 4) = (f32x4){y[4], y[5], y[6], y[7]};
.LBB0_636:
	s_or_b64 exec, exec, s[18:19]
	v_lshlrev_b64 v[70:71], 5, v[70:71]
	v_lshl_add_u64 v[72:73], s[26:27], 0, v[72:73]
	v_lshl_add_u64 v[70:71], v[72:73], 0, v[70:71]
	global_store_dwordx4 v[70:71], v[54:57], off sc1
	global_store_dwordx4 v[70:71], v[58:61], off offset:16 sc1

;     __device__ __forceinline__ void operator()(const f32x4 (&acc)[2][2][4][2], const Unit& u, int wr, int wc, int fr, int fq) const {
;     ...
;                     else if (reg == 6) { const int c = c8 - O_GZ; *(u32x4*)(Zb + (size_t)r * GW + c) = w; }
.LBB0_638:
	s_andn2_b64 vcc, exec, s[18:19]
	s_cbranch_vccnz .LBB0_640
	v_lshl_add_u64 v[54:55], s[56:57], 0, v[68:69]
	v_lshl_add_u64 v[54:55], v[160:161], 1, v[54:55]
	v_add_co_u32_e32 v54, vcc, 0xffffd000, v54
	s_nop 1
	v_addc_co_u32_e32 v55, vcc, -1, v55, vcc
	global_store_dwordx4 v[54:55], v[50:53], off sc1

;     __device__ __forceinline__ void operator()(const f32x4 (&acc)[2][2][4][2], const Unit& u, int wr, int wc, int fr, int fq) const {
;     ...
;                     else if (reg < 6) { const int c = c8 - O_GQKV; *(u32x4*)(CIN + (size_t)r * CONVCH + c) = w;
;                         const int t = r & (T - 1); if (t >= T - 3) { float* o = outGconv + ((size_t)(r >> 12) * 3 + (t - (T - 3))) * CONVCH + c; *(f32x4*)o = v0; *(f32x4*)(o + 4) = v1; } }
.LBB0_641:
	s_andn2_b64 vcc, exec, s[18:19]
	s_cbranch_vccnz .LBB0_645
	v_add_u32_e32 v54, 0xfffff400, v160
	v_lshl_add_u64 v[56:57], s[54:55], 0, v[64:65]
	v_ashrrev_i32_e32 v55, 31, v54
	v_lshl_add_u64 v[56:57], v[54:55], 1, v[56:57]
	global_store_dwordx4 v[56:57], v[50:53], off sc1
	s_and_saveexec_b64 s[18:19], s[16:17]
	s_cbranch_execz .LBB0_644
	v_lshl_add_u64 v[56:57], s[62:63], 0, v[66:67]
	v_lshl_add_u64 v[54:55], v[54:55], 2, v[56:57]
	global_store_dwordx4 v[54:55], v[46:49], off sc1
	global_store_dwordx4 v[54:55], v[42:45], off offset:16 sc1

;     __device__ __forceinline__ void operator()(const f32x4 (&acc)[2][2][4][2], const Unit& u, int wr, int wc, int fr, int fq) const {
;     ...
;                     else if (reg == 1) { const int c = c8 - O_SB_K; *(u32x4*)(Kb + (size_t)r * SBW + c) = w; float* o = outK + (size_t)r * SBW + c; __builtin_nontemporal_store(v0, (f32x4*)o); __builtin_nontemporal_store(v1, (f32x4*)(o + 4)); }
.LBB0_649:
	v_lshl_add_u64 v[54:55], v[62:63], 1, s[50:51]
	v_lshl_add_u64 v[54:55], v[160:161], 1, v[54:55]
	global_store_dwordx4 v[54:55], v[50:53], off offset:-2048 sc1
	v_lshl_add_u64 v[54:55], v[62:63], 2, s[58:59]
	v_lshl_add_u64 v[54:55], v[160:161], 2, v[54:55]
	global_store_dwordx4 v[54:55], v[46:49], off offset:-4096 nt
	global_store_dwordx4 v[54:55], v[42:45], off offset:-4080 nt

; __device__ __forceinline__ unsigned cvt_pk_bf16(float lo, float hi) { unsigned r; asm volatile("v_cvt_pk_bf16_f32 %0, %1, %2" : "=v"(r) : "v"(lo), "v"(hi)); return r; }
;     __device__ __forceinline__ void operator()(const f32x4 (&acc)[2][2][4][2], const Unit& u, int wr, int wc, int fr, int fq) const {
;     ...
;                     u32x4 w; w.x = cvt_pk_bf16(v0[0], v0[1]); w.y = cvt_pk_bf16(v0[2], v0[3]); w.z = cvt_pk_bf16(v1[0], v1[1]); w.w = cvt_pk_bf16(v1[2], v1[3]);
;                     if (reg == 0) { *(u32x4*)(Qb + (size_t)r * SBW + c8) = w; }
;                     else if (reg == 1) { const int c = c8 - O_SB_K; *(u32x4*)(Kb + (size_t)r * SBW + c) = w; float* o = outK + (size_t)r * SBW + c; __builtin_nontemporal_store(v0, (f32x4*)o); __builtin_nontemporal_store(v1, (f32x4*)(o + 4)); }
;                     else if (reg == 2) { const int c = c8 - O_SB_V; *(u32x4*)(Vb + (size_t)r * SBW + c) = w; float* o = outV + (size_t)r * SBW + c; __builtin_nontemporal_store(v0, (f32x4*)o); __builtin_nontemporal_store(v1, (f32x4*)(o + 4)); }
.LBB0_651:
	s_and_b64 vcc, exec, s[18:19]
	v_lshl_add_u64 v[46:47], s[48:49], 0, v[68:69]
	s_cbranch_vccz .LBB0_653
	v_lshl_add_u64 v[42:43], v[160:161], 1, v[46:47]
	global_store_dwordx4 v[42:43], v[50:53], off sc1
.LBB0_653:
	s_and_b64 vcc, exec, s[14:15]
	s_mov_b64 s[18:19], -1
	v_cvt_pk_bf16_f32 v42, v38, v39
	v_cvt_pk_bf16_f32 v43, v40, v41
	v_cvt_pk_bf16_f32 v44, v34, v35
	v_cvt_pk_bf16_f32 v45, v36, v37
	s_cbranch_vccnz .LBB0_673
	s_mov_b64 s[86:87], -1
	s_mov_b64 s[18:19], 0
	s_cmp_lt_i32 s46, 2
	s_mov_b64 s[84:85], 0
	s_cbranch_scc1 .LBB0_668
	s_cmp_eq_u32 s46, 2
	s_mov_b64 s[84:85], -1
	s_cbranch_scc0 .LBB0_657
	v_add_u32_e32 v48, 0xfffff880, v160
	v_lshl_add_u64 v[50:51], v[62:63], 1, s[52:53]
	v_ashrrev_i32_e32 v49, 31, v48
	v_lshl_add_u64 v[50:51], v[48:49], 1, v[50:51]
	global_store_dwordx4 v[50:51], v[42:45], off sc1
	v_lshl_add_u64 v[50:51], v[62:63], 2, s[60:61]
	v_lshl_add_u64 v[48:49], v[48:49], 2, v[50:51]
	global_store_dwordx4 v[48:49], v[38:41], off nt
	global_store_dwordx4 v[48:49], v[34:37], off offset:16 nt
	s_mov_b64 s[84:85], 0

;     __device__ __forceinline__ void operator()(const f32x4 (&acc)[2][2][4][2], const Unit& u, int wr, int wc, int fr, int fq) const {
;     ...
;                     else if (reg == 6) { const int c = c8 - O_GZ; *(u32x4*)(Zb + (size_t)r * GW + c) = w; }
.LBB0_659:
	s_andn2_b64 vcc, exec, s[80:81]
	s_mov_b64 s[18:19], -1
	s_cbranch_vccnz .LBB0_663
	s_andn2_b64 vcc, exec, s[78:79]
	s_cbranch_vccnz .LBB0_662
	v_lshl_add_u64 v[48:49], s[56:57], 0, v[68:69]
	v_ashrrev_i32_e32 v127, 31, v126
	v_lshl_add_u64 v[48:49], v[126:127], 1, v[48:49]
	v_add_co_u32_e32 v48, vcc, 0xffffd000, v48
	s_nop 1
	v_addc_co_u32_e32 v49, vcc, -1, v49, vcc
	global_store_dwordx4 v[48:49], v[42:45], off sc1

;     __device__ __forceinline__ void operator()(const f32x4 (&acc)[2][2][4][2], const Unit& u, int wr, int wc, int fr, int fq) const {
;     ...
;                     else if (reg < 6) { const int c = c8 - O_GQKV; *(u32x4*)(CIN + (size_t)r * CONVCH + c) = w;
;                         const int t = r & (T - 1); if (t >= T - 3) { float* o = outGconv + ((size_t)(r >> 12) * 3 + (t - (T - 3))) * CONVCH + c; *(f32x4*)o = v0; *(f32x4*)(o + 4) = v1; } }
.LBB0_663:
	s_andn2_b64 vcc, exec, s[18:19]
	s_cbranch_vccnz .LBB0_667
	v_add_u32_e32 v48, 0xfffff480, v160
	v_lshl_add_u64 v[50:51], s[54:55], 0, v[64:65]
	v_ashrrev_i32_e32 v49, 31, v48
	v_lshl_add_u64 v[50:51], v[48:49], 1, v[50:51]
	global_store_dwordx4 v[50:51], v[42:45], off sc1
	s_and_saveexec_b64 s[18:19], s[16:17]
	s_cbranch_execz .LBB0_666
	v_lshl_add_u64 v[50:51], s[62:63], 0, v[66:67]
	v_lshl_add_u64 v[48:49], v[48:49], 2, v[50:51]
	global_store_dwordx4 v[48:49], v[38:41], off sc1
	global_store_dwordx4 v[48:49], v[34:37], off offset:16 sc1

;     __device__ __forceinline__ void operator()(const f32x4 (&acc)[2][2][4][2], const Unit& u, int wr, int wc, int fr, int fq) const {
;     ...
;                     else if (reg == 1) { const int c = c8 - O_SB_K; *(u32x4*)(Kb + (size_t)r * SBW + c) = w; float* o = outK + (size_t)r * SBW + c; __builtin_nontemporal_store(v0, (f32x4*)o); __builtin_nontemporal_store(v1, (f32x4*)(o + 4)); }
.LBB0_671:
	v_add_u32_e32 v48, 0xfffffc80, v160
	v_lshl_add_u64 v[50:51], v[62:63], 1, s[50:51]
	v_ashrrev_i32_e32 v49, 31, v48
	v_lshl_add_u64 v[50:51], v[48:49], 1, v[50:51]
	global_store_dwordx4 v[50:51], v[42:45], off sc1
	v_lshl_add_u64 v[50:51], v[62:63], 2, s[58:59]
	v_lshl_add_u64 v[48:49], v[48:49], 2, v[50:51]
	global_store_dwordx4 v[48:49], v[38:41], off nt
	global_store_dwordx4 v[48:49], v[34:37], off offset:16 nt

; __device__ __forceinline__ unsigned cvt_pk_bf16(float lo, float hi) { unsigned r; asm volatile("v_cvt_pk_bf16_f32 %0, %1, %2" : "=v"(r) : "v"(lo), "v"(hi)); return r; }
;     __device__ __forceinline__ void operator()(const f32x4 (&acc)[2][2][4][2], const Unit& u, int wr, int wc, int fr, int fq) const {
;     ...
;                 const int r = u.pm * BM + ai * HALF + wr * 64 + m * 16 + fr;
; #pragma unroll
;                 for (int bj = 0; bj < 2; ++bj) {
;                     const int c8 = u.pn * BM + bj * HALF + wc * 32 + 8 * fq;
;                     const f32x4 v0 = acc[ai][bj][m][0], v1 = acc[ai][bj][m][1];
;                     u32x4 w; w.x = cvt_pk_bf16(v0[0], v0[1]); w.y = cvt_pk_bf16(v0[2], v0[3]); w.z = cvt_pk_bf16(v1[0], v1[1]); w.w = cvt_pk_bf16(v1[2], v1[3]);
;                     if (reg == 0) { *(u32x4*)(Qb + (size_t)r * SBW + c8) = w; }
;                     else if (reg == 1) { const int c = c8 - O_SB_K; *(u32x4*)(Kb + (size_t)r * SBW + c) = w; float* o = outK + (size_t)r * SBW + c; __builtin_nontemporal_store(v0, (f32x4*)o); __builtin_nontemporal_store(v1, (f32x4*)(o + 4)); }
;                     else if (reg == 2) { const int c = c8 - O_SB_V; *(u32x4*)(Vb + (size_t)r * SBW + c) = w; float* o = outV + (size_t)r * SBW + c; __builtin_nontemporal_store(v0, (f32x4*)o); __builtin_nontemporal_store(v1, (f32x4*)(o + 4)); }
.LBB0_673:
	s_and_b64 vcc, exec, s[18:19]
	s_cbranch_vccz .LBB0_675
	v_lshl_add_u64 v[34:35], v[160:161], 1, v[46:47]
	global_store_dwordx4 v[34:35], v[42:45], off offset:256 sc1
.LBB0_675:
	v_add_u32_e32 v54, 0xa0, v162
	v_ashrrev_i32_e32 v34, 12, v54
	v_and_b32_e32 v36, 0xfff, v54
	v_mul_i32_i24_e32 v34, 3, v34
	v_ashrrev_i32_e32 v35, 31, v34
	v_add_u32_e32 v150, 0xfffff003, v36
	v_lshl_add_u64 v[34:35], v[34:35], 0, v[150:151]
	v_ashrrev_i32_e32 v55, 31, v54
	v_mad_i64_i32 v[48:49], s[16:17], v54, s31, 0
	v_mad_u64_u32 v[50:51], s[18:19], v34, s29, 0
	v_lshlrev_b64 v[46:47], 10, v[54:55]
	v_lshlrev_b64 v[52:53], 11, v[54:55]
	v_cmp_lt_u32_e64 s[16:17], s28, v36
	v_mad_i32_i24 v51, v35, s29, v51
	s_and_b64 vcc, exec, s[14:15]
	s_mov_b64 s[18:19], -1
	v_cvt_pk_bf16_f32 v34, v30, v31
	v_cvt_pk_bf16_f32 v35, v32, v33
	v_cvt_pk_bf16_f32 v36, v26, v27
	v_cvt_pk_bf16_f32 v37, v28, v29
	s_cbranch_vccnz .LBB0_733
	s_mov_b64 s[86:87], -1
	s_mov_b64 s[18:19], 0
	s_cmp_lt_i32 s46, 2
	s_mov_b64 s[84:85], 0
	s_cbranch_scc1 .LBB0_728
	s_cmp_eq_u32 s46, 2
	s_mov_b64 s[84:85], -1
	s_cbranch_scc0 .LBB0_679
	v_lshl_add_u64 v[38:39], v[46:47], 1, s[52:53]
	v_lshl_add_u64 v[38:39], v[160:161], 1, v[38:39]
	global_store_dwordx4 v[38:39], v[34:37], off offset:-4096 sc1
	v_lshl_add_u64 v[38:39], v[46:47], 2, s[60:61]
	s_movk_i32 s84, 0xe000
	v_lshl_add_u64 v[38:39], v[160:161], 2, v[38:39]
	s_mov_b32 s85, -1
	v_lshl_add_u64 v[40:41], v[38:39], 0, s[84:85]
	v_add_co_u32_e32 v38, vcc, 0xffffe000, v38
	s_mov_b64 s[84:85], 0
	s_nop 0
	v_addc_co_u32_e32 v39, vcc, -1, v39, vcc
	global_store_dwordx4 v[38:39], v[30:33], off nt
	global_store_dwordx4 v[40:41], v[26:29], off offset:16 nt

;     __device__ __forceinline__ void operator()(const f32x4 (&acc)[2][2][4][2], const Unit& u, int wr, int wc, int fr, int fq) const {
;     ...
;                     else if (bj == 0 && wc == 0 && fq < 2 && u.pn == 28) {
;                         float x[8] = {v0[0], v0[1], v0[2], v0[3], v1[0], v1[1], v1[2], v1[3]}; float y[8];
; #pragma unroll
;                         for (int h = 0; h < 8; ++h) {
;                             const float xb = x[h] + (fq == 0 ? dt_bias[h] : 0.f), e = __expf(-fabsf(xb));
;                             const float sp = fmaxf(xb, 0.f) + __logf(1.0f + e), sg = (xb >= 0.f ? 1.f : e) * __builtin_amdgcn_rcpf(1.0f + e);
;                             y[h] = (fq == 0) ? -__expf(a_log[h]) * sp : sg; }
;                         float* o = (fq == 0 ? G : BETA) + (size_t)r * NH; *(f32x4*)o = (f32x4){y[0], y[1], y[2], y[3]}; *(f32x4*)(o + 4) = (f32x4){y[4], y[5], y[6], y[7]};
.LBB0_718:
	s_or_b64 exec, exec, s[18:19]
	v_lshlrev_b64 v[54:55], 5, v[54:55]
	v_lshl_add_u64 v[56:57], s[26:27], 0, v[56:57]
	v_lshl_add_u64 v[54:55], v[56:57], 0, v[54:55]
	global_store_dwordx4 v[54:55], v[38:41], off sc1
	global_store_dwordx4 v[54:55], v[42:45], off offset:16 sc1

;     __device__ __forceinline__ void operator()(const f32x4 (&acc)[2][2][4][2], const Unit& u, int wr, int wc, int fr, int fq) const {
;     ...
;                     else if (reg == 6) { const int c = c8 - O_GZ; *(u32x4*)(Zb + (size_t)r * GW + c) = w; }
.LBB0_720:
	s_andn2_b64 vcc, exec, s[18:19]
	s_cbranch_vccnz .LBB0_722
	v_lshl_add_u64 v[38:39], s[56:57], 0, v[52:53]
	v_lshl_add_u64 v[38:39], v[160:161], 1, v[38:39]
	v_add_co_u32_e32 v38, vcc, 0xffffd000, v38
	s_nop 1
	v_addc_co_u32_e32 v39, vcc, -1, v39, vcc
	global_store_dwordx4 v[38:39], v[34:37], off sc1

;     __device__ __forceinline__ void operator()(const f32x4 (&acc)[2][2][4][2], const Unit& u, int wr, int wc, int fr, int fq) const {
;     ...
;                     else if (reg < 6) { const int c = c8 - O_GQKV; *(u32x4*)(CIN + (size_t)r * CONVCH + c) = w;
;                         const int t = r & (T - 1); if (t >= T - 3) { float* o = outGconv + ((size_t)(r >> 12) * 3 + (t - (T - 3))) * CONVCH + c; *(f32x4*)o = v0; *(f32x4*)(o + 4) = v1; } }
.LBB0_723:
	s_andn2_b64 vcc, exec, s[18:19]
	s_cbranch_vccnz .LBB0_727
	v_add_u32_e32 v38, 0xfffff400, v160
	v_lshl_add_u64 v[40:41], s[54:55], 0, v[48:49]
	v_ashrrev_i32_e32 v39, 31, v38
	v_lshl_add_u64 v[40:41], v[38:39], 1, v[40:41]
	global_store_dwordx4 v[40:41], v[34:37], off sc1
	s_and_saveexec_b64 s[18:19], s[16:17]
	s_cbranch_execz .LBB0_726
	v_lshl_add_u64 v[40:41], s[62:63], 0, v[50:51]
	v_lshl_add_u64 v[38:39], v[38:39], 2, v[40:41]
	global_store_dwordx4 v[38:39], v[30:33], off sc1
	global_store_dwordx4 v[38:39], v[26:29], off offset:16 sc1

;     __device__ __forceinline__ void operator()(const f32x4 (&acc)[2][2][4][2], const Unit& u, int wr, int wc, int fr, int fq) const {
;     ...
;                     else if (reg == 1) { const int c = c8 - O_SB_K; *(u32x4*)(Kb + (size_t)r * SBW + c) = w; float* o = outK + (size_t)r * SBW + c; __builtin_nontemporal_store(v0, (f32x4*)o); __builtin_nontemporal_store(v1, (f32x4*)(o + 4)); }
.LBB0_731:
	v_lshl_add_u64 v[38:39], v[46:47], 1, s[50:51]
	v_lshl_add_u64 v[38:39], v[160:161], 1, v[38:39]
	global_store_dwordx4 v[38:39], v[34:37], off offset:-2048 sc1
	v_lshl_add_u64 v[38:39], v[46:47], 2, s[58:59]
	v_lshl_add_u64 v[38:39], v[160:161], 2, v[38:39]
	global_store_dwordx4 v[38:39], v[30:33], off offset:-4096 nt
	global_store_dwordx4 v[38:39], v[26:29], off offset:-4080 nt

; __device__ __forceinline__ unsigned cvt_pk_bf16(float lo, float hi) { unsigned r; asm volatile("v_cvt_pk_bf16_f32 %0, %1, %2" : "=v"(r) : "v"(lo), "v"(hi)); return r; }
;     __device__ __forceinline__ void operator()(const f32x4 (&acc)[2][2][4][2], const Unit& u, int wr, int wc, int fr, int fq) const {
;     ...
;                     u32x4 w; w.x = cvt_pk_bf16(v0[0], v0[1]); w.y = cvt_pk_bf16(v0[2], v0[3]); w.z = cvt_pk_bf16(v1[0], v1[1]); w.w = cvt_pk_bf16(v1[2], v1[3]);
;                     if (reg == 0) { *(u32x4*)(Qb + (size_t)r * SBW + c8) = w; }
;                     else if (reg == 1) { const int c = c8 - O_SB_K; *(u32x4*)(Kb + (size_t)r * SBW + c) = w; float* o = outK + (size_t)r * SBW + c; __builtin_nontemporal_store(v0, (f32x4*)o); __builtin_nontemporal_store(v1, (f32x4*)(o + 4)); }
;                     else if (reg == 2) { const int c = c8 - O_SB_V; *(u32x4*)(Vb + (size_t)r * SBW + c) = w; float* o = outV + (size_t)r * SBW + c; __builtin_nontemporal_store(v0, (f32x4*)o); __builtin_nontemporal_store(v1, (f32x4*)(o + 4)); }
.LBB0_733:
	s_and_b64 vcc, exec, s[18:19]
	v_lshl_add_u64 v[30:31], s[48:49], 0, v[52:53]
	s_cbranch_vccz .LBB0_735
	v_lshl_add_u64 v[26:27], v[160:161], 1, v[30:31]
	global_store_dwordx4 v[26:27], v[34:37], off sc1
.LBB0_735:
	s_and_b64 vcc, exec, s[14:15]
	s_mov_b64 s[18:19], -1
	v_cvt_pk_bf16_f32 v26, v22, v23
	v_cvt_pk_bf16_f32 v27, v24, v25
	v_cvt_pk_bf16_f32 v28, v18, v19
	v_cvt_pk_bf16_f32 v29, v20, v21
	s_cbranch_vccnz .LBB0_755
	s_mov_b64 s[86:87], -1
	s_mov_b64 s[18:19], 0
	s_cmp_lt_i32 s46, 2
	s_mov_b64 s[84:85], 0
	s_cbranch_scc1 .LBB0_750
	s_cmp_eq_u32 s46, 2
	s_mov_b64 s[84:85], -1
	s_cbranch_scc0 .LBB0_739
	v_add_u32_e32 v32, 0xfffff880, v160
	v_lshl_add_u64 v[34:35], v[46:47], 1, s[52:53]
	v_ashrrev_i32_e32 v33, 31, v32
	v_lshl_add_u64 v[34:35], v[32:33], 1, v[34:35]
	global_store_dwordx4 v[34:35], v[26:29], off sc1
	v_lshl_add_u64 v[34:35], v[46:47], 2, s[60:61]
	v_lshl_add_u64 v[32:33], v[32:33], 2, v[34:35]
	global_store_dwordx4 v[32:33], v[22:25], off nt
	global_store_dwordx4 v[32:33], v[18:21], off offset:16 nt
	s_mov_b64 s[84:85], 0

;     __device__ __forceinline__ void operator()(const f32x4 (&acc)[2][2][4][2], const Unit& u, int wr, int wc, int fr, int fq) const {
;     ...
;                     else if (reg == 6) { const int c = c8 - O_GZ; *(u32x4*)(Zb + (size_t)r * GW + c) = w; }
.LBB0_741:
	s_andn2_b64 vcc, exec, s[80:81]
	s_mov_b64 s[18:19], -1
	s_cbranch_vccnz .LBB0_745
	s_andn2_b64 vcc, exec, s[78:79]
	s_cbranch_vccnz .LBB0_744
	v_lshl_add_u64 v[32:33], s[56:57], 0, v[52:53]
	v_ashrrev_i32_e32 v127, 31, v126
	v_lshl_add_u64 v[32:33], v[126:127], 1, v[32:33]
	v_add_co_u32_e32 v32, vcc, 0xffffd000, v32
	s_nop 1
	v_addc_co_u32_e32 v33, vcc, -1, v33, vcc
	global_store_dwordx4 v[32:33], v[26:29], off sc1

;     __device__ __forceinline__ void operator()(const f32x4 (&acc)[2][2][4][2], const Unit& u, int wr, int wc, int fr, int fq) const {
;     ...
;                     else if (reg < 6) { const int c = c8 - O_GQKV; *(u32x4*)(CIN + (size_t)r * CONVCH + c) = w;
;                         const int t = r & (T - 1); if (t >= T - 3) { float* o = outGconv + ((size_t)(r >> 12) * 3 + (t - (T - 3))) * CONVCH + c; *(f32x4*)o = v0; *(f32x4*)(o + 4) = v1; } }
.LBB0_745:
	s_andn2_b64 vcc, exec, s[18:19]
	s_cbranch_vccnz .LBB0_749
	v_add_u32_e32 v32, 0xfffff480, v160
	v_lshl_add_u64 v[34:35], s[54:55], 0, v[48:49]
	v_ashrrev_i32_e32 v33, 31, v32
	v_lshl_add_u64 v[34:35], v[32:33], 1, v[34:35]
	global_store_dwordx4 v[34:35], v[26:29], off sc1
	s_and_saveexec_b64 s[18:19], s[16:17]
	s_cbranch_execz .LBB0_748
	v_lshl_add_u64 v[34:35], s[62:63], 0, v[50:51]
	v_lshl_add_u64 v[32:33], v[32:33], 2, v[34:35]
	global_store_dwordx4 v[32:33], v[22:25], off sc1
	global_store_dwordx4 v[32:33], v[18:21], off offset:16 sc1

;     __device__ __forceinline__ void operator()(const f32x4 (&acc)[2][2][4][2], const Unit& u, int wr, int wc, int fr, int fq) const {
;     ...
;                     else if (reg == 1) { const int c = c8 - O_SB_K; *(u32x4*)(Kb + (size_t)r * SBW + c) = w; float* o = outK + (size_t)r * SBW + c; __builtin_nontemporal_store(v0, (f32x4*)o); __builtin_nontemporal_store(v1, (f32x4*)(o + 4)); }
.LBB0_753:
	v_add_u32_e32 v32, 0xfffffc80, v160
	v_lshl_add_u64 v[34:35], v[46:47], 1, s[50:51]
	v_ashrrev_i32_e32 v33, 31, v32
	v_lshl_add_u64 v[34:35], v[32:33], 1, v[34:35]
	global_store_dwordx4 v[34:35], v[26:29], off sc1
	v_lshl_add_u64 v[34:35], v[46:47], 2, s[58:59]
	v_lshl_add_u64 v[32:33], v[32:33], 2, v[34:35]
	global_store_dwordx4 v[32:33], v[22:25], off nt
	global_store_dwordx4 v[32:33], v[18:21], off offset:16 nt

; __device__ __forceinline__ unsigned cvt_pk_bf16(float lo, float hi) { unsigned r; asm volatile("v_cvt_pk_bf16_f32 %0, %1, %2" : "=v"(r) : "v"(lo), "v"(hi)); return r; }
;     __device__ __forceinline__ void operator()(const f32x4 (&acc)[2][2][4][2], const Unit& u, int wr, int wc, int fr, int fq) const {
;     ...
;                 const int r = u.pm * BM + ai * HALF + wr * 64 + m * 16 + fr;
; #pragma unroll
;                 for (int bj = 0; bj < 2; ++bj) {
;                     const int c8 = u.pn * BM + bj * HALF + wc * 32 + 8 * fq;
;                     const f32x4 v0 = acc[ai][bj][m][0], v1 = acc[ai][bj][m][1];
;                     u32x4 w; w.x = cvt_pk_bf16(v0[0], v0[1]); w.y = cvt_pk_bf16(v0[2], v0[3]); w.z = cvt_pk_bf16(v1[0], v1[1]); w.w = cvt_pk_bf16(v1[2], v1[3]);
;                     if (reg == 0) { *(u32x4*)(Qb + (size_t)r * SBW + c8) = w; }
;                     else if (reg == 1) { const int c = c8 - O_SB_K; *(u32x4*)(Kb + (size_t)r * SBW + c) = w; float* o = outK + (size_t)r * SBW + c; __builtin_nontemporal_store(v0, (f32x4*)o); __builtin_nontemporal_store(v1, (f32x4*)(o + 4)); }
;                     else if (reg == 2) { const int c = c8 - O_SB_V; *(u32x4*)(Vb + (size_t)r * SBW + c) = w; float* o = outV + (size_t)r * SBW + c; __builtin_nontemporal_store(v0, (f32x4*)o); __builtin_nontemporal_store(v1, (f32x4*)(o + 4)); }
.LBB0_755:
	s_and_b64 vcc, exec, s[18:19]
	s_cbranch_vccz .LBB0_757
	v_lshl_add_u64 v[18:19], v[160:161], 1, v[30:31]
	global_store_dwordx4 v[18:19], v[26:29], off offset:256 sc1
.LBB0_757:
	v_add_u32_e32 v38, 0xb0, v162
	v_ashrrev_i32_e32 v18, 12, v38
	v_and_b32_e32 v20, 0xfff, v38
	v_mul_i32_i24_e32 v18, 3, v18
	v_ashrrev_i32_e32 v19, 31, v18
	v_add_u32_e32 v150, 0xfffff003, v20
	v_lshl_add_u64 v[18:19], v[18:19], 0, v[150:151]
	v_ashrrev_i32_e32 v39, 31, v38
	v_mad_i64_i32 v[32:33], s[16:17], v38, s31, 0
	v_mad_u64_u32 v[34:35], s[18:19], v18, s29, 0
	v_lshlrev_b64 v[30:31], 10, v[38:39]
	v_lshlrev_b64 v[36:37], 11, v[38:39]
	v_cmp_lt_u32_e64 s[16:17], s28, v20
	v_mad_i32_i24 v35, v19, s29, v35
	s_and_b64 vcc, exec, s[14:15]
	s_mov_b64 s[18:19], -1
	v_cvt_pk_bf16_f32 v18, v14, v15
	v_cvt_pk_bf16_f32 v19, v16, v17
	v_cvt_pk_bf16_f32 v20, v10, v11
	v_cvt_pk_bf16_f32 v21, v12, v13
	s_cbranch_vccnz .LBB0_815
	s_mov_b64 s[86:87], -1
	s_mov_b64 s[18:19], 0
	s_cmp_lt_i32 s46, 2
	s_mov_b64 s[84:85], 0
	s_cbranch_scc1 .LBB0_810
	s_cmp_eq_u32 s46, 2
	s_mov_b64 s[84:85], -1
	s_cbranch_scc0 .LBB0_761
	v_lshl_add_u64 v[22:23], v[30:31], 1, s[52:53]
	v_lshl_add_u64 v[22:23], v[160:161], 1, v[22:23]
	global_store_dwordx4 v[22:23], v[18:21], off offset:-4096 sc1
	v_lshl_add_u64 v[22:23], v[30:31], 2, s[60:61]
	s_movk_i32 s84, 0xe000
	v_lshl_add_u64 v[22:23], v[160:161], 2, v[22:23]
	s_mov_b32 s85, -1
	v_lshl_add_u64 v[24:25], v[22:23], 0, s[84:85]
	v_add_co_u32_e32 v22, vcc, 0xffffe000, v22
	s_mov_b64 s[84:85], 0
	s_nop 0
	v_addc_co_u32_e32 v23, vcc, -1, v23, vcc
	global_store_dwordx4 v[22:23], v[14:17], off nt
	global_store_dwordx4 v[24:25], v[10:13], off offset:16 nt

;     __device__ __forceinline__ void operator()(const f32x4 (&acc)[2][2][4][2], const Unit& u, int wr, int wc, int fr, int fq) const {
;     ...
;                     else if (bj == 0 && wc == 0 && fq < 2 && u.pn == 28) {
;                         float x[8] = {v0[0], v0[1], v0[2], v0[3], v1[0], v1[1], v1[2], v1[3]}; float y[8];
; #pragma unroll
;                         for (int h = 0; h < 8; ++h) {
;                             const float xb = x[h] + (fq == 0 ? dt_bias[h] : 0.f), e = __expf(-fabsf(xb));
;                             const float sp = fmaxf(xb, 0.f) + __logf(1.0f + e), sg = (xb >= 0.f ? 1.f : e) * __builtin_amdgcn_rcpf(1.0f + e);
;                             y[h] = (fq == 0) ? -__expf(a_log[h]) * sp : sg; }
;                         float* o = (fq == 0 ? G : BETA) + (size_t)r * NH; *(f32x4*)o = (f32x4){y[0], y[1], y[2], y[3]}; *(f32x4*)(o + 4) = (f32x4){y[4], y[5], y[6], y[7]};
.LBB0_800:
	s_or_b64 exec, exec, s[10:11]
	v_lshlrev_b64 v[38:39], 5, v[38:39]
	v_lshl_add_u64 v[40:41], s[26:27], 0, v[40:41]
	v_lshl_add_u64 v[38:39], v[40:41], 0, v[38:39]
	global_store_dwordx4 v[38:39], v[22:25], off sc1
	global_store_dwordx4 v[38:39], v[26:29], off offset:16 sc1

;     __device__ __forceinline__ void operator()(const f32x4 (&acc)[2][2][4][2], const Unit& u, int wr, int wc, int fr, int fq) const {
;     ...
;                     else if (reg == 6) { const int c = c8 - O_GZ; *(u32x4*)(Zb + (size_t)r * GW + c) = w; }
.LBB0_802:
	s_andn2_b64 vcc, exec, s[18:19]
	s_cbranch_vccnz .LBB0_804
	v_lshl_add_u64 v[22:23], s[56:57], 0, v[36:37]
	v_lshl_add_u64 v[22:23], v[160:161], 1, v[22:23]
	v_add_co_u32_e32 v22, vcc, 0xffffd000, v22
	s_nop 1
	v_addc_co_u32_e32 v23, vcc, -1, v23, vcc
	global_store_dwordx4 v[22:23], v[18:21], off sc1

;     __device__ __forceinline__ void operator()(const f32x4 (&acc)[2][2][4][2], const Unit& u, int wr, int wc, int fr, int fq) const {
;     ...
;                     else if (reg < 6) { const int c = c8 - O_GQKV; *(u32x4*)(CIN + (size_t)r * CONVCH + c) = w;
;                         const int t = r & (T - 1); if (t >= T - 3) { float* o = outGconv + ((size_t)(r >> 12) * 3 + (t - (T - 3))) * CONVCH + c; *(f32x4*)o = v0; *(f32x4*)(o + 4) = v1; } }
.LBB0_805:
	s_andn2_b64 vcc, exec, s[18:19]
	s_cbranch_vccnz .LBB0_809
	v_add_u32_e32 v22, 0xfffff400, v160
	v_lshl_add_u64 v[24:25], s[54:55], 0, v[32:33]
	v_ashrrev_i32_e32 v23, 31, v22
	v_lshl_add_u64 v[24:25], v[22:23], 1, v[24:25]
	global_store_dwordx4 v[24:25], v[18:21], off sc1
	s_and_saveexec_b64 s[8:9], s[16:17]
	s_cbranch_execz .LBB0_808
	v_lshl_add_u64 v[24:25], s[62:63], 0, v[34:35]
	v_lshl_add_u64 v[22:23], v[22:23], 2, v[24:25]
	global_store_dwordx4 v[22:23], v[14:17], off sc1
	global_store_dwordx4 v[22:23], v[10:13], off offset:16 sc1

;     __device__ __forceinline__ void operator()(const f32x4 (&acc)[2][2][4][2], const Unit& u, int wr, int wc, int fr, int fq) const {
;     ...
;                     else if (reg == 1) { const int c = c8 - O_SB_K; *(u32x4*)(Kb + (size_t)r * SBW + c) = w; float* o = outK + (size_t)r * SBW + c; __builtin_nontemporal_store(v0, (f32x4*)o); __builtin_nontemporal_store(v1, (f32x4*)(o + 4)); }
.LBB0_813:
	v_lshl_add_u64 v[22:23], v[30:31], 1, s[50:51]
	v_lshl_add_u64 v[22:23], v[160:161], 1, v[22:23]
	global_store_dwordx4 v[22:23], v[18:21], off offset:-2048 sc1
	v_lshl_add_u64 v[22:23], v[30:31], 2, s[58:59]
	v_lshl_add_u64 v[22:23], v[160:161], 2, v[22:23]
	global_store_dwordx4 v[22:23], v[14:17], off offset:-4096 nt
	global_store_dwordx4 v[22:23], v[10:13], off offset:-4080 nt

; __device__ __forceinline__ unsigned cvt_pk_bf16(float lo, float hi) { unsigned r; asm volatile("v_cvt_pk_bf16_f32 %0, %1, %2" : "=v"(r) : "v"(lo), "v"(hi)); return r; }
;     __device__ __forceinline__ void operator()(const f32x4 (&acc)[2][2][4][2], const Unit& u, int wr, int wc, int fr, int fq) const {
;     ...
;                     u32x4 w; w.x = cvt_pk_bf16(v0[0], v0[1]); w.y = cvt_pk_bf16(v0[2], v0[3]); w.z = cvt_pk_bf16(v1[0], v1[1]); w.w = cvt_pk_bf16(v1[2], v1[3]);
;                     if (reg == 0) { *(u32x4*)(Qb + (size_t)r * SBW + c8) = w; }
;                     else if (reg == 1) { const int c = c8 - O_SB_K; *(u32x4*)(Kb + (size_t)r * SBW + c) = w; float* o = outK + (size_t)r * SBW + c; __builtin_nontemporal_store(v0, (f32x4*)o); __builtin_nontemporal_store(v1, (f32x4*)(o + 4)); }
;                     else if (reg == 2) { const int c = c8 - O_SB_V; *(u32x4*)(Vb + (size_t)r * SBW + c) = w; float* o = outV + (size_t)r * SBW + c; __builtin_nontemporal_store(v0, (f32x4*)o); __builtin_nontemporal_store(v1, (f32x4*)(o + 4)); }
.LBB0_815:
	s_and_b64 vcc, exec, s[18:19]
	v_lshl_add_u64 v[14:15], s[48:49], 0, v[36:37]
	s_cbranch_vccz .LBB0_817
	v_lshl_add_u64 v[10:11], v[160:161], 1, v[14:15]
	global_store_dwordx4 v[10:11], v[18:21], off sc1
.LBB0_817:
	s_and_b64 vcc, exec, s[14:15]
	s_mov_b64 s[8:9], -1
	v_cvt_pk_bf16_f32 v10, v6, v7
	v_cvt_pk_bf16_f32 v11, v8, v9
	v_cvt_pk_bf16_f32 v12, v2, v3
	v_cvt_pk_bf16_f32 v13, v4, v5
	s_cbranch_vccnz .LBB0_832
	s_mov_b64 s[12:13], -1
	s_mov_b64 s[8:9], 0
	s_cmp_lt_i32 s46, 2
	s_mov_b64 s[10:11], 0
	s_cbranch_scc1 .LBB0_834
	s_cmp_eq_u32 s46, 2
	s_mov_b64 s[10:11], -1
	s_cbranch_scc0 .LBB0_821
	v_add_u32_e32 v16, 0xfffff880, v160
	v_lshl_add_u64 v[18:19], v[30:31], 1, s[52:53]
	v_ashrrev_i32_e32 v17, 31, v16
	v_lshl_add_u64 v[18:19], v[16:17], 1, v[18:19]
	global_store_dwordx4 v[18:19], v[10:13], off sc1
	v_lshl_add_u64 v[18:19], v[30:31], 2, s[60:61]
	v_lshl_add_u64 v[16:17], v[16:17], 2, v[18:19]
	global_store_dwordx4 v[16:17], v[6:9], off nt
	global_store_dwordx4 v[16:17], v[2:5], off offset:16 nt
	s_mov_b64 s[10:11], 0

;     __device__ __forceinline__ void operator()(const f32x4 (&acc)[2][2][4][2], const Unit& u, int wr, int wc, int fr, int fq) const {
;     ...
;                     else if (reg == 6) { const int c = c8 - O_GZ; *(u32x4*)(Zb + (size_t)r * GW + c) = w; }
.LBB0_823:
	s_andn2_b64 vcc, exec, s[80:81]
	s_mov_b64 s[8:9], -1
	s_cbranch_vccnz .LBB0_827
	s_andn2_b64 vcc, exec, s[78:79]
	s_cbranch_vccnz .LBB0_826
	v_lshl_add_u64 v[16:17], s[56:57], 0, v[36:37]
	v_ashrrev_i32_e32 v127, 31, v126
	v_lshl_add_u64 v[16:17], v[126:127], 1, v[16:17]
	v_add_co_u32_e32 v16, vcc, 0xffffd000, v16
	s_nop 1
	v_addc_co_u32_e32 v17, vcc, -1, v17, vcc
	global_store_dwordx4 v[16:17], v[10:13], off sc1

;     __device__ __forceinline__ void operator()(const f32x4 (&acc)[2][2][4][2], const Unit& u, int wr, int wc, int fr, int fq) const {
;     ...
;                     else if (reg < 6) { const int c = c8 - O_GQKV; *(u32x4*)(CIN + (size_t)r * CONVCH + c) = w;
;                         const int t = r & (T - 1); if (t >= T - 3) { float* o = outGconv + ((size_t)(r >> 12) * 3 + (t - (T - 3))) * CONVCH + c; *(f32x4*)o = v0; *(f32x4*)(o + 4) = v1; } }
.LBB0_827:
	s_andn2_b64 vcc, exec, s[8:9]
	s_cbranch_vccnz .LBB0_831
	v_add_u32_e32 v16, 0xfffff480, v160
	v_lshl_add_u64 v[18:19], s[54:55], 0, v[32:33]
	v_ashrrev_i32_e32 v17, 31, v16
	v_lshl_add_u64 v[18:19], v[16:17], 1, v[18:19]
	global_store_dwordx4 v[18:19], v[10:13], off sc1
	s_and_saveexec_b64 s[8:9], s[16:17]
	s_cbranch_execz .LBB0_830
	v_lshl_add_u64 v[18:19], s[62:63], 0, v[34:35]
	v_lshl_add_u64 v[16:17], v[16:17], 2, v[18:19]
	global_store_dwordx4 v[16:17], v[6:9], off sc1
	global_store_dwordx4 v[16:17], v[2:5], off offset:16 sc1

;     __device__ __forceinline__ void operator()(const f32x4 (&acc)[2][2][4][2], const Unit& u, int wr, int wc, int fr, int fq) const {
;     ...
;                     if (reg == 0) { *(u32x4*)(Qb + (size_t)r * SBW + c8) = w; }
.LBB0_832:
	s_and_b64 vcc, exec, s[8:9]
	s_cbranch_vccz .LBB0_839
	v_lshl_add_u64 v[2:3], v[160:161], 1, v[14:15]
	global_store_dwordx4 v[2:3], v[10:13], off offset:256 sc1
	s_and_b64 vcc, exec, s[6:7]
	s_mov_b64 s[6:7], -1
	s_cbranch_vccnz .LBB0_171
	s_branch .LBB0_840

;     __device__ __forceinline__ void operator()(const f32x4 (&acc)[2][2][4][2], const Unit& u, int wr, int wc, int fr, int fq) const {
;     ...
;                     else if (reg == 1) { const int c = c8 - O_SB_K; *(u32x4*)(Kb + (size_t)r * SBW + c) = w; float* o = outK + (size_t)r * SBW + c; __builtin_nontemporal_store(v0, (f32x4*)o); __builtin_nontemporal_store(v1, (f32x4*)(o + 4)); }
.LBB0_837:
	v_add_u32_e32 v16, 0xfffffc80, v160
	v_lshl_add_u64 v[18:19], v[30:31], 1, s[50:51]
	v_ashrrev_i32_e32 v17, 31, v16
	v_lshl_add_u64 v[18:19], v[16:17], 1, v[18:19]
	global_store_dwordx4 v[18:19], v[10:13], off sc1
	v_lshl_add_u64 v[18:19], v[30:31], 2, s[58:59]
	v_lshl_add_u64 v[16:17], v[16:17], 2, v[18:19]
	global_store_dwordx4 v[16:17], v[6:9], off nt
	global_store_dwordx4 v[16:17], v[2:5], off offset:16 nt

; __device__ __forceinline__ unsigned cvt_pk_bf16(float lo, float hi) { unsigned r; asm volatile("v_cvt_pk_bf16_f32 %0, %1, %2" : "=v"(r) : "v"(lo), "v"(hi)); return r; }
;     __device__ __forceinline__ void operator()(const f32x4 (&acc)[2][2][4][2], const Unit& u, int wr, int wc, int fr, int fq) const {
; #pragma unroll
;         for (int ai = 0; ai < 2; ++ai)
; #pragma unroll
;             for (int m = 0; m < 4; ++m) { const int r = u.pm * BM + ai * HALF + wr * 64 + m * 16 + fr;
; #pragma unroll
;                 for (int bj = 0; bj < 2; ++bj) { const int c8 = u.pn * BM + bj * HALF + wc * 32 + 8 * fq; const f32x4 v0 = acc[ai][bj][m][0], v1 = acc[ai][bj][m][1];
;                     u32x4 w; w.x = cvt_pk_bf16(v0[0], v0[1]); w.y = cvt_pk_bf16(v0[2], v0[3]); w.z = cvt_pk_bf16(v1[0], v1[1]); w.w = cvt_pk_bf16(v1[2], v1[3]);
;                     *(u32x4*)(O + (size_t)r * ldc + c8) = w; } }
.LBB0_976:
	s_lshl_b32 s2, s54, 8
	v_mov_b32_e32 v151, v1
	v_mov_b32_e32 v153, v146
	s_add_i32 s2, s2, s47
	v_cvt_pk_bf16_f32 v122, v122, v123
	v_cvt_pk_bf16_f32 v123, v124, v125
	v_cvt_pk_bf16_f32 v124, v126, v127
	v_cvt_pk_bf16_f32 v125, v128, v129
	s_and_b64 vcc, exec, s[6:7]
	v_add_u32_e32 v152, s2, v151
	s_lshl_b32 s2, s57, 8
	s_or_b32 s2, s2, s48
	v_lshl_add_u32 v154, v153, 3, s2
	v_ashrrev_i32_e32 v153, 31, v152
	v_lshlrev_b64 v[126:127], 12, v[152:153]
	v_ashrrev_i32_e32 v155, 31, v154
	v_lshl_add_u64 v[126:127], s[16:17], 0, v[126:127]
	v_lshlrev_b64 v[128:129], 1, v[154:155]
	v_lshl_add_u64 v[126:127], v[126:127], 0, v[128:129]
	global_store_dwordx4 v[126:127], v[122:125], off sc1
	v_cvt_pk_bf16_f32 v118, v118, v119
	v_cvt_pk_bf16_f32 v119, v120, v121
	v_cvt_pk_bf16_f32 v120, v114, v115
	v_add_u32_e32 v114, 16, v152
	v_ashrrev_i32_e32 v115, 31, v114
	v_cvt_pk_bf16_f32 v121, v116, v117
	global_store_dwordx4 v[126:127], v[118:121], off offset:256 sc1
	v_cvt_pk_bf16_f32 v110, v110, v111
	v_cvt_pk_bf16_f32 v111, v112, v113
	v_cvt_pk_bf16_f32 v112, v106, v107
	v_lshlrev_b64 v[106:107], 12, v[114:115]
	v_lshl_add_u64 v[106:107], s[16:17], 0, v[106:107]
	v_lshl_add_u64 v[106:107], v[106:107], 0, v[128:129]
	v_cvt_pk_bf16_f32 v113, v108, v109
	global_store_dwordx4 v[106:107], v[110:113], off sc1
	v_cvt_pk_bf16_f32 v102, v102, v103
	v_cvt_pk_bf16_f32 v103, v104, v105
	v_cvt_pk_bf16_f32 v104, v98, v99
	v_add_u32_e32 v98, 32, v152
	v_ashrrev_i32_e32 v99, 31, v98
	v_cvt_pk_bf16_f32 v105, v100, v101
	global_store_dwordx4 v[106:107], v[102:105], off offset:256 sc1
	v_cvt_pk_bf16_f32 v94, v94, v95
	v_cvt_pk_bf16_f32 v95, v96, v97
	v_cvt_pk_bf16_f32 v96, v90, v91
	v_lshlrev_b64 v[90:91], 12, v[98:99]
	v_lshl_add_u64 v[90:91], s[16:17], 0, v[90:91]
	v_lshl_add_u64 v[90:91], v[90:91], 0, v[128:129]
	v_cvt_pk_bf16_f32 v97, v92, v93
	global_store_dwordx4 v[90:91], v[94:97], off sc1
	v_cvt_pk_bf16_f32 v86, v86, v87
	v_cvt_pk_bf16_f32 v87, v88, v89
	v_cvt_pk_bf16_f32 v88, v82, v83
	v_add_u32_e32 v82, 48, v152
	v_ashrrev_i32_e32 v83, 31, v82
	v_cvt_pk_bf16_f32 v89, v84, v85
	global_store_dwordx4 v[90:91], v[86:89], off offset:256 sc1
	v_cvt_pk_bf16_f32 v78, v78, v79
	v_cvt_pk_bf16_f32 v79, v80, v81
	v_cvt_pk_bf16_f32 v80, v74, v75
	v_lshlrev_b64 v[74:75], 12, v[82:83]
	v_lshl_add_u64 v[74:75], s[16:17], 0, v[74:75]
	v_lshl_add_u64 v[74:75], v[74:75], 0, v[128:129]
	v_cvt_pk_bf16_f32 v81, v76, v77
	global_store_dwordx4 v[74:75], v[78:81], off sc1
	v_cvt_pk_bf16_f32 v70, v70, v71
	v_cvt_pk_bf16_f32 v71, v72, v73
	v_cvt_pk_bf16_f32 v72, v66, v67
	v_add_u32_e32 v66, 0x80, v152
	v_ashrrev_i32_e32 v67, 31, v66
	v_cvt_pk_bf16_f32 v73, v68, v69
	global_store_dwordx4 v[74:75], v[70:73], off offset:256 sc1
	v_cvt_pk_bf16_f32 v62, v62, v63
	v_cvt_pk_bf16_f32 v63, v64, v65
	v_cvt_pk_bf16_f32 v64, v58, v59
	v_lshlrev_b64 v[58:59], 12, v[66:67]
	v_lshl_add_u64 v[58:59], s[16:17], 0, v[58:59]
	v_lshl_add_u64 v[58:59], v[58:59], 0, v[128:129]
	v_cvt_pk_bf16_f32 v65, v60, v61
	global_store_dwordx4 v[58:59], v[62:65], off sc1
	v_cvt_pk_bf16_f32 v54, v54, v55
	v_cvt_pk_bf16_f32 v55, v56, v57
	v_cvt_pk_bf16_f32 v56, v50, v51
	v_add_u32_e32 v50, 0x90, v152
	v_ashrrev_i32_e32 v51, 31, v50
	v_cvt_pk_bf16_f32 v57, v52, v53
	global_store_dwordx4 v[58:59], v[54:57], off offset:256 sc1
	v_cvt_pk_bf16_f32 v46, v46, v47
	v_cvt_pk_bf16_f32 v47, v48, v49
	v_cvt_pk_bf16_f32 v48, v42, v43
	v_lshlrev_b64 v[42:43], 12, v[50:51]
	v_lshl_add_u64 v[42:43], s[16:17], 0, v[42:43]
	v_lshl_add_u64 v[42:43], v[42:43], 0, v[128:129]
	v_cvt_pk_bf16_f32 v49, v44, v45
	global_store_dwordx4 v[42:43], v[46:49], off sc1
	v_cvt_pk_bf16_f32 v38, v38, v39
	v_cvt_pk_bf16_f32 v39, v40, v41
	v_cvt_pk_bf16_f32 v40, v34, v35
	v_add_u32_e32 v34, 0xa0, v152
	v_ashrrev_i32_e32 v35, 31, v34
	v_cvt_pk_bf16_f32 v41, v36, v37
	global_store_dwordx4 v[42:43], v[38:41], off offset:256 sc1
	v_cvt_pk_bf16_f32 v30, v30, v31
	v_cvt_pk_bf16_f32 v31, v32, v33
	v_cvt_pk_bf16_f32 v32, v26, v27
	v_lshlrev_b64 v[26:27], 12, v[34:35]
	v_lshl_add_u64 v[26:27], s[16:17], 0, v[26:27]
	v_lshl_add_u64 v[26:27], v[26:27], 0, v[128:129]
	v_cvt_pk_bf16_f32 v33, v28, v29
	global_store_dwordx4 v[26:27], v[30:33], off sc1
	v_cvt_pk_bf16_f32 v22, v22, v23
	v_cvt_pk_bf16_f32 v23, v24, v25
	v_cvt_pk_bf16_f32 v24, v18, v19
	v_add_u32_e32 v18, 0xb0, v152
	v_ashrrev_i32_e32 v19, 31, v18
	v_cvt_pk_bf16_f32 v25, v20, v21
	global_store_dwordx4 v[26:27], v[22:25], off offset:256 sc1
	v_cvt_pk_bf16_f32 v14, v14, v15
	v_cvt_pk_bf16_f32 v15, v16, v17
	v_cvt_pk_bf16_f32 v16, v10, v11
	v_lshlrev_b64 v[10:11], 12, v[18:19]
	v_lshl_add_u64 v[10:11], s[16:17], 0, v[10:11]
	v_lshl_add_u64 v[10:11], v[10:11], 0, v[128:129]
	s_mov_b64 s[6:7], -1
	v_cvt_pk_bf16_f32 v17, v12, v13
	global_store_dwordx4 v[10:11], v[14:17], off sc1
	v_cvt_pk_bf16_f32 v6, v6, v7
	v_cvt_pk_bf16_f32 v7, v8, v9
	v_cvt_pk_bf16_f32 v8, v2, v3
	v_cvt_pk_bf16_f32 v9, v4, v5
	global_store_dwordx4 v[10:11], v[6:9], off offset:256 sc1
	s_cbranch_vccnz .LBB0_960
	s_andn2_b64 vcc, exec, s[14:15]
	s_cbranch_vccnz .LBB0_959
	s_barrier
	s_branch .LBB0_959

; #define LAS __attribute__((address_space(3)))
; #define LDS_WAIT() asm volatile("s_waitcnt lgkmcnt(0)" ::: "memory")
; __device__ __forceinline__ unsigned pk2(float lo, float hi) { return f2bf(lo) | (f2bf(hi) << 16); }
; __device__ __forceinline__ void ti_store(const TItem& t, const f32x4 (&v)[16], const float (&sc)[16], LAS float* scr, int lane) {
;     const int n4 = (lane & 15) * 4, kq = lane >> 4;
; #pragma unroll
;     for (int i = 0; i < 16; ++i) { const int kk = 4 * i + kq; const f32x4 x = v[i] * sc[i]; LAS float* d = scr + kk * 65 + n4; d[0] = x.x; d[1] = x.y; d[2] = x.z; d[3] = x.w; }
;     LDS_WAIT(); asm volatile("" ::: "memory");
;     const int c = lane & 7;
; #pragma unroll
;     for (int j = 0; j < 8; ++j) { const int n = (lane >> 3) + 8 * j; const LAS float* s = scr + (8 * c) * 65 + n;
;         v4u o; o.x = pk2(s[0 * 65], s[1 * 65]); o.y = pk2(s[2 * 65], s[3 * 65]); o.z = pk2(s[4 * 65], s[5 * 65]); o.w = pk2(s[6 * 65], s[7 * 65]);
.LBB0_1063:
	s_waitcnt vmcnt(0)
	v_pk_mul_f32 v[194:195], v[2:3], v[34:35] op_sel_hi:[0,1]
	v_pk_mul_f32 v[166:167], v[2:3], v[36:37] op_sel_hi:[0,1]
	ds_write2_b32 v192, v194, v195 offset1:1
	ds_write2_b32 v192, v166, v167 offset0:2 offset1:3
	v_pk_mul_f32 v[194:195], v[2:3], v[38:39] op_sel:[1,0]
	v_add_u32_e32 v165, 0x410, v192
	v_pk_mul_f32 v[166:167], v[2:3], v[40:41] op_sel:[1,0]
	ds_write2_b32 v165, v194, v195 offset1:1
	v_add_u32_e32 v165, 0x418, v192
	ds_write2_b32 v165, v166, v167 offset1:1
	v_pk_mul_f32 v[194:195], v[4:5], v[42:43] op_sel_hi:[0,1]
	v_add_u32_e32 v165, 0x820, v192
	v_pk_mul_f32 v[166:167], v[4:5], v[44:45] op_sel_hi:[0,1]
	ds_write2_b32 v165, v194, v195 offset1:1
	v_add_u32_e32 v165, 0x828, v192
	ds_write2_b32 v165, v166, v167 offset1:1
	v_mov_b32_e32 v166, v5
	v_pk_mul_f32 v[194:195], v[166:167], v[48:49] op_sel_hi:[0,1]
	v_pk_mul_f32 v[166:167], v[166:167], v[46:47] op_sel_hi:[0,1]
	v_add_u32_e32 v165, 0xc30, v192
	ds_write2_b32 v165, v166, v167 offset1:1
	v_add_u32_e32 v165, 0xc38, v192
	ds_write2_b32 v165, v194, v195 offset1:1
	v_pk_mul_f32 v[194:195], v[6:7], v[50:51] op_sel_hi:[0,1]
	v_add_u32_e32 v165, 0x1040, v192
	v_pk_mul_f32 v[166:167], v[6:7], v[52:53] op_sel_hi:[0,1]
	ds_write2_b32 v165, v194, v195 offset1:1
	v_add_u32_e32 v165, 0x1048, v192
	ds_write2_b32 v165, v166, v167 offset1:1
	v_mov_b32_e32 v166, v7
	v_pk_mul_f32 v[194:195], v[166:167], v[56:57] op_sel_hi:[0,1]
	v_pk_mul_f32 v[166:167], v[166:167], v[54:55] op_sel_hi:[0,1]
	v_add_u32_e32 v165, 0x1450, v192
	ds_write2_b32 v165, v166, v167 offset1:1
	v_add_u32_e32 v165, 0x1458, v192
	ds_write2_b32 v165, v194, v195 offset1:1
	v_pk_mul_f32 v[194:195], v[8:9], v[58:59] op_sel_hi:[0,1]
	v_add_u32_e32 v165, 0x1860, v192
	v_pk_mul_f32 v[166:167], v[8:9], v[60:61] op_sel_hi:[0,1]
	ds_write2_b32 v165, v194, v195 offset1:1
	v_add_u32_e32 v165, 0x1868, v192
	ds_write2_b32 v165, v166, v167 offset1:1
	v_mov_b32_e32 v166, v9
	v_pk_mul_f32 v[194:195], v[166:167], v[64:65] op_sel_hi:[0,1]
	v_pk_mul_f32 v[166:167], v[166:167], v[62:63] op_sel_hi:[0,1]
	v_add_u32_e32 v165, 0x1c70, v192
	ds_write2_b32 v165, v166, v167 offset1:1
	v_add_u32_e32 v165, 0x1c78, v192
	ds_write2_b32 v165, v194, v195 offset1:1
	v_pk_mul_f32 v[194:195], v[10:11], v[66:67] op_sel_hi:[0,1]
	v_add_u32_e32 v165, 0x2080, v192
	v_pk_mul_f32 v[166:167], v[10:11], v[68:69] op_sel_hi:[0,1]
	ds_write2_b32 v165, v194, v195 offset1:1
	v_add_u32_e32 v165, 0x2088, v192
	ds_write2_b32 v165, v166, v167 offset1:1
	v_mov_b32_e32 v166, v11
	v_pk_mul_f32 v[194:195], v[166:167], v[72:73] op_sel_hi:[0,1]
	v_pk_mul_f32 v[166:167], v[166:167], v[70:71] op_sel_hi:[0,1]
	v_add_u32_e32 v165, 0x2490, v192
	ds_write2_b32 v165, v166, v167 offset1:1
	v_add_u32_e32 v165, 0x2498, v192
	ds_write2_b32 v165, v194, v195 offset1:1
	v_pk_mul_f32 v[194:195], v[12:13], v[74:75] op_sel_hi:[0,1]
	v_add_u32_e32 v165, 0x28a0, v192
	v_pk_mul_f32 v[166:167], v[12:13], v[76:77] op_sel_hi:[0,1]
	ds_write2_b32 v165, v194, v195 offset1:1
	v_add_u32_e32 v165, 0x28a8, v192
	ds_write2_b32 v165, v166, v167 offset1:1
	v_mov_b32_e32 v166, v13
	v_pk_mul_f32 v[194:195], v[166:167], v[80:81] op_sel_hi:[0,1]
	v_pk_mul_f32 v[166:167], v[166:167], v[78:79] op_sel_hi:[0,1]
	v_add_u32_e32 v165, 0x2cb0, v192
	ds_write2_b32 v165, v166, v167 offset1:1
	v_add_u32_e32 v165, 0x2cb8, v192
	ds_write2_b32 v165, v194, v195 offset1:1
	v_pk_mul_f32 v[194:195], v[14:15], v[82:83] op_sel_hi:[0,1]
	v_add_u32_e32 v165, 0x30c0, v192
	v_pk_mul_f32 v[166:167], v[14:15], v[84:85] op_sel_hi:[0,1]
	ds_write2_b32 v165, v194, v195 offset1:1
	v_add_u32_e32 v165, 0x30c8, v192
	ds_write2_b32 v165, v166, v167 offset1:1
	v_mov_b32_e32 v166, v15
	v_pk_mul_f32 v[194:195], v[88:89], v[166:167] op_sel_hi:[1,0]
	v_pk_mul_f32 v[166:167], v[86:87], v[166:167] op_sel_hi:[1,0]
	v_add_u32_e32 v165, 0x34d0, v192
	ds_write2_b32 v165, v166, v167 offset1:1
	v_add_u32_e32 v165, 0x34d8, v192
	ds_write2_b32 v165, v194, v195 offset1:1
	v_pk_mul_f32 v[194:195], v[90:91], v[16:17] op_sel_hi:[1,0]
	v_add_u32_e32 v165, 0x38e0, v192
	v_pk_mul_f32 v[166:167], v[92:93], v[16:17] op_sel_hi:[1,0]
	ds_write2_b32 v165, v194, v195 offset1:1
	v_add_u32_e32 v165, 0x38e8, v192
	ds_write2_b32 v165, v166, v167 offset1:1
	v_mov_b32_e32 v166, v17
	v_pk_mul_f32 v[194:195], v[96:97], v[166:167] op_sel_hi:[1,0]
	v_pk_mul_f32 v[166:167], v[94:95], v[166:167] op_sel_hi:[1,0]
	v_add_u32_e32 v165, 0x3cf0, v192
	ds_write2_b32 v165, v166, v167 offset1:1
	v_add_u32_e32 v165, 0x3cf8, v192
	ds_write2_b32 v165, v194, v195 offset1:1
	s_waitcnt lgkmcnt(0)
	ds_read2_b32 v[166:167], v184 offset1:8
	ds_read2_b32 v[200:201], v184 offset0:65 offset1:73
	ds_read2_b32 v[202:203], v184 offset0:130 offset1:138
	ds_read2_b32 v[204:205], v184 offset0:195 offset1:203
	v_add_u32_e32 v193, 0x400, v184
	s_waitcnt lgkmcnt(3)
	v_bfe_u32 v165, v166, 16, 1
	v_add3_u32 v165, v166, v165, s23
	s_waitcnt lgkmcnt(2)
	v_bfe_u32 v166, v200, 16, 1
	ds_read2_b32 v[206:207], v193 offset0:4 offset1:12
	v_lshrrev_b32_e32 v165, 16, v165
	v_add3_u32 v166, v200, v166, s23
	ds_read2_b32 v[208:209], v193 offset0:69 offset1:77
	v_and_or_b32 v194, v166, s28, v165
	s_waitcnt lgkmcnt(3)
	v_bfe_u32 v165, v202, 16, 1
	v_add3_u32 v165, v202, v165, s23
	s_waitcnt lgkmcnt(2)
	v_bfe_u32 v166, v204, 16, 1
	ds_read2_b32 v[210:211], v193 offset0:134 offset1:142
	v_lshrrev_b32_e32 v165, 16, v165
	v_add3_u32 v166, v204, v166, s23
	ds_read2_b32 v[212:213], v193 offset0:199 offset1:207
	v_and_or_b32 v195, v166, s28, v165
	s_waitcnt lgkmcnt(3)
	v_bfe_u32 v165, v206, 16, 1
	v_add3_u32 v165, v206, v165, s23
	s_waitcnt lgkmcnt(2)
; #define LAS __attribute__((address_space(3)))
; __device__ __forceinline__ unsigned pk2(float lo, float hi) { return f2bf(lo) | (f2bf(hi) << 16); }
; __device__ __forceinline__ void ti_store(const TItem& t, const f32x4 (&v)[16], const float (&sc)[16], LAS float* scr, int lane) {
;     ...
;     const int c = lane & 7;
; #pragma unroll
;     for (int j = 0; j < 8; ++j) { const int n = (lane >> 3) + 8 * j; const LAS float* s = scr + (8 * c) * 65 + n;
;         v4u o; o.x = pk2(s[0 * 65], s[1 * 65]); o.y = pk2(s[2 * 65], s[3 * 65]); o.z = pk2(s[4 * 65], s[5 * 65]); o.w = pk2(s[6 * 65], s[7 * 65]);
;         *(v4u*)(t.WT + (size_t)(t.drow + n) * t.K + t.k0 + 8 * c) = o; }
	v_bfe_u32 v166, v208, 16, 1
	v_lshrrev_b32_e32 v165, 16, v165
	v_add3_u32 v166, v208, v166, s23
	v_and_or_b32 v196, v166, s28, v165
	s_waitcnt lgkmcnt(1)
	v_bfe_u32 v165, v210, 16, 1
	v_add_u32_e32 v214, s5, v183
	v_add3_u32 v165, v210, v165, s23
	s_waitcnt lgkmcnt(0)
	v_bfe_u32 v166, v212, 16, 1
	v_ashrrev_i32_e32 v215, 31, v214
	v_lshrrev_b32_e32 v165, 16, v165
	v_add3_u32 v166, v212, v166, s23
	v_lshlrev_b64 v[214:215], 12, v[214:215]
	s_ashr_i32 s9, s8, 31
	v_and_or_b32 v197, v166, s28, v165
	v_lshl_add_u64 v[214:215], s[12:13], 0, v[214:215]
	s_lshl_b64 s[6:7], s[8:9], 1
	v_bfe_u32 v166, v167, 16, 1
	v_lshl_add_u64 v[214:215], v[214:215], 0, s[6:7]
	v_mov_b32_e32 v165, v163
	v_add3_u32 v166, v167, v166, s23
	v_bfe_u32 v167, v201, 16, 1
	v_lshl_add_u64 v[214:215], v[214:215], 0, v[164:165]
	v_lshrrev_b32_e32 v166, 16, v166
	v_add3_u32 v167, v201, v167, s23
	global_store_dwordx4 v[214:215], v[194:197], off sc1
	ds_read2_b32 v[200:201], v184 offset0:16 offset1:24
	v_add_u32_e32 v214, s5, v186
	v_and_or_b32 v194, v167, s28, v166
	v_bfe_u32 v166, v203, 16, 1
	v_add3_u32 v166, v203, v166, s23
	v_bfe_u32 v167, v205, 16, 1
	v_lshrrev_b32_e32 v166, 16, v166
	v_add3_u32 v167, v205, v167, s23
	v_and_or_b32 v195, v167, s28, v166
	v_bfe_u32 v166, v207, 16, 1
	v_add3_u32 v166, v207, v166, s23
	v_bfe_u32 v167, v209, 16, 1
	v_lshrrev_b32_e32 v166, 16, v166
	v_add3_u32 v167, v209, v167, s23
	v_and_or_b32 v196, v167, s28, v166
	v_bfe_u32 v166, v211, 16, 1
	v_add3_u32 v166, v211, v166, s23
	v_bfe_u32 v167, v213, 16, 1
	v_lshrrev_b32_e32 v166, 16, v166
	v_add3_u32 v167, v213, v167, s23
	v_and_or_b32 v197, v167, s28, v166
	v_add_u32_e32 v166, s5, v185
	v_ashrrev_i32_e32 v167, 31, v166
	v_lshlrev_b64 v[166:167], 12, v[166:167]
	v_lshl_add_u64 v[166:167], s[12:13], 0, v[166:167]
	v_lshl_add_u64 v[166:167], v[166:167], 0, s[6:7]
	v_lshl_add_u64 v[166:167], v[166:167], 0, v[164:165]
	global_store_dwordx4 v[166:167], v[194:197], off sc1
	ds_read2_b32 v[166:167], v184 offset0:81 offset1:89
	ds_read2_b32 v[202:203], v184 offset0:146 offset1:154
	ds_read2_b32 v[204:205], v184 offset0:211 offset1:219
	s_waitcnt lgkmcnt(3)
	v_bfe_u32 v194, v200, 16, 1
	v_add3_u32 v194, v200, v194, s23
	s_waitcnt lgkmcnt(2)
	v_bfe_u32 v195, v166, 16, 1
	ds_read2_b32 v[206:207], v193 offset0:20 offset1:28
	v_lshrrev_b32_e32 v194, 16, v194
	v_add3_u32 v166, v166, v195, s23
	ds_read2_b32 v[208:209], v193 offset0:85 offset1:93
	v_and_or_b32 v194, v166, s28, v194
	s_waitcnt lgkmcnt(3)
	v_bfe_u32 v166, v202, 16, 1
	v_add3_u32 v166, v202, v166, s23
	s_waitcnt lgkmcnt(2)
	v_bfe_u32 v195, v204, 16, 1
	ds_read2_b32 v[210:211], v193 offset0:150 offset1:158
	v_lshrrev_b32_e32 v166, 16, v166
	v_add3_u32 v195, v204, v195, s23
	ds_read2_b32 v[212:213], v193 offset0:215 offset1:223
	v_and_or_b32 v195, v195, s28, v166
	s_waitcnt lgkmcnt(3)
	v_bfe_u32 v166, v206, 16, 1
	v_add3_u32 v166, v206, v166, s23
	s_waitcnt lgkmcnt(2)
	v_bfe_u32 v196, v208, 16, 1
	v_lshrrev_b32_e32 v166, 16, v166
	v_add3_u32 v196, v208, v196, s23
	v_ashrrev_i32_e32 v215, 31, v214
	v_and_or_b32 v196, v196, s28, v166
	s_waitcnt lgkmcnt(1)
	v_bfe_u32 v166, v210, 16, 1
	v_lshlrev_b64 v[214:215], 12, v[214:215]
	v_add3_u32 v166, v210, v166, s23
	s_waitcnt lgkmcnt(0)
	v_bfe_u32 v197, v212, 16, 1
	v_lshl_add_u64 v[214:215], s[12:13], 0, v[214:215]
	v_lshrrev_b32_e32 v166, 16, v166
	v_add3_u32 v197, v212, v197, s23
	v_lshl_add_u64 v[214:215], v[214:215], 0, s[6:7]
	v_and_or_b32 v197, v197, s28, v166
	v_lshl_add_u64 v[214:215], v[214:215], 0, v[164:165]
	v_bfe_u32 v166, v201, 16, 1
	global_store_dwordx4 v[214:215], v[194:197], off sc1
	v_add3_u32 v166, v201, v166, s23
	v_lshrrev_b32_e32 v166, 16, v166
	v_bfe_u32 v194, v167, 16, 1
	v_add3_u32 v167, v167, v194, s23
	v_and_or_b32 v194, v167, s28, v166
	v_bfe_u32 v166, v203, 16, 1
	v_add3_u32 v166, v203, v166, s23
	v_bfe_u32 v167, v205, 16, 1
	v_lshrrev_b32_e32 v166, 16, v166
	v_add3_u32 v167, v205, v167, s23
	v_and_or_b32 v195, v167, s28, v166
	v_bfe_u32 v166, v207, 16, 1
	v_add3_u32 v166, v207, v166, s23
	v_bfe_u32 v167, v209, 16, 1
	v_lshrrev_b32_e32 v166, 16, v166
	v_add3_u32 v167, v209, v167, s23
	v_and_or_b32 v196, v167, s28, v166
	v_bfe_u32 v166, v211, 16, 1
	v_add3_u32 v166, v211, v166, s23
	v_bfe_u32 v167, v213, 16, 1
	v_lshrrev_b32_e32 v166, 16, v166
	v_add3_u32 v167, v213, v167, s23
	v_and_or_b32 v197, v167, s28, v166
	v_add_u32_e32 v166, s5, v187
	v_ashrrev_i32_e32 v167, 31, v166
	v_lshlrev_b64 v[166:167], 12, v[166:167]
	v_lshl_add_u64 v[166:167], s[12:13], 0, v[166:167]
	v_lshl_add_u64 v[166:167], v[166:167], 0, s[6:7]
	ds_read2_b32 v[200:201], v184 offset0:32 offset1:40
	v_lshl_add_u64 v[166:167], v[166:167], 0, v[164:165]
	global_store_dwordx4 v[166:167], v[194:197], off sc1
	ds_read2_b32 v[166:167], v184 offset0:97 offset1:105
	ds_read2_b32 v[202:203], v184 offset0:162 offset1:170
	ds_read2_b32 v[204:205], v184 offset0:227 offset1:235
	s_waitcnt lgkmcnt(3)
	v_bfe_u32 v194, v200, 16, 1
	v_add3_u32 v194, v200, v194, s23
	s_waitcnt lgkmcnt(2)
	v_bfe_u32 v195, v166, 16, 1
	ds_read2_b32 v[206:207], v193 offset0:36 offset1:44
	v_lshrrev_b32_e32 v194, 16, v194
	v_add3_u32 v166, v166, v195, s23
	ds_read2_b32 v[208:209], v193 offset0:101 offset1:109
	v_and_or_b32 v194, v166, s28, v194
	s_waitcnt lgkmcnt(3)
	v_bfe_u32 v166, v202, 16, 1
	v_add3_u32 v166, v202, v166, s23
	s_waitcnt lgkmcnt(2)
	v_bfe_u32 v195, v204, 16, 1
	ds_read2_b32 v[210:211], v193 offset0:166 offset1:174
	v_lshrrev_b32_e32 v166, 16, v166
	v_add3_u32 v195, v204, v195, s23
	ds_read2_b32 v[212:213], v193 offset0:231 offset1:239
	v_and_or_b32 v195, v195, s28, v166
	s_waitcnt lgkmcnt(3)
; #define LAS __attribute__((address_space(3)))
; #define LDS_WAIT() asm volatile("s_waitcnt lgkmcnt(0)" ::: "memory")
; __device__ __forceinline__ unsigned pk2(float lo, float hi) { return f2bf(lo) | (f2bf(hi) << 16); }
; __device__ __forceinline__ void ti_store(const TItem& t, const f32x4 (&v)[16], const float (&sc)[16], LAS float* scr, int lane) {
;     ...
;     for (int j = 0; j < 8; ++j) { const int n = (lane >> 3) + 8 * j; const LAS float* s = scr + (8 * c) * 65 + n;
;         v4u o; o.x = pk2(s[0 * 65], s[1 * 65]); o.y = pk2(s[2 * 65], s[3 * 65]); o.z = pk2(s[4 * 65], s[5 * 65]); o.w = pk2(s[6 * 65], s[7 * 65]);
;         *(v4u*)(t.WT + (size_t)(t.drow + n) * t.K + t.k0 + 8 * c) = o; }
;     LDS_WAIT(); asm volatile("" ::: "memory");
; __device__ __forceinline__ void convert_set(Frame& F, int set, int wv, int nw) {
;     ...
;         cur = nxt; it = itn;
; #pragma unroll
;         for (int i = 0; i < 16; ++i) { vc[i] = vn[i]; sc[i] = sn[i]; }
	v_bfe_u32 v166, v206, 16, 1
	v_add3_u32 v166, v206, v166, s23
	s_waitcnt lgkmcnt(2)
	v_bfe_u32 v196, v208, 16, 1
	v_add_u32_e32 v214, s5, v188
	v_lshrrev_b32_e32 v166, 16, v166
	v_add3_u32 v196, v208, v196, s23
	v_ashrrev_i32_e32 v215, 31, v214
	v_and_or_b32 v196, v196, s28, v166
	s_waitcnt lgkmcnt(1)
	v_bfe_u32 v166, v210, 16, 1
	v_lshlrev_b64 v[214:215], 12, v[214:215]
	v_add3_u32 v166, v210, v166, s23
	s_waitcnt lgkmcnt(0)
	v_bfe_u32 v197, v212, 16, 1
	v_lshl_add_u64 v[214:215], s[12:13], 0, v[214:215]
	v_lshrrev_b32_e32 v166, 16, v166
	v_add3_u32 v197, v212, v197, s23
	v_lshl_add_u64 v[214:215], v[214:215], 0, s[6:7]
	v_and_or_b32 v197, v197, s28, v166
	v_lshl_add_u64 v[214:215], v[214:215], 0, v[164:165]
	v_bfe_u32 v166, v201, 16, 1
	global_store_dwordx4 v[214:215], v[194:197], off sc1
	v_add3_u32 v166, v201, v166, s23
	v_lshrrev_b32_e32 v166, 16, v166
	v_bfe_u32 v194, v167, 16, 1
	v_add3_u32 v167, v167, v194, s23
	v_and_or_b32 v194, v167, s28, v166
	v_bfe_u32 v166, v203, 16, 1
	v_add3_u32 v166, v203, v166, s23
	v_bfe_u32 v167, v205, 16, 1
	v_lshrrev_b32_e32 v166, 16, v166
	v_add3_u32 v167, v205, v167, s23
	v_and_or_b32 v195, v167, s28, v166
	v_bfe_u32 v166, v207, 16, 1
	v_add3_u32 v166, v207, v166, s23
	v_bfe_u32 v167, v209, 16, 1
	v_lshrrev_b32_e32 v166, 16, v166
	v_add3_u32 v167, v209, v167, s23
	v_and_or_b32 v196, v167, s28, v166
	v_bfe_u32 v166, v211, 16, 1
	v_add3_u32 v166, v211, v166, s23
	v_bfe_u32 v167, v213, 16, 1
	v_lshrrev_b32_e32 v166, 16, v166
	v_add3_u32 v167, v213, v167, s23
	v_and_or_b32 v197, v167, s28, v166
	v_add_u32_e32 v166, s5, v189
	v_ashrrev_i32_e32 v167, 31, v166
	v_lshlrev_b64 v[166:167], 12, v[166:167]
	v_lshl_add_u64 v[166:167], s[12:13], 0, v[166:167]
	v_lshl_add_u64 v[166:167], v[166:167], 0, s[6:7]
	ds_read2_b32 v[200:201], v184 offset0:48 offset1:56
	v_lshl_add_u64 v[166:167], v[166:167], 0, v[164:165]
	global_store_dwordx4 v[166:167], v[194:197], off sc1
	ds_read2_b32 v[166:167], v184 offset0:113 offset1:121
	ds_read2_b32 v[202:203], v184 offset0:178 offset1:186
	ds_read2_b32 v[204:205], v184 offset0:243 offset1:251
	s_waitcnt lgkmcnt(3)
	v_bfe_u32 v194, v200, 16, 1
	v_add3_u32 v194, v200, v194, s23
	s_waitcnt lgkmcnt(2)
	v_bfe_u32 v195, v166, 16, 1
	ds_read2_b32 v[206:207], v193 offset0:52 offset1:60
	v_lshrrev_b32_e32 v194, 16, v194
	v_add3_u32 v166, v166, v195, s23
	ds_read2_b32 v[208:209], v193 offset0:117 offset1:125
	v_and_or_b32 v194, v166, s28, v194
	s_waitcnt lgkmcnt(3)
	v_bfe_u32 v166, v202, 16, 1
	v_add3_u32 v166, v202, v166, s23
	s_waitcnt lgkmcnt(2)
	v_bfe_u32 v195, v204, 16, 1
	ds_read2_b32 v[210:211], v193 offset0:182 offset1:190
	v_lshrrev_b32_e32 v166, 16, v166
	v_add3_u32 v195, v204, v195, s23
	ds_read2_b32 v[212:213], v193 offset0:247 offset1:255
	v_and_or_b32 v195, v195, s28, v166
	s_waitcnt lgkmcnt(3)
	v_bfe_u32 v166, v206, 16, 1
	v_add3_u32 v166, v206, v166, s23
	s_waitcnt lgkmcnt(2)
	v_bfe_u32 v196, v208, 16, 1
	v_lshrrev_b32_e32 v166, 16, v166
	v_add3_u32 v196, v208, v196, s23
	v_and_or_b32 v196, v196, s28, v166
	s_waitcnt lgkmcnt(1)
	v_bfe_u32 v166, v210, 16, 1
	v_add_u32_e32 v214, s5, v190
	v_add3_u32 v166, v210, v166, s23
	s_waitcnt lgkmcnt(0)
	v_bfe_u32 v193, v212, 16, 1
	v_ashrrev_i32_e32 v215, 31, v214
	v_lshrrev_b32_e32 v166, 16, v166
	v_add3_u32 v193, v212, v193, s23
	v_lshlrev_b64 v[214:215], 12, v[214:215]
	v_and_or_b32 v197, v193, s28, v166
	v_lshl_add_u64 v[214:215], s[12:13], 0, v[214:215]
	v_bfe_u32 v166, v201, 16, 1
	v_lshl_add_u64 v[214:215], v[214:215], 0, s[6:7]
	v_add3_u32 v166, v201, v166, s23
	v_bfe_u32 v193, v167, 16, 1
	v_lshl_add_u64 v[214:215], v[214:215], 0, v[164:165]
	v_lshrrev_b32_e32 v166, 16, v166
	v_add3_u32 v167, v167, v193, s23
	global_store_dwordx4 v[214:215], v[194:197], off sc1
	s_andn2_b64 vcc, exec, s[16:17]
	s_nop 0
	v_and_or_b32 v194, v167, s28, v166
	v_bfe_u32 v166, v203, 16, 1
	v_add3_u32 v166, v203, v166, s23
	v_bfe_u32 v167, v205, 16, 1
	v_lshrrev_b32_e32 v166, 16, v166
	v_add3_u32 v167, v205, v167, s23
	v_and_or_b32 v195, v167, s28, v166
	v_bfe_u32 v166, v207, 16, 1
	v_add3_u32 v166, v207, v166, s23
	v_bfe_u32 v167, v209, 16, 1
	v_lshrrev_b32_e32 v166, 16, v166
	v_add3_u32 v167, v209, v167, s23
	v_and_or_b32 v196, v167, s28, v166
	v_bfe_u32 v166, v211, 16, 1
	v_add3_u32 v166, v211, v166, s23
	v_bfe_u32 v167, v213, 16, 1
	v_lshrrev_b32_e32 v166, 16, v166
	v_add3_u32 v167, v213, v167, s23
	v_and_or_b32 v197, v167, s28, v166
	v_add_u32_e32 v166, s5, v191
	v_ashrrev_i32_e32 v167, 31, v166
	v_lshlrev_b64 v[166:167], 12, v[166:167]
	v_lshl_add_u64 v[166:167], s[12:13], 0, v[166:167]
	v_lshl_add_u64 v[166:167], v[166:167], 0, s[6:7]
	v_lshl_add_u64 v[166:167], v[166:167], 0, v[164:165]
	global_store_dwordx4 v[166:167], v[194:197], off sc1
	s_waitcnt lgkmcnt(0)
	s_cbranch_vccnz .LBB0_1024
	v_mov_b64_e32 v[2:3], v[18:19]
	v_mov_b64_e32 v[94:95], v[158:159]
	v_mov_b64_e32 v[90:91], v[154:155]
	v_mov_b64_e32 v[86:87], v[150:151]
	v_mov_b64_e32 v[82:83], v[146:147]
	v_mov_b64_e32 v[78:79], v[142:143]
	v_mov_b64_e32 v[74:75], v[138:139]
	v_mov_b64_e32 v[70:71], v[134:135]
	v_mov_b64_e32 v[66:67], v[130:131]
	v_mov_b64_e32 v[62:63], v[126:127]
	v_mov_b64_e32 v[58:59], v[122:123]
	v_mov_b64_e32 v[54:55], v[118:119]
	v_mov_b64_e32 v[50:51], v[114:115]
	v_mov_b64_e32 v[46:47], v[110:111]
	v_mov_b64_e32 v[42:43], v[106:107]
	v_mov_b64_e32 v[38:39], v[102:103]
	v_mov_b64_e32 v[34:35], v[98:99]
	v_mov_b64_e32 v[4:5], v[20:21]
	v_mov_b64_e32 v[6:7], v[22:23]
	v_mov_b64_e32 v[8:9], v[24:25]
	v_mov_b64_e32 v[10:11], v[26:27]
	v_mov_b64_e32 v[12:13], v[28:29]
	v_mov_b64_e32 v[14:15], v[30:31]
	v_mov_b64_e32 v[16:17], v[32:33]
	v_mov_b64_e32 v[96:97], v[160:161]
	v_mov_b64_e32 v[92:93], v[156:157]
	v_mov_b64_e32 v[88:89], v[152:153]
	v_mov_b64_e32 v[84:85], v[148:149]
	v_mov_b64_e32 v[80:81], v[144:145]
	v_mov_b64_e32 v[76:77], v[140:141]
	v_mov_b64_e32 v[72:73], v[136:137]
	v_mov_b64_e32 v[68:69], v[132:133]
	v_mov_b64_e32 v[64:65], v[128:129]
	v_mov_b64_e32 v[60:61], v[124:125]
	v_mov_b64_e32 v[56:57], v[120:121]
	v_mov_b64_e32 v[52:53], v[116:117]
	v_mov_b64_e32 v[48:49], v[112:113]
	v_mov_b64_e32 v[44:45], v[108:109]
	v_mov_b64_e32 v[40:41], v[104:105]
	v_mov_b64_e32 v[36:37], v[100:101]
	s_mov_b32 s8, s29
	s_mov_b32 s5, s10
	s_mov_b32 s4, s30
	s_branch .LBB0_1024

; __device__ __forceinline__ unsigned cvt_pk_bf16(float lo, float hi) { unsigned r; asm volatile("v_cvt_pk_bf16_f32 %0, %1, %2" : "=v"(r) : "v"(lo), "v"(hi)); return r; }
;     __device__ __forceinline__ void operator()(const f32x4 (&acc)[2][2][4][2], const Unit& u, int wr, int wc, int fr, int fq) const {
;     ...
;             for (int m = 0; m < 4; ++m) { const int r = u.pm * BM + ai * HALF + wr * 64 + m * 16 + fr; float ss = 0.f;
; #pragma unroll
;                 for (int bj = 0; bj < 2; ++bj) { const int c8 = u.pn * BM + bj * HALF + wc * 32 + 8 * fq; const size_t off = (size_t)r * ldc + c8;
;                     float b[8];
;                     if (BF) { const u32x4 w = *(const u32x4*)((const bf16_t*)base + off); b[0] = bflo(w.x); b[1] = bfhi(w.x); b[2] = bflo(w.y); b[3] = bfhi(w.y); b[4] = bflo(w.z); b[5] = bfhi(w.z); b[6] = bflo(w.w); b[7] = bfhi(w.w); }
;                     else { const f32x4 b0 = __builtin_nontemporal_load((const f32x4*)((const float*)base + off)), b1 = __builtin_nontemporal_load((const f32x4*)((const float*)base + off + 4)); b[0] = b0[0]; b[1] = b0[1]; b[2] = b0[2]; b[3] = b0[3]; b[4] = b1[0]; b[5] = b1[1]; b[6] = b1[2]; b[7] = b1[3]; }
;                     float h[8];
; #pragma unroll
;                     for (int j = 0; j < 4; ++j) { h[j] = b[j] + acc[ai][bj][m][0][j]; h[4 + j] = b[4 + j] + acc[ai][bj][m][1][j]; }
; #pragma unroll
;                     for (int j = 0; j < 8; ++j) ss += h[j] * h[j];
;                     u32x4 w; w.x = cvt_pk_bf16(h[0], h[1]); w.y = cvt_pk_bf16(h[2], h[3]); w.z = cvt_pk_bf16(h[4], h[5]); w.w = cvt_pk_bf16(h[6], h[7]);
;                     *(u32x4*)(Hb + off) = w; }
;                 ss += __shfl_xor(ss, 16); ss += __shfl_xor(ss, 32);
;                 if (fq == 0) unsafeAtomicAdd(sumsq + r, ss); }
.LBB0_1608:
	s_lshl_b32 s2, s62, 8
	v_mov_b32_e32 v146, v1
	v_mov_b32_e32 v172, v152
	s_add_i32 s2, s2, s54
	s_nop 0
	v_add_u32_e32 v148, s2, v146
	s_lshl_b32 s2, s61, 8
	s_or_b32 s2, s2, s55
	v_lshl_add_u32 v146, v172, 3, s2
	v_ashrrev_i32_e32 v149, 31, v148
	v_lshlrev_b64 v[166:167], 11, v[148:149]
	v_ashrrev_i32_e32 v147, 31, v146
	v_lshl_add_u64 v[168:169], v[166:167], 0, v[146:147]
	s_waitcnt lgkmcnt(0)
	v_lshl_add_u64 v[150:151], v[168:169], 2, s[14:15]
	v_mov_b32_e32 v252, v150
	v_mov_b32_e32 v253, v151
	s_mov_b32 s99, 0
	s_mov_b32 s98, 0x0
	v_lshl_add_u64 v[254:255], v[252:253], 0, s[98:99]
	global_load_dwordx4 v[176:179], v[254:255], off nt
	global_load_dwordx4 v[184:187], v[254:255], off offset:16 nt
	s_mov_b32 s98, 0x200
	v_lshl_add_u64 v[254:255], v[252:253], 0, s[98:99]
	global_load_dwordx4 v[188:191], v[254:255], off nt
	global_load_dwordx4 v[192:195], v[254:255], off offset:16 nt
	s_mov_b32 s98, 0x20000
	v_lshl_add_u64 v[254:255], v[252:253], 0, s[98:99]
	global_load_dwordx4 v[200:203], v[254:255], off nt
	global_load_dwordx4 v[204:207], v[254:255], off offset:16 nt
	s_mov_b32 s98, 0x20200
	v_lshl_add_u64 v[254:255], v[252:253], 0, s[98:99]
	global_load_dwordx4 v[208:211], v[254:255], off nt
	global_load_dwordx4 v[212:215], v[254:255], off offset:16 nt
	s_mov_b32 s98, 0x40000
	v_lshl_add_u64 v[254:255], v[252:253], 0, s[98:99]
	global_load_dwordx4 v[218:221], v[254:255], off nt
	global_load_dwordx4 v[222:225], v[254:255], off offset:16 nt
	s_mov_b32 s98, 0x40200
	v_lshl_add_u64 v[254:255], v[252:253], 0, s[98:99]
	global_load_dwordx4 v[226:229], v[254:255], off nt
	global_load_dwordx4 v[230:233], v[254:255], off offset:16 nt
	s_waitcnt vmcnt(10)
	v_mov_b32_e32 v158, v176
	v_mov_b32_e32 v159, v177
	v_mov_b32_e32 v160, v178
	v_mov_b32_e32 v161, v179
	v_mov_b32_e32 v162, v184
	v_mov_b32_e32 v163, v185
	v_mov_b32_e32 v164, v186
	v_mov_b32_e32 v165, v187
	s_mov_b32 s98, 0x60000
	v_lshl_add_u64 v[254:255], v[252:253], 0, s[98:99]
	global_load_dwordx4 v[176:179], v[254:255], off nt
	global_load_dwordx4 v[184:187], v[254:255], off offset:16 nt
	v_add_u32_e32 v150, 0x80, v146
	v_ashrrev_i32_e32 v151, 31, v150
	v_lshl_add_u64 v[166:167], v[166:167], 0, v[150:151]
	v_lshl_add_u64 v[168:169], v[168:169], 1, s[20:21]
	v_lshl_add_u64 v[170:171], v[166:167], 2, s[14:15]
	v_cmp_eq_u32_e32 vcc, 0, v172
	v_add_f32_e32 v173, v122, v158
	v_add_f32_e32 v162, v126, v162
	v_add_f32_e32 v174, v123, v159
	v_add_f32_e32 v163, v127, v163
	v_add_f32_e32 v175, v124, v160
	v_add_f32_e32 v128, v128, v164
	v_add_f32_e32 v164, v125, v161
	v_add_f32_e32 v129, v129, v165
	v_cvt_pk_bf16_f32 v122, v173, v174
	v_cvt_pk_bf16_f32 v123, v175, v164
	v_cvt_pk_bf16_f32 v124, v162, v163
	v_cvt_pk_bf16_f32 v125, v128, v129
	global_store_dwordx4 v[168:169], v[122:125], off sc1
	s_waitcnt vmcnt(11)
	v_mov_b32_e32 v124, v188
	v_mov_b32_e32 v125, v189
	v_mov_b32_e32 v126, v190
	v_mov_b32_e32 v127, v191
	s_nop 0
	v_mov_b32_e32 v158, v192
	v_mov_b32_e32 v159, v193
	v_mov_b32_e32 v160, v194
	v_mov_b32_e32 v161, v195
	s_mov_b32 s98, 0x60200
	v_lshl_add_u64 v[254:255], v[252:253], 0, s[98:99]
	global_load_dwordx4 v[188:191], v[254:255], off nt
	global_load_dwordx4 v[192:195], v[254:255], off offset:16 nt
	v_mul_f32_e32 v168, v174, v174
	v_fmac_f32_e32 v168, v173, v173
	v_fmac_f32_e32 v168, v175, v175
	v_fmac_f32_e32 v168, v164, v164
	v_fmac_f32_e32 v168, v162, v162
	v_fmac_f32_e32 v168, v163, v163
	v_fmac_f32_e32 v168, v128, v128
	v_fmac_f32_e32 v168, v129, v129
	v_and_b32_e32 v123, 64, v157
	v_xor_b32_e32 v122, 16, v157
	v_add_u32_e32 v123, 64, v123
	v_cmp_lt_i32_e64 s[8:9], v122, v123
	v_xor_b32_e32 v165, 32, v157
	v_add_f32_e32 v118, v118, v124
	v_add_f32_e32 v124, v114, v158
	v_add_f32_e32 v114, v119, v125
	v_fmac_f32_e32 v168, v118, v118
	v_add_f32_e32 v125, v115, v159
	v_add_f32_e32 v115, v120, v126
	v_fmac_f32_e32 v168, v114, v114
	v_add_f32_e32 v126, v116, v160
	v_add_f32_e32 v116, v121, v127
	v_fmac_f32_e32 v168, v115, v115
	v_fmac_f32_e32 v168, v116, v116
	v_fmac_f32_e32 v168, v124, v124
	v_fmac_f32_e32 v168, v125, v125
	v_cndmask_b32_e64 v122, v157, v122, s[8:9]
	v_add_f32_e32 v117, v117, v161
	v_fmac_f32_e32 v168, v126, v126
	v_lshlrev_b32_e32 v122, 2, v122
	v_fmac_f32_e32 v168, v117, v117
	ds_bpermute_b32 v120, v122, v168
	v_cmp_lt_i32_e64 s[8:9], v165, v123
	v_cvt_pk_bf16_f32 v118, v118, v114
	v_cvt_pk_bf16_f32 v119, v115, v116
	s_waitcnt lgkmcnt(0)
	v_add_f32_e32 v114, v168, v120
	v_cndmask_b32_e64 v121, v157, v165, s[8:9]
	v_lshlrev_b32_e32 v116, 2, v121
	ds_bpermute_b32 v115, v116, v114
	v_cvt_pk_bf16_f32 v120, v124, v125
	v_lshl_add_u64 v[124:125], v[166:167], 1, s[20:21]
	v_cvt_pk_bf16_f32 v121, v126, v117
	global_store_dwordx4 v[124:125], v[118:121], off sc1
	s_and_saveexec_b64 s[8:9], vcc
	s_cbranch_execz .LBB0_1610
	v_lshl_add_u64 v[118:119], v[148:149], 2, s[18:19]
	s_waitcnt lgkmcnt(0)
	v_add_f32_e32 v114, v114, v115
	global_atomic_add_f32 v[118:119], v114, off
; __device__ __forceinline__ unsigned cvt_pk_bf16(float lo, float hi) { unsigned r; asm volatile("v_cvt_pk_bf16_f32 %0, %1, %2" : "=v"(r) : "v"(lo), "v"(hi)); return r; }
;     __device__ __forceinline__ void operator()(const f32x4 (&acc)[2][2][4][2], const Unit& u, int wr, int wc, int fr, int fq) const {
;     ...
;             for (int m = 0; m < 4; ++m) { const int r = u.pm * BM + ai * HALF + wr * 64 + m * 16 + fr; float ss = 0.f;
; #pragma unroll
;                 for (int bj = 0; bj < 2; ++bj) { const int c8 = u.pn * BM + bj * HALF + wc * 32 + 8 * fq; const size_t off = (size_t)r * ldc + c8;
;                     float b[8];
;                     if (BF) { const u32x4 w = *(const u32x4*)((const bf16_t*)base + off); b[0] = bflo(w.x); b[1] = bfhi(w.x); b[2] = bflo(w.y); b[3] = bfhi(w.y); b[4] = bflo(w.z); b[5] = bfhi(w.z); b[6] = bflo(w.w); b[7] = bfhi(w.w); }
;                     else { const f32x4 b0 = __builtin_nontemporal_load((const f32x4*)((const float*)base + off)), b1 = __builtin_nontemporal_load((const f32x4*)((const float*)base + off + 4)); b[0] = b0[0]; b[1] = b0[1]; b[2] = b0[2]; b[3] = b0[3]; b[4] = b1[0]; b[5] = b1[1]; b[6] = b1[2]; b[7] = b1[3]; }
;                     float h[8];
; #pragma unroll
;                     for (int j = 0; j < 4; ++j) { h[j] = b[j] + acc[ai][bj][m][0][j]; h[4 + j] = b[4 + j] + acc[ai][bj][m][1][j]; }
; #pragma unroll
;                     for (int j = 0; j < 8; ++j) ss += h[j] * h[j];
;                     u32x4 w; w.x = cvt_pk_bf16(h[0], h[1]); w.y = cvt_pk_bf16(h[2], h[3]); w.z = cvt_pk_bf16(h[4], h[5]); w.w = cvt_pk_bf16(h[6], h[7]);
;                     *(u32x4*)(Hb + off) = w; }
;                 ss += __shfl_xor(ss, 16); ss += __shfl_xor(ss, 32);
;                 if (fq == 0) unsafeAtomicAdd(sumsq + r, ss); }
.LBB0_1610:
	s_or_b64 exec, exec, s[8:9]
	v_add_u32_e32 v114, 16, v148
	s_waitcnt lgkmcnt(0)
	v_ashrrev_i32_e32 v115, 31, v114
	v_lshlrev_b64 v[128:129], 11, v[114:115]
	v_lshl_add_u64 v[158:159], v[128:129], 0, v[146:147]
	v_lshl_add_u64 v[124:125], v[158:159], 2, s[14:15]
	s_waitcnt vmcnt(12)
	v_mov_b32_e32 v118, v200
	v_mov_b32_e32 v119, v201
	v_mov_b32_e32 v120, v202
	v_mov_b32_e32 v121, v203
	s_nop 0
	v_mov_b32_e32 v124, v204
	v_mov_b32_e32 v125, v205
	v_mov_b32_e32 v126, v206
	v_mov_b32_e32 v127, v207
	s_mov_b32 s98, 0x100000
	v_lshl_add_u64 v[254:255], v[252:253], 0, s[98:99]
	global_load_dwordx4 v[200:203], v[254:255], off nt
	global_load_dwordx4 v[204:207], v[254:255], off offset:16 nt
	v_lshl_add_u64 v[128:129], v[128:129], 0, v[150:151]
	v_lshl_add_u64 v[158:159], v[158:159], 1, s[20:21]
	v_lshl_add_u64 v[160:161], v[128:129], 2, s[14:15]
	v_add_f32_e32 v117, v110, v118
	v_add_f32_e32 v118, v106, v124
	v_add_f32_e32 v119, v111, v119
	v_add_f32_e32 v123, v107, v125
	v_add_f32_e32 v120, v112, v120
	v_add_f32_e32 v124, v108, v126
	v_add_f32_e32 v121, v113, v121
	v_add_f32_e32 v125, v109, v127
	v_cvt_pk_bf16_f32 v106, v117, v119
	v_cvt_pk_bf16_f32 v107, v120, v121
	v_cvt_pk_bf16_f32 v108, v118, v123
	v_cvt_pk_bf16_f32 v109, v124, v125
	global_store_dwordx4 v[158:159], v[106:109], off sc1
	s_waitcnt vmcnt(13)
	v_mov_b32_e32 v106, v208
	v_mov_b32_e32 v107, v209
	v_mov_b32_e32 v108, v210
	v_mov_b32_e32 v109, v211
	s_nop 0
	v_mov_b32_e32 v110, v212
	v_mov_b32_e32 v111, v213
	v_mov_b32_e32 v112, v214
	v_mov_b32_e32 v113, v215
	s_mov_b32 s98, 0x100200
	v_lshl_add_u64 v[254:255], v[252:253], 0, s[98:99]
	global_load_dwordx4 v[208:211], v[254:255], off nt
	global_load_dwordx4 v[212:215], v[254:255], off offset:16 nt
	v_mul_f32_e32 v119, v119, v119
	v_fmac_f32_e32 v119, v117, v117
	v_fmac_f32_e32 v119, v120, v120
	v_fmac_f32_e32 v119, v121, v121
	v_fmac_f32_e32 v119, v118, v118
	v_fmac_f32_e32 v119, v123, v123
	v_fmac_f32_e32 v119, v124, v124
	v_fmac_f32_e32 v119, v125, v125
	v_add_f32_e32 v102, v102, v106
	v_add_f32_e32 v106, v98, v110
	v_add_f32_e32 v98, v103, v107
	v_fmac_f32_e32 v119, v102, v102
	v_add_f32_e32 v103, v99, v111
	v_add_f32_e32 v99, v104, v108
	v_fmac_f32_e32 v119, v98, v98
	v_add_f32_e32 v105, v105, v109
	v_fmac_f32_e32 v119, v99, v99
	v_fmac_f32_e32 v119, v105, v105
	v_fmac_f32_e32 v119, v106, v106
	v_add_f32_e32 v104, v100, v112
	v_fmac_f32_e32 v119, v103, v103
	v_add_f32_e32 v107, v101, v113
	v_fmac_f32_e32 v119, v104, v104
	v_fmac_f32_e32 v119, v107, v107
	ds_bpermute_b32 v108, v122, v119
	v_cvt_pk_bf16_f32 v100, v102, v98
	v_cvt_pk_bf16_f32 v101, v99, v105
	v_cvt_pk_bf16_f32 v102, v106, v103
	v_cvt_pk_bf16_f32 v103, v104, v107
	s_waitcnt lgkmcnt(0)
	v_add_f32_e32 v98, v119, v108
	ds_bpermute_b32 v99, v116, v98
	v_lshl_add_u64 v[104:105], v[128:129], 1, s[20:21]
	global_store_dwordx4 v[104:105], v[100:103], off sc1
	s_and_saveexec_b64 s[8:9], vcc
	s_cbranch_execz .LBB0_1612
	v_lshl_add_u64 v[100:101], v[114:115], 2, s[18:19]
	s_waitcnt lgkmcnt(0)
	v_add_f32_e32 v98, v98, v99
	global_atomic_add_f32 v[100:101], v98, off
.LBB0_1612:
	s_or_b64 exec, exec, s[8:9]
	v_add_u32_e32 v98, 32, v148
	s_waitcnt lgkmcnt(0)
	v_ashrrev_i32_e32 v99, 31, v98
	v_lshlrev_b64 v[108:109], 11, v[98:99]
	v_lshl_add_u64 v[110:111], v[108:109], 0, v[146:147]
	v_lshl_add_u64 v[104:105], v[110:111], 2, s[14:15]
	s_waitcnt vmcnt(14)
	v_mov_b32_e32 v100, v218
	v_mov_b32_e32 v101, v219
	v_mov_b32_e32 v102, v220
	v_mov_b32_e32 v103, v221
	s_nop 0
	v_mov_b32_e32 v104, v222
	v_mov_b32_e32 v105, v223
	v_mov_b32_e32 v106, v224
	v_mov_b32_e32 v107, v225
	s_mov_b32 s98, 0x120000
	v_lshl_add_u64 v[254:255], v[252:253], 0, s[98:99]
	global_load_dwordx4 v[218:221], v[254:255], off nt
	global_load_dwordx4 v[222:225], v[254:255], off offset:16 nt
	v_lshl_add_u64 v[108:109], v[108:109], 0, v[150:151]
	v_lshl_add_u64 v[110:111], v[110:111], 1, s[20:21]
	v_lshl_add_u64 v[112:113], v[108:109], 2, s[14:15]
	v_add_f32_e32 v100, v94, v100
	v_add_f32_e32 v104, v90, v104
	v_add_f32_e32 v101, v95, v101
	v_add_f32_e32 v105, v91, v105
	v_add_f32_e32 v102, v96, v102
	v_add_f32_e32 v106, v92, v106
	v_add_f32_e32 v103, v97, v103
	v_add_f32_e32 v107, v93, v107
	v_cvt_pk_bf16_f32 v90, v100, v101
	v_cvt_pk_bf16_f32 v91, v102, v103
	v_cvt_pk_bf16_f32 v92, v104, v105
	v_cvt_pk_bf16_f32 v93, v106, v107
	global_store_dwordx4 v[110:111], v[90:93], off sc1
	s_waitcnt vmcnt(15)
	v_mov_b32_e32 v90, v226
	v_mov_b32_e32 v91, v227
	v_mov_b32_e32 v92, v228
	v_mov_b32_e32 v93, v229
	s_nop 0
	v_mov_b32_e32 v94, v230
	v_mov_b32_e32 v95, v231
	v_mov_b32_e32 v96, v232
	v_mov_b32_e32 v97, v233
	s_mov_b32 s98, 0x120200
	v_lshl_add_u64 v[254:255], v[252:253], 0, s[98:99]
	global_load_dwordx4 v[226:229], v[254:255], off nt
	global_load_dwordx4 v[230:233], v[254:255], off offset:16 nt
	v_mul_f32_e32 v101, v101, v101
	v_fmac_f32_e32 v101, v100, v100
	v_fmac_f32_e32 v101, v102, v102
	v_fmac_f32_e32 v101, v103, v103
	v_fmac_f32_e32 v101, v104, v104
	v_fmac_f32_e32 v101, v105, v105
	v_fmac_f32_e32 v101, v106, v106
	v_fmac_f32_e32 v101, v107, v107
	v_add_f32_e32 v86, v86, v90
	v_add_f32_e32 v90, v82, v94
	v_add_f32_e32 v82, v87, v91
	v_fmac_f32_e32 v101, v86, v86
	v_add_f32_e32 v87, v83, v95
	v_add_f32_e32 v83, v88, v92
	v_fmac_f32_e32 v101, v82, v82
	v_add_f32_e32 v89, v89, v93
	v_fmac_f32_e32 v101, v83, v83
	v_fmac_f32_e32 v101, v89, v89
	v_fmac_f32_e32 v101, v90, v90
	v_add_f32_e32 v88, v84, v96
	v_fmac_f32_e32 v101, v87, v87
	v_add_f32_e32 v91, v85, v97
	v_fmac_f32_e32 v101, v88, v88
	v_fmac_f32_e32 v101, v91, v91
	ds_bpermute_b32 v92, v122, v101
	v_cvt_pk_bf16_f32 v84, v86, v82
	v_cvt_pk_bf16_f32 v85, v83, v89
	v_cvt_pk_bf16_f32 v86, v90, v87
	v_cvt_pk_bf16_f32 v87, v88, v91
	s_waitcnt lgkmcnt(0)
	v_add_f32_e32 v82, v101, v92
	ds_bpermute_b32 v83, v116, v82
	v_lshl_add_u64 v[88:89], v[108:109], 1, s[20:21]
	global_store_dwordx4 v[88:89], v[84:87], off sc1
	s_and_saveexec_b64 s[8:9], vcc
	s_cbranch_execz .LBB0_1614
	v_lshl_add_u64 v[84:85], v[98:99], 2, s[18:19]
	s_waitcnt lgkmcnt(0)
	v_add_f32_e32 v82, v82, v83
	global_atomic_add_f32 v[84:85], v82, off
; __device__ __forceinline__ unsigned cvt_pk_bf16(float lo, float hi) { unsigned r; asm volatile("v_cvt_pk_bf16_f32 %0, %1, %2" : "=v"(r) : "v"(lo), "v"(hi)); return r; }
;     __device__ __forceinline__ void operator()(const f32x4 (&acc)[2][2][4][2], const Unit& u, int wr, int wc, int fr, int fq) const {
;     ...
;             for (int m = 0; m < 4; ++m) { const int r = u.pm * BM + ai * HALF + wr * 64 + m * 16 + fr; float ss = 0.f;
; #pragma unroll
;                 for (int bj = 0; bj < 2; ++bj) { const int c8 = u.pn * BM + bj * HALF + wc * 32 + 8 * fq; const size_t off = (size_t)r * ldc + c8;
;                     float b[8];
;                     if (BF) { const u32x4 w = *(const u32x4*)((const bf16_t*)base + off); b[0] = bflo(w.x); b[1] = bfhi(w.x); b[2] = bflo(w.y); b[3] = bfhi(w.y); b[4] = bflo(w.z); b[5] = bfhi(w.z); b[6] = bflo(w.w); b[7] = bfhi(w.w); }
;                     else { const f32x4 b0 = __builtin_nontemporal_load((const f32x4*)((const float*)base + off)), b1 = __builtin_nontemporal_load((const f32x4*)((const float*)base + off + 4)); b[0] = b0[0]; b[1] = b0[1]; b[2] = b0[2]; b[3] = b0[3]; b[4] = b1[0]; b[5] = b1[1]; b[6] = b1[2]; b[7] = b1[3]; }
;                     float h[8];
; #pragma unroll
;                     for (int j = 0; j < 4; ++j) { h[j] = b[j] + acc[ai][bj][m][0][j]; h[4 + j] = b[4 + j] + acc[ai][bj][m][1][j]; }
; #pragma unroll
;                     for (int j = 0; j < 8; ++j) ss += h[j] * h[j];
;                     u32x4 w; w.x = cvt_pk_bf16(h[0], h[1]); w.y = cvt_pk_bf16(h[2], h[3]); w.z = cvt_pk_bf16(h[4], h[5]); w.w = cvt_pk_bf16(h[6], h[7]);
;                     *(u32x4*)(Hb + off) = w; }
;                 ss += __shfl_xor(ss, 16); ss += __shfl_xor(ss, 32);
;                 if (fq == 0) unsafeAtomicAdd(sumsq + r, ss); }
.LBB0_1614:
	s_or_b64 exec, exec, s[8:9]
	v_add_u32_e32 v82, 48, v148
	s_waitcnt lgkmcnt(0)
	v_ashrrev_i32_e32 v83, 31, v82
	v_lshlrev_b64 v[92:93], 11, v[82:83]
	v_lshl_add_u64 v[94:95], v[92:93], 0, v[146:147]
	v_lshl_add_u64 v[88:89], v[94:95], 2, s[14:15]
	s_waitcnt vmcnt(16)
	v_mov_b32_e32 v84, v176
	v_mov_b32_e32 v85, v177
	v_mov_b32_e32 v86, v178
	v_mov_b32_e32 v87, v179
	s_nop 0
	v_mov_b32_e32 v88, v184
	v_mov_b32_e32 v89, v185
	v_mov_b32_e32 v90, v186
	v_mov_b32_e32 v91, v187
	s_mov_b32 s98, 0x140000
	v_lshl_add_u64 v[254:255], v[252:253], 0, s[98:99]
	global_load_dwordx4 v[176:179], v[254:255], off nt
	global_load_dwordx4 v[184:187], v[254:255], off offset:16 nt
	v_lshl_add_u64 v[92:93], v[92:93], 0, v[150:151]
	v_lshl_add_u64 v[94:95], v[94:95], 1, s[20:21]
	v_lshl_add_u64 v[96:97], v[92:93], 2, s[14:15]
	v_add_f32_e32 v84, v78, v84
	v_add_f32_e32 v88, v74, v88
	v_add_f32_e32 v85, v79, v85
	v_add_f32_e32 v89, v75, v89
	v_add_f32_e32 v86, v80, v86
	v_add_f32_e32 v90, v76, v90
	v_add_f32_e32 v87, v81, v87
	v_add_f32_e32 v91, v77, v91
	v_cvt_pk_bf16_f32 v74, v84, v85
	v_cvt_pk_bf16_f32 v75, v86, v87
	v_cvt_pk_bf16_f32 v76, v88, v89
	v_cvt_pk_bf16_f32 v77, v90, v91
	global_store_dwordx4 v[94:95], v[74:77], off sc1
	s_waitcnt vmcnt(16)
	v_mov_b32_e32 v74, v188
	v_mov_b32_e32 v75, v189
	v_mov_b32_e32 v76, v190
	v_mov_b32_e32 v77, v191
	s_nop 0
	v_mov_b32_e32 v78, v192
	v_mov_b32_e32 v79, v193
	v_mov_b32_e32 v80, v194
	v_mov_b32_e32 v81, v195
	s_mov_b32 s98, 0x140200
	v_lshl_add_u64 v[254:255], v[252:253], 0, s[98:99]
	global_load_dwordx4 v[188:191], v[254:255], off nt
	global_load_dwordx4 v[192:195], v[254:255], off offset:16 nt
	v_mul_f32_e32 v85, v85, v85
	v_fmac_f32_e32 v85, v84, v84
	v_fmac_f32_e32 v85, v86, v86
	v_fmac_f32_e32 v85, v87, v87
	v_fmac_f32_e32 v85, v88, v88
	v_fmac_f32_e32 v85, v89, v89
	v_fmac_f32_e32 v85, v90, v90
	v_fmac_f32_e32 v85, v91, v91
	v_add_f32_e32 v70, v70, v74
	v_add_f32_e32 v74, v66, v78
	v_add_f32_e32 v66, v71, v75
	v_fmac_f32_e32 v85, v70, v70
	v_add_f32_e32 v71, v67, v79
	v_add_f32_e32 v67, v72, v76
	v_fmac_f32_e32 v85, v66, v66
	v_add_f32_e32 v73, v73, v77
	v_fmac_f32_e32 v85, v67, v67
	v_fmac_f32_e32 v85, v73, v73
	v_fmac_f32_e32 v85, v74, v74
	v_add_f32_e32 v72, v68, v80
	v_fmac_f32_e32 v85, v71, v71
	v_add_f32_e32 v75, v69, v81
	v_fmac_f32_e32 v85, v72, v72
	v_fmac_f32_e32 v85, v75, v75
	ds_bpermute_b32 v76, v122, v85
	v_cvt_pk_bf16_f32 v68, v70, v66
	v_cvt_pk_bf16_f32 v69, v67, v73
	v_cvt_pk_bf16_f32 v70, v74, v71
	v_cvt_pk_bf16_f32 v71, v72, v75
	s_waitcnt lgkmcnt(0)
	v_add_f32_e32 v66, v85, v76
	ds_bpermute_b32 v67, v116, v66
	v_lshl_add_u64 v[72:73], v[92:93], 1, s[20:21]
	global_store_dwordx4 v[72:73], v[68:71], off sc1
	s_and_saveexec_b64 s[8:9], vcc
	s_cbranch_execz .LBB0_1616
	v_lshl_add_u64 v[68:69], v[82:83], 2, s[18:19]
	s_waitcnt lgkmcnt(0)
	v_add_f32_e32 v66, v66, v67
	global_atomic_add_f32 v[68:69], v66, off
.LBB0_1616:
	s_or_b64 exec, exec, s[8:9]
	v_add_u32_e32 v66, 0x80, v148
	s_waitcnt lgkmcnt(0)
	v_ashrrev_i32_e32 v67, 31, v66
	v_lshlrev_b64 v[76:77], 11, v[66:67]
	v_lshl_add_u64 v[78:79], v[76:77], 0, v[146:147]
	v_lshl_add_u64 v[72:73], v[78:79], 2, s[14:15]
	s_waitcnt vmcnt(16)
	v_mov_b32_e32 v68, v200
	v_mov_b32_e32 v69, v201
	v_mov_b32_e32 v70, v202
	v_mov_b32_e32 v71, v203
	s_nop 0
	v_mov_b32_e32 v72, v204
	v_mov_b32_e32 v73, v205
	v_mov_b32_e32 v74, v206
	v_mov_b32_e32 v75, v207
	s_mov_b32 s98, 0x160000
	v_lshl_add_u64 v[254:255], v[252:253], 0, s[98:99]
	global_load_dwordx4 v[200:203], v[254:255], off nt
	global_load_dwordx4 v[204:207], v[254:255], off offset:16 nt
	v_lshl_add_u64 v[76:77], v[76:77], 0, v[150:151]
	v_lshl_add_u64 v[78:79], v[78:79], 1, s[20:21]
	v_lshl_add_u64 v[80:81], v[76:77], 2, s[14:15]
	v_add_f32_e32 v68, v62, v68
	v_add_f32_e32 v72, v58, v72
	v_add_f32_e32 v69, v63, v69
	v_add_f32_e32 v73, v59, v73
	v_add_f32_e32 v70, v64, v70
	v_add_f32_e32 v74, v60, v74
	v_add_f32_e32 v71, v65, v71
	v_add_f32_e32 v75, v61, v75
	v_cvt_pk_bf16_f32 v58, v68, v69
	v_cvt_pk_bf16_f32 v59, v70, v71
	v_cvt_pk_bf16_f32 v60, v72, v73
	v_cvt_pk_bf16_f32 v61, v74, v75
	global_store_dwordx4 v[78:79], v[58:61], off sc1
	s_waitcnt vmcnt(16)
	v_mov_b32_e32 v58, v208
	v_mov_b32_e32 v59, v209
	v_mov_b32_e32 v60, v210
	v_mov_b32_e32 v61, v211
	s_nop 0
	v_mov_b32_e32 v62, v212
	v_mov_b32_e32 v63, v213
	v_mov_b32_e32 v64, v214
	v_mov_b32_e32 v65, v215
	s_mov_b32 s98, 0x160200
	v_lshl_add_u64 v[254:255], v[252:253], 0, s[98:99]
	global_load_dwordx4 v[208:211], v[254:255], off nt
	global_load_dwordx4 v[212:215], v[254:255], off offset:16 nt
	v_mul_f32_e32 v69, v69, v69
	v_fmac_f32_e32 v69, v68, v68
	v_fmac_f32_e32 v69, v70, v70
	v_fmac_f32_e32 v69, v71, v71
	v_fmac_f32_e32 v69, v72, v72
	v_fmac_f32_e32 v69, v73, v73
	v_fmac_f32_e32 v69, v74, v74
	v_fmac_f32_e32 v69, v75, v75
	v_add_f32_e32 v54, v54, v58
	v_add_f32_e32 v58, v50, v62
	v_add_f32_e32 v50, v55, v59
	v_fmac_f32_e32 v69, v54, v54
	v_add_f32_e32 v55, v51, v63
	v_add_f32_e32 v51, v56, v60
	v_fmac_f32_e32 v69, v50, v50
	v_add_f32_e32 v57, v57, v61
	v_fmac_f32_e32 v69, v51, v51
	v_fmac_f32_e32 v69, v57, v57
	v_fmac_f32_e32 v69, v58, v58
	v_add_f32_e32 v56, v52, v64
	v_fmac_f32_e32 v69, v55, v55
	v_add_f32_e32 v59, v53, v65
	v_fmac_f32_e32 v69, v56, v56
	v_fmac_f32_e32 v69, v59, v59
	ds_bpermute_b32 v60, v122, v69
	v_cvt_pk_bf16_f32 v52, v54, v50
	v_cvt_pk_bf16_f32 v53, v51, v57
	v_cvt_pk_bf16_f32 v54, v58, v55
	v_cvt_pk_bf16_f32 v55, v56, v59
	s_waitcnt lgkmcnt(0)
	v_add_f32_e32 v50, v69, v60
	ds_bpermute_b32 v51, v116, v50
	v_lshl_add_u64 v[56:57], v[76:77], 1, s[20:21]
	global_store_dwordx4 v[56:57], v[52:55], off sc1
	s_and_saveexec_b64 s[8:9], vcc
	s_cbranch_execz .LBB0_1618
	v_lshl_add_u64 v[52:53], v[66:67], 2, s[18:19]
	s_waitcnt lgkmcnt(0)
	v_add_f32_e32 v50, v50, v51
	global_atomic_add_f32 v[52:53], v50, off
; __device__ __forceinline__ unsigned cvt_pk_bf16(float lo, float hi) { unsigned r; asm volatile("v_cvt_pk_bf16_f32 %0, %1, %2" : "=v"(r) : "v"(lo), "v"(hi)); return r; }
;     __device__ __forceinline__ void operator()(const f32x4 (&acc)[2][2][4][2], const Unit& u, int wr, int wc, int fr, int fq) const {
;     ...
;             for (int m = 0; m < 4; ++m) { const int r = u.pm * BM + ai * HALF + wr * 64 + m * 16 + fr; float ss = 0.f;
; #pragma unroll
;                 for (int bj = 0; bj < 2; ++bj) { const int c8 = u.pn * BM + bj * HALF + wc * 32 + 8 * fq; const size_t off = (size_t)r * ldc + c8;
;                     float b[8];
;                     if (BF) { const u32x4 w = *(const u32x4*)((const bf16_t*)base + off); b[0] = bflo(w.x); b[1] = bfhi(w.x); b[2] = bflo(w.y); b[3] = bfhi(w.y); b[4] = bflo(w.z); b[5] = bfhi(w.z); b[6] = bflo(w.w); b[7] = bfhi(w.w); }
;                     else { const f32x4 b0 = __builtin_nontemporal_load((const f32x4*)((const float*)base + off)), b1 = __builtin_nontemporal_load((const f32x4*)((const float*)base + off + 4)); b[0] = b0[0]; b[1] = b0[1]; b[2] = b0[2]; b[3] = b0[3]; b[4] = b1[0]; b[5] = b1[1]; b[6] = b1[2]; b[7] = b1[3]; }
;                     float h[8];
; #pragma unroll
;                     for (int j = 0; j < 4; ++j) { h[j] = b[j] + acc[ai][bj][m][0][j]; h[4 + j] = b[4 + j] + acc[ai][bj][m][1][j]; }
; #pragma unroll
;                     for (int j = 0; j < 8; ++j) ss += h[j] * h[j];
;                     u32x4 w; w.x = cvt_pk_bf16(h[0], h[1]); w.y = cvt_pk_bf16(h[2], h[3]); w.z = cvt_pk_bf16(h[4], h[5]); w.w = cvt_pk_bf16(h[6], h[7]);
;                     *(u32x4*)(Hb + off) = w; }
;                 ss += __shfl_xor(ss, 16); ss += __shfl_xor(ss, 32);
;                 if (fq == 0) unsafeAtomicAdd(sumsq + r, ss); }
.LBB0_1618:
	s_or_b64 exec, exec, s[8:9]
	v_add_u32_e32 v50, 0x90, v148
	s_waitcnt lgkmcnt(0)
	v_ashrrev_i32_e32 v51, 31, v50
	v_lshlrev_b64 v[60:61], 11, v[50:51]
	v_lshl_add_u64 v[62:63], v[60:61], 0, v[146:147]
	v_lshl_add_u64 v[56:57], v[62:63], 2, s[14:15]
	s_waitcnt vmcnt(16)
	v_mov_b32_e32 v52, v218
	v_mov_b32_e32 v53, v219
	v_mov_b32_e32 v54, v220
	v_mov_b32_e32 v55, v221
	s_nop 0
	v_mov_b32_e32 v56, v222
	v_mov_b32_e32 v57, v223
	v_mov_b32_e32 v58, v224
	v_mov_b32_e32 v59, v225
	v_lshl_add_u64 v[60:61], v[60:61], 0, v[150:151]
	v_lshl_add_u64 v[62:63], v[62:63], 1, s[20:21]
	v_lshl_add_u64 v[64:65], v[60:61], 2, s[14:15]
	v_add_f32_e32 v52, v46, v52
	v_add_f32_e32 v56, v42, v56
	v_add_f32_e32 v53, v47, v53
	v_add_f32_e32 v57, v43, v57
	v_add_f32_e32 v54, v48, v54
	v_add_f32_e32 v58, v44, v58
	v_add_f32_e32 v55, v49, v55
	v_add_f32_e32 v59, v45, v59
	v_cvt_pk_bf16_f32 v42, v52, v53
	v_cvt_pk_bf16_f32 v43, v54, v55
	v_cvt_pk_bf16_f32 v44, v56, v57
	v_cvt_pk_bf16_f32 v45, v58, v59
	global_store_dwordx4 v[62:63], v[42:45], off sc1
	s_waitcnt vmcnt(14)
	v_mov_b32_e32 v42, v226
	v_mov_b32_e32 v43, v227
	v_mov_b32_e32 v44, v228
	v_mov_b32_e32 v45, v229
	s_nop 0
	v_mov_b32_e32 v46, v230
	v_mov_b32_e32 v47, v231
	v_mov_b32_e32 v48, v232
	v_mov_b32_e32 v49, v233
	v_mul_f32_e32 v53, v53, v53
	v_fmac_f32_e32 v53, v52, v52
	v_fmac_f32_e32 v53, v54, v54
	v_fmac_f32_e32 v53, v55, v55
	v_fmac_f32_e32 v53, v56, v56
	v_fmac_f32_e32 v53, v57, v57
	v_fmac_f32_e32 v53, v58, v58
	v_fmac_f32_e32 v53, v59, v59
	v_add_f32_e32 v38, v38, v42
	v_add_f32_e32 v42, v34, v46
	v_add_f32_e32 v34, v39, v43
	v_fmac_f32_e32 v53, v38, v38
	v_add_f32_e32 v39, v35, v47
	v_add_f32_e32 v35, v40, v44
	v_fmac_f32_e32 v53, v34, v34
	v_add_f32_e32 v41, v41, v45
	v_fmac_f32_e32 v53, v35, v35
	v_fmac_f32_e32 v53, v41, v41
	v_fmac_f32_e32 v53, v42, v42
	v_add_f32_e32 v40, v36, v48
	v_fmac_f32_e32 v53, v39, v39
	v_add_f32_e32 v43, v37, v49
	v_fmac_f32_e32 v53, v40, v40
	v_fmac_f32_e32 v53, v43, v43
	ds_bpermute_b32 v44, v122, v53
	v_cvt_pk_bf16_f32 v36, v38, v34
	v_cvt_pk_bf16_f32 v37, v35, v41
	v_cvt_pk_bf16_f32 v38, v42, v39
	v_cvt_pk_bf16_f32 v39, v40, v43
	s_waitcnt lgkmcnt(0)
	v_add_f32_e32 v34, v53, v44
	ds_bpermute_b32 v35, v116, v34
	v_lshl_add_u64 v[40:41], v[60:61], 1, s[20:21]
	global_store_dwordx4 v[40:41], v[36:39], off sc1
	s_and_saveexec_b64 s[8:9], vcc
	s_cbranch_execz .LBB0_1620
	v_lshl_add_u64 v[36:37], v[50:51], 2, s[18:19]
	s_waitcnt lgkmcnt(0)
	v_add_f32_e32 v34, v34, v35
	global_atomic_add_f32 v[36:37], v34, off
; __device__ __forceinline__ unsigned cvt_pk_bf16(float lo, float hi) { unsigned r; asm volatile("v_cvt_pk_bf16_f32 %0, %1, %2" : "=v"(r) : "v"(lo), "v"(hi)); return r; }
;     __device__ __forceinline__ void operator()(const f32x4 (&acc)[2][2][4][2], const Unit& u, int wr, int wc, int fr, int fq) const {
;     ...
;             for (int m = 0; m < 4; ++m) { const int r = u.pm * BM + ai * HALF + wr * 64 + m * 16 + fr; float ss = 0.f;
; #pragma unroll
;                 for (int bj = 0; bj < 2; ++bj) { const int c8 = u.pn * BM + bj * HALF + wc * 32 + 8 * fq; const size_t off = (size_t)r * ldc + c8;
;                     float b[8];
;                     if (BF) { const u32x4 w = *(const u32x4*)((const bf16_t*)base + off); b[0] = bflo(w.x); b[1] = bfhi(w.x); b[2] = bflo(w.y); b[3] = bfhi(w.y); b[4] = bflo(w.z); b[5] = bfhi(w.z); b[6] = bflo(w.w); b[7] = bfhi(w.w); }
;                     else { const f32x4 b0 = __builtin_nontemporal_load((const f32x4*)((const float*)base + off)), b1 = __builtin_nontemporal_load((const f32x4*)((const float*)base + off + 4)); b[0] = b0[0]; b[1] = b0[1]; b[2] = b0[2]; b[3] = b0[3]; b[4] = b1[0]; b[5] = b1[1]; b[6] = b1[2]; b[7] = b1[3]; }
;                     float h[8];
; #pragma unroll
;                     for (int j = 0; j < 4; ++j) { h[j] = b[j] + acc[ai][bj][m][0][j]; h[4 + j] = b[4 + j] + acc[ai][bj][m][1][j]; }
; #pragma unroll
;                     for (int j = 0; j < 8; ++j) ss += h[j] * h[j];
;                     u32x4 w; w.x = cvt_pk_bf16(h[0], h[1]); w.y = cvt_pk_bf16(h[2], h[3]); w.z = cvt_pk_bf16(h[4], h[5]); w.w = cvt_pk_bf16(h[6], h[7]);
;                     *(u32x4*)(Hb + off) = w; }
;                 ss += __shfl_xor(ss, 16); ss += __shfl_xor(ss, 32);
;                 if (fq == 0) unsafeAtomicAdd(sumsq + r, ss); }
.LBB0_1620:
	s_or_b64 exec, exec, s[8:9]
	v_add_u32_e32 v34, 0xa0, v148
	s_waitcnt lgkmcnt(0)
	v_ashrrev_i32_e32 v35, 31, v34
	v_lshlrev_b64 v[44:45], 11, v[34:35]
	v_lshl_add_u64 v[46:47], v[44:45], 0, v[146:147]
	v_lshl_add_u64 v[40:41], v[46:47], 2, s[14:15]
	s_waitcnt vmcnt(12)
	v_mov_b32_e32 v36, v176
	v_mov_b32_e32 v37, v177
	v_mov_b32_e32 v38, v178
	v_mov_b32_e32 v39, v179
	s_nop 0
	v_mov_b32_e32 v40, v184
	v_mov_b32_e32 v41, v185
	v_mov_b32_e32 v42, v186
	v_mov_b32_e32 v43, v187
	v_lshl_add_u64 v[44:45], v[44:45], 0, v[150:151]
	v_lshl_add_u64 v[46:47], v[46:47], 1, s[20:21]
	v_lshl_add_u64 v[48:49], v[44:45], 2, s[14:15]
	v_add_f32_e32 v36, v30, v36
	v_add_f32_e32 v40, v26, v40
	v_add_f32_e32 v37, v31, v37
	v_add_f32_e32 v41, v27, v41
	v_add_f32_e32 v38, v32, v38
	v_add_f32_e32 v42, v28, v42
	v_add_f32_e32 v39, v33, v39
	v_add_f32_e32 v43, v29, v43
	v_cvt_pk_bf16_f32 v26, v36, v37
	v_cvt_pk_bf16_f32 v27, v38, v39
	v_cvt_pk_bf16_f32 v28, v40, v41
	v_cvt_pk_bf16_f32 v29, v42, v43
	global_store_dwordx4 v[46:47], v[26:29], off sc1
	s_waitcnt vmcnt(10)
	v_mov_b32_e32 v26, v188
	v_mov_b32_e32 v27, v189
	v_mov_b32_e32 v28, v190
	v_mov_b32_e32 v29, v191
	s_nop 0
	v_mov_b32_e32 v30, v192
	v_mov_b32_e32 v31, v193
	v_mov_b32_e32 v32, v194
	v_mov_b32_e32 v33, v195
	v_mul_f32_e32 v37, v37, v37
	v_fmac_f32_e32 v37, v36, v36
	v_fmac_f32_e32 v37, v38, v38
	v_fmac_f32_e32 v37, v39, v39
	v_fmac_f32_e32 v37, v40, v40
	v_fmac_f32_e32 v37, v41, v41
	v_fmac_f32_e32 v37, v42, v42
	v_fmac_f32_e32 v37, v43, v43
	v_add_f32_e32 v22, v22, v26
	v_add_f32_e32 v26, v18, v30
	v_add_f32_e32 v18, v23, v27
	v_fmac_f32_e32 v37, v22, v22
	v_add_f32_e32 v23, v19, v31
	v_add_f32_e32 v19, v24, v28
	v_fmac_f32_e32 v37, v18, v18
	v_add_f32_e32 v25, v25, v29
	v_fmac_f32_e32 v37, v19, v19
	v_fmac_f32_e32 v37, v25, v25
	v_fmac_f32_e32 v37, v26, v26
	v_add_f32_e32 v24, v20, v32
	v_fmac_f32_e32 v37, v23, v23
	v_add_f32_e32 v27, v21, v33
	v_fmac_f32_e32 v37, v24, v24
	v_fmac_f32_e32 v37, v27, v27
	ds_bpermute_b32 v28, v122, v37
	v_cvt_pk_bf16_f32 v20, v22, v18
	v_cvt_pk_bf16_f32 v21, v19, v25
	v_cvt_pk_bf16_f32 v22, v26, v23
	v_cvt_pk_bf16_f32 v23, v24, v27
	s_waitcnt lgkmcnt(0)
	v_add_f32_e32 v18, v37, v28
	ds_bpermute_b32 v19, v116, v18
	v_lshl_add_u64 v[24:25], v[44:45], 1, s[20:21]
	global_store_dwordx4 v[24:25], v[20:23], off sc1
	s_and_saveexec_b64 s[8:9], vcc
	s_cbranch_execz .LBB0_1622
	v_lshl_add_u64 v[20:21], v[34:35], 2, s[18:19]
	s_waitcnt lgkmcnt(0)
	v_add_f32_e32 v18, v18, v19
	global_atomic_add_f32 v[20:21], v18, off
.LBB0_1622:
	s_or_b64 exec, exec, s[8:9]
	v_add_u32_e32 v18, 0xb0, v148
	s_waitcnt lgkmcnt(0)
	v_ashrrev_i32_e32 v19, 31, v18
	v_lshlrev_b64 v[28:29], 11, v[18:19]
	v_lshl_add_u64 v[30:31], v[28:29], 0, v[146:147]
	v_lshl_add_u64 v[24:25], v[30:31], 2, s[14:15]
	s_waitcnt vmcnt(8)
	v_mov_b32_e32 v20, v200
	v_mov_b32_e32 v21, v201
	v_mov_b32_e32 v22, v202
	v_mov_b32_e32 v23, v203
	s_nop 0
	v_mov_b32_e32 v24, v204
	v_mov_b32_e32 v25, v205
	v_mov_b32_e32 v26, v206
	v_mov_b32_e32 v27, v207
	v_lshl_add_u64 v[28:29], v[28:29], 0, v[150:151]
	v_lshl_add_u64 v[30:31], v[30:31], 1, s[20:21]
	v_lshl_add_u64 v[32:33], v[28:29], 2, s[14:15]
	v_add_f32_e32 v20, v14, v20
	v_add_f32_e32 v24, v10, v24
	v_add_f32_e32 v21, v15, v21
	v_add_f32_e32 v25, v11, v25
	v_add_f32_e32 v22, v16, v22
	v_add_f32_e32 v26, v12, v26
	v_add_f32_e32 v23, v17, v23
	v_add_f32_e32 v27, v13, v27
	v_cvt_pk_bf16_f32 v10, v20, v21
	v_cvt_pk_bf16_f32 v11, v22, v23
	v_cvt_pk_bf16_f32 v12, v24, v25
	v_cvt_pk_bf16_f32 v13, v26, v27
	global_store_dwordx4 v[30:31], v[10:13], off sc1
	s_waitcnt vmcnt(6)
	v_mov_b32_e32 v10, v208
	v_mov_b32_e32 v11, v209
	v_mov_b32_e32 v12, v210
	v_mov_b32_e32 v13, v211
	s_nop 0
	v_mov_b32_e32 v14, v212
	v_mov_b32_e32 v15, v213
	v_mov_b32_e32 v16, v214
	v_mov_b32_e32 v17, v215
	v_mul_f32_e32 v21, v21, v21
	v_fmac_f32_e32 v21, v20, v20
	v_fmac_f32_e32 v21, v22, v22
	v_fmac_f32_e32 v21, v23, v23
	v_fmac_f32_e32 v21, v24, v24
	v_fmac_f32_e32 v21, v25, v25
	v_fmac_f32_e32 v21, v26, v26
	v_fmac_f32_e32 v21, v27, v27
	v_add_f32_e32 v6, v6, v10
	v_add_f32_e32 v10, v2, v14
	v_add_f32_e32 v2, v7, v11
	v_fmac_f32_e32 v21, v6, v6
	v_add_f32_e32 v7, v3, v15
	v_add_f32_e32 v3, v8, v12
	v_fmac_f32_e32 v21, v2, v2
	v_add_f32_e32 v9, v9, v13
	v_fmac_f32_e32 v21, v3, v3
	v_fmac_f32_e32 v21, v9, v9
	v_fmac_f32_e32 v21, v10, v10
	v_add_f32_e32 v8, v4, v16
	v_fmac_f32_e32 v21, v7, v7
	v_add_f32_e32 v11, v5, v17
	v_fmac_f32_e32 v21, v8, v8
	v_fmac_f32_e32 v21, v11, v11
	ds_bpermute_b32 v12, v122, v21
	v_cvt_pk_bf16_f32 v4, v6, v2
	v_cvt_pk_bf16_f32 v5, v3, v9
	v_cvt_pk_bf16_f32 v6, v10, v7
	v_cvt_pk_bf16_f32 v7, v8, v11
	s_waitcnt lgkmcnt(0)
	v_add_f32_e32 v2, v21, v12
	ds_bpermute_b32 v3, v116, v2
	v_lshl_add_u64 v[8:9], v[28:29], 1, s[20:21]
	global_store_dwordx4 v[8:9], v[4:7], off sc1
	s_and_saveexec_b64 s[8:9], vcc
	s_cbranch_execz .LBB0_1624
	v_lshl_add_u64 v[4:5], v[18:19], 2, s[18:19]
	s_waitcnt lgkmcnt(0)
	v_add_f32_e32 v2, v2, v3
	global_atomic_add_f32 v[4:5], v2, off

;     __device__ __forceinline__ void operator()(const f32x4 (&acc)[2][2][4][2], const Unit& u, int wr, int wc, int fr, int fq) const {
;     ...
;             for (int m = 0; m < 4; ++m) { const int r = u.pm * BM + ai * HALF + wr * 64 + m * 16 + fr; const float rs = rsqrtf(sumsq[r] * (1.0f / D) + EPS);
; #pragma unroll
;                 for (int n = 0; n < 2; ++n)
; #pragma unroll
;                     for (int j = 0; j < 4; ++j) { gp[ai][m][4 * n + j] = acc[ai][0][m][n][j] * rs; up[ai][m][4 * n + j] = acc[ai][1][m][n][j] * rs; } }
;         if (fr >= 14) {
; #pragma unroll
;             for (int ai = 0; ai < 2; ++ai) { PG8_LAS float* hp = halo + ((wc * 4 + (2 * ai + wr)) * 2 + (fr - 14)) * 32 + 8 * fq;
;                 *(PG8_LAS f32x4*)hp = (f32x4){gp[ai][3][0], gp[ai][3][1], gp[ai][3][2], gp[ai][3][3]}; *(PG8_LAS f32x4*)(hp + 4) = (f32x4){gp[ai][3][4], gp[ai][3][5], gp[ai][3][6], gp[ai][3][7]}; }
;         }
;         asm volatile("s_waitcnt lgkmcnt(0)" ::: "memory"); __builtin_amdgcn_s_barrier(); asm volatile("" ::: "memory");
;         const int src1 = (lane & 48) | ((fr - 1) & 15), src2 = (lane & 48) | ((fr - 2) & 15);
; #pragma unroll
;         for (int ai = 0; ai < 2; ++ai) {
;             const int B = 2 * ai + wr;
;             float h62[8], h63[8];
;             if (B > 0) { const PG8_LAS float* hp = halo + ((wc * 4 + (B - 1)) * 2) * 32 + 8 * fq;
;                 const f32x4 a0 = *(const PG8_LAS f32x4*)hp, a1 = *(const PG8_LAS f32x4*)(hp + 4), b0 = *(const PG8_LAS f32x4*)(hp + 32), b1 = *(const PG8_LAS f32x4*)(hp + 36);
; #pragma unroll
;                 for (int j = 0; j < 4; ++j) { h62[j] = a0[j]; h62[4 + j] = a1[j]; h63[j] = b0[j]; h63[4 + j] = b1[j]; } }
;             else {
; #pragma unroll
;                 for (int j = 0; j < 8; ++j) { h62[j] = 0.f; h63[j] = 0.f; } }
;             float ps1[8], ps2[8];
; #pragma unroll
;             for (int j = 0; j < 8; ++j) { ps1[j] = h63[j]; ps2[j] = (fr == 0) ? h62[j] : h63[j]; }
; #pragma unroll
;             for (int m = 0; m < 4; ++m) {
;                 const int r = u.pm * BM + ai * HALF + wr * 64 + m * 16 + fr;
;                 float gate[8], a[8];
; #pragma unroll
;                 for (int j = 0; j < 8; ++j) {
;                     const float s1 = __shfl(gp[ai][m][j], src1), s2 = __shfl(gp[ai][m][j], src2);
;                     const float p1 = (fr >= 1) ? s1 : ps1[j], p2 = (fr >= 2) ? s2 : ps2[j];
.LBB0_1714:
	v_lshl_add_u32 v178, v178, 4, v214
	v_add_u32_e32 v193, -1, v214
	v_add_u32_e32 v195, 14, v214
	v_and_b32_e32 v178, 48, v178
	v_and_b32_e32 v193, 15, v193
	v_and_b32_e32 v195, 15, v195
	v_or3_b32 v193, v178, v193, v223
	v_or3_b32 v178, v178, v195, v223
	v_lshlrev_b32_e32 v195, 2, v178
	v_fmamk_f32 v178, v205, 0x3a000000, v222
	v_mul_f32_e32 v205, 0x4b800000, v178
	v_cmp_gt_f32_e32 vcc, s95, v178
	s_and_b32 s5, s16, 15
	v_lshlrev_b32_e32 v193, 2, v193
	v_cndmask_b32_e32 v178, v178, v205, vcc
	v_rsq_f32_e32 v178, v178
	s_cmp_eq_u32 s5, 0
	s_cselect_b64 s[76:77], -1, 0
	s_ashr_i32 s17, s16, 31
	v_mul_f32_e32 v205, 0x45800000, v178
	v_cndmask_b32_e32 v178, v178, v205, vcc
	v_mul_f32_e32 v150, v150, v178
	ds_bpermute_b32 v238, v193, v150
	s_lshl_b64 s[78:79], s[16:17], 1
	v_ashrrev_i32_e32 v215, 31, v214
	ds_bpermute_b32 v239, v195, v150
	v_lshl_add_u64 v[206:207], s[78:79], 0, v[214:215]
	v_mad_u64_u32 v[240:241], s[10:11], v206, s96, 0
	v_cmp_eq_u32_e64 s[14:15], 0, v214
	v_cmp_lt_i32_e64 s[10:11], 0, v214
	v_mul_f32_e32 v206, v151, v178
	v_mul_f32_e32 v226, v142, v178
	v_mul_f32_e32 v244, v144, v178
	s_waitcnt lgkmcnt(3)
	v_cndmask_b32_e64 v142, v158, v166, s[14:15]
	v_cndmask_b32_e64 v144, v159, v167, s[14:15]
	s_waitcnt lgkmcnt(1)
	v_cndmask_b32_e64 v151, v158, v238, s[10:11]
	v_cmp_lt_i32_e64 s[12:13], 1, v214
	v_mov_b32_e32 v166, v86
	v_mov_b32_e32 v167, v82
	v_mul_f32_e32 v242, v143, v178
	v_mul_f32_e32 v246, v145, v178
	s_waitcnt lgkmcnt(0)
	v_cndmask_b32_e64 v145, v142, v239, s[12:13]
	v_pk_mul_f32 v[142:143], v[166:167], v[150:151]
	ds_bpermute_b32 v236, v193, v206
	v_fma_f32 v143, v70, v145, v143
	v_add_f32_e32 v142, v142, v143
	v_mul_f32_e32 v143, 0xbfb8aa3b, v142
	v_exp_f32_e32 v143, v143
	ds_bpermute_b32 v237, v195, v206
	v_mul_f32_e32 v152, v152, v178
	ds_bpermute_b32 v234, v193, v152
	v_add_f32_e32 v143, 1.0, v143
	v_rcp_f32_e32 v143, v143
	v_mad_i32_i24 v241, v207, s96, v241
	s_waitcnt lgkmcnt(2)
	v_cndmask_b32_e64 v207, v159, v236, s[10:11]
	v_mov_b32_e32 v158, v87
	v_mov_b32_e32 v159, v83
	ds_bpermute_b32 v235, v195, v152
	v_mul_f32_e32 v151, v142, v143
	s_waitcnt lgkmcnt(2)
	v_cndmask_b32_e64 v143, v144, v237, s[12:13]
	v_pk_mul_f32 v[144:145], v[158:159], v[206:207]
	v_pk_mul_f32 v[146:147], v[146:147], v[178:179] op_sel_hi:[1,0]
	v_fma_f32 v143, v71, v143, v145
	v_add_f32_e32 v143, v144, v143
	v_mul_f32_e32 v208, v153, v178
	v_pk_mul_f32 v[148:149], v[148:149], v[178:179] op_sel_hi:[1,0]
	v_pk_mul_f32 v[138:139], v[138:139], v[178:179] op_sel_hi:[1,0]
	v_pk_mul_f32 v[140:141], v[140:141], v[178:179] op_sel_hi:[1,0]
	v_cndmask_b32_e64 v168, v160, v168, s[14:15]
	v_cndmask_b32_e64 v150, v161, v169, s[14:15]
	v_cndmask_b32_e64 v169, v154, v162, s[14:15]
	v_cndmask_b32_e64 v178, v155, v163, s[14:15]
	v_mul_f32_e32 v144, 0xbfb8aa3b, v143
	s_waitcnt lgkmcnt(1)
	v_cndmask_b32_e64 v153, v160, v234, s[10:11]
	v_mov_b32_e32 v162, v88
	v_mov_b32_e32 v163, v84
	v_cndmask_b32_e64 v205, v156, v164, s[14:15]
	v_exp_f32_e32 v164, v144
	s_waitcnt lgkmcnt(0)
	v_cndmask_b32_e64 v160, v168, v235, s[12:13]
	v_pk_mul_f32 v[144:145], v[162:163], v[152:153]
	v_mul_f32_e32 v249, v146, v151
	v_fma_f32 v145, v72, v160, v145
	v_add_f32_e32 v144, v144, v145
	v_mul_f32_e32 v145, 0xbfb8aa3b, v144
	v_exp_f32_e32 v145, v145
	v_add_f32_e32 v151, 1.0, v164
	ds_bpermute_b32 v232, v193, v208
	v_rcp_f32_e32 v151, v151
	v_add_f32_e32 v145, 1.0, v145
	ds_bpermute_b32 v233, v195, v208
	v_rcp_f32_e32 v145, v145
	ds_bpermute_b32 v230, v193, v226
	v_mul_f32_e32 v151, v143, v151
	s_waitcnt lgkmcnt(2)
	v_cndmask_b32_e64 v209, v161, v232, s[10:11]
	v_mov_b32_e32 v160, v89
	v_mov_b32_e32 v161, v85
	ds_bpermute_b32 v231, v195, v226
	v_mul_f32_e32 v250, v147, v151
	v_mul_f32_e32 v152, v144, v145
	s_waitcnt lgkmcnt(2)
	v_cndmask_b32_e64 v145, v150, v233, s[12:13]
	v_pk_mul_f32 v[150:151], v[160:161], v[208:209]
	v_cndmask_b32_e64 v248, v157, v165, s[14:15]
	v_fma_f32 v145, v73, v145, v151
	v_add_f32_e32 v145, v150, v145
	v_mul_f32_e32 v150, 0xbfb8aa3b, v145
	s_waitcnt lgkmcnt(1)
	v_cndmask_b32_e64 v227, v154, v230, s[10:11]
	v_mov_b32_e32 v164, v78
	v_mov_b32_e32 v165, v74
	v_exp_f32_e32 v153, v150
	s_waitcnt lgkmcnt(0)
	v_cndmask_b32_e64 v154, v169, v231, s[12:13]
	v_pk_mul_f32 v[150:151], v[164:165], v[226:227]
	v_mul_f32_e32 v208, v148, v152
	v_fma_f32 v151, v66, v154, v151
	v_add_f32_e32 v150, v150, v151
	v_mul_f32_e32 v151, 0xbfb8aa3b, v150
	v_exp_f32_e32 v151, v151
	v_add_f32_e32 v152, 1.0, v153
	ds_bpermute_b32 v227, v193, v242
	v_rcp_f32_e32 v152, v152
	v_add_f32_e32 v151, 1.0, v151
	ds_bpermute_b32 v228, v195, v242
	v_rcp_f32_e32 v151, v151
	v_mul_f32_e32 v152, v145, v152
	s_waitcnt lgkmcnt(1)
	v_cndmask_b32_e64 v243, v155, v227, s[10:11]
	v_mov_b32_e32 v154, v79
	v_mov_b32_e32 v155, v75
	v_mul_f32_e32 v209, v149, v152
	v_mul_f32_e32 v168, v150, v151
	s_waitcnt lgkmcnt(0)
	v_cndmask_b32_e64 v151, v178, v228, s[12:13]
	v_pk_mul_f32 v[152:153], v[154:155], v[242:243]
	ds_bpermute_b32 v225, v193, v244
	v_fma_f32 v151, v67, v151, v153
	v_add_f32_e32 v151, v152, v151
	v_mul_f32_e32 v152, 0xbfb8aa3b, v151
	v_exp_f32_e32 v152, v152
	ds_bpermute_b32 v226, v195, v244
	ds_bpermute_b32 v213, v193, v246
	v_mul_f32_e32 v178, v138, v168
	v_add_f32_e32 v152, 1.0, v152
	s_waitcnt lgkmcnt(2)
	v_cndmask_b32_e64 v245, v156, v225, s[10:11]
	v_mov_b32_e32 v168, v80
	v_mov_b32_e32 v169, v76
	ds_bpermute_b32 v215, v195, v246
	v_rcp_f32_e32 v242, v152
	s_waitcnt lgkmcnt(2)
	v_cndmask_b32_e64 v156, v205, v226, s[12:13]
	v_pk_mul_f32 v[152:153], v[168:169], v[244:245]
	s_waitcnt lgkmcnt(1)
	v_cndmask_b32_e64 v247, v157, v213, s[10:11]
	v_fma_f32 v153, v68, v156, v153
	v_add_f32_e32 v152, v152, v153
	v_mul_f32_e32 v153, 0xbfb8aa3b, v152
	v_mov_b32_e32 v156, v81
	v_mov_b32_e32 v157, v77
	v_exp_f32_e32 v205, v153
	s_waitcnt lgkmcnt(0)
	v_cndmask_b32_e64 v153, v248, v215, s[12:13]
	v_pk_mul_f32 v[206:207], v[156:157], v[246:247]
	v_add_f32_e32 v205, 1.0, v205
	v_fma_f32 v153, v69, v153, v207
	v_add_f32_e32 v153, v206, v153
	v_mul_f32_e32 v206, 0xbfb8aa3b, v153
	v_exp_f32_e32 v206, v206
	v_rcp_f32_e32 v205, v205
	v_mul_f32_e32 v207, v151, v242
	v_mul_f32_e32 v242, v139, v207
	v_add_f32_e32 v206, 1.0, v206
	v_rcp_f32_e32 v206, v206
	v_mul_f32_e32 v205, v152, v205
	v_mul_f32_e32 v205, v140, v205
	v_mul_f32_e32 v206, v153, v206
	v_mul_f32_e32 v243, v141, v206
	v_cvt_pk_bf16_f32 v206, v249, v250
	v_cvt_pk_bf16_f32 v207, v208, v209
	v_cvt_pk_bf16_f32 v208, v178, v242
	v_cvt_pk_bf16_f32 v209, v205, v243
	v_mov_b64_e32 v[242:243], s[44:45]
	v_mad_i64_i32 v[204:205], s[80:81], v204, s97, v[242:243]
	v_lshl_add_u64 v[204:205], v[190:191], 1, v[204:205]
	global_store_dwordx4 v[204:205], v[206:209], off sc1
	s_or_b64 s[80:81], s[64:65], s[12:13]
	s_nor_b64 vcc, s[80:81], s[76:77]
	v_lshlrev_b64 v[208:209], 2, v[240:241]
	v_lshlrev_b64 v[204:205], 2, v[190:191]
	v_lshl_add_u64 v[206:207], s[50:51], 0, v[208:209]
	v_lshl_add_u64 v[208:209], s[48:49], 0, v[208:209]
	s_and_saveexec_b64 s[80:81], vcc
	s_cbranch_execz .LBB0_1716
; __device__ __forceinline__ float silu_f(float x) { return x * __builtin_amdgcn_rcpf(1.0f + __expf(-x)); }
;     __device__ __forceinline__ void operator()(const f32x4 (&acc)[2][2][4][2], const Unit& u, int wr, int wc, int fr, int fq) const {
;     ...
;             for (int m = 0; m < 4; ++m) {
;                 const int r = u.pm * BM + ai * HALF + wr * 64 + m * 16 + fr;
;                 float gate[8], a[8];
; #pragma unroll
;                 for (int j = 0; j < 8; ++j) {
;                     const float s1 = __shfl(gp[ai][m][j], src1), s2 = __shfl(gp[ai][m][j], src2);
;                     const float p1 = (fr >= 1) ? s1 : ps1[j], p2 = (fr >= 2) ? s2 : ps2[j];
;                     ps1[j] = s1; ps2[j] = s2;
;                     gate[j] = w0[j] * p2 + w1[j] * p1 + w2[j] * gp[ai][m][j];
;                     a[j] = silu_f(gate[j]) * up[ai][m][j];
;     ...
;                 if (B == 0 && m == 0 && fr < 2 && (u.pm & 15) != 0) {
;                     float* fg = FIXG + ((size_t)u.pm * 2 + fr) * DFF + cg; float* fu = FIXU + ((size_t)u.pm * 2 + fr) * DFF + cg;
;                     *(f32x4*)fg = (f32x4){gate[0], gate[1], gate[2], gate[3]}; *(f32x4*)(fg + 4) = (f32x4){gate[4], gate[5], gate[6], gate[7]};
;                     *(f32x4*)fu = (f32x4){up[ai][m][0], up[ai][m][1], up[ai][m][2], up[ai][m][3]}; *(f32x4*)(fu + 4) = (f32x4){up[ai][m][4], up[ai][m][5], up[ai][m][6], up[ai][m][7]};
	v_lshl_add_u64 v[242:243], v[208:209], 0, v[204:205]
	v_lshl_add_u64 v[240:241], v[206:207], 0, v[204:205]
	global_store_dwordx4 v[242:243], v[142:145], off sc1
	global_store_dwordx4 v[242:243], v[150:153], off offset:16 sc1
	global_store_dwordx4 v[240:241], v[146:149], off sc1
	global_store_dwordx4 v[240:241], v[138:141], off offset:16 sc1
.LBB0_1716:
	s_or_b64 exec, exec, s[80:81]
	v_add_u32_e32 v178, -14, v214
	v_lshl_add_u64 v[138:139], s[78:79], 0, v[178:179]
	v_mad_u64_u32 v[140:141], s[78:79], v138, s22, 0
	s_cmp_eq_u32 s5, 15
	s_cselect_b64 s[78:79], -1, 0
	s_ashr_i32 s16, s16, 4
	s_ashr_i32 s17, s16, 31
	v_lshl_add_u64 v[142:143], s[16:17], 1, v[178:179]
	v_mad_i32_i24 v141, v139, s22, v141
	v_mad_u64_u32 v[138:139], s[16:17], v142, s22, 0
	v_fmamk_f32 v142, v229, 0x3a000000, v222
	v_mad_i32_i24 v139, v143, s22, v139
	v_cmp_gt_f32_e32 vcc, s95, v142
	v_mul_f32_e32 v143, 0x4b800000, v142
	v_mul_f32_e32 v105, v105, v216
	v_cndmask_b32_e32 v142, v142, v143, vcc
	v_rsq_f32_e32 v142, v142
	s_and_b64 s[80:81], s[62:63], s[8:9]
	v_mul_f32_e32 v143, 0x45800000, v142
	v_cndmask_b32_e32 v142, v142, v143, vcc
	v_mul_f32_e32 v150, v122, v142
	v_fmamk_f32 v122, v224, 0x3a000000, v222
	v_mul_f32_e32 v147, v130, v142
	v_mul_f32_e32 v130, v127, v142
	v_mul_f32_e32 v127, v123, v142
	v_cmp_gt_f32_e32 vcc, s95, v122
	v_mul_f32_e32 v123, 0x4b800000, v122
	v_mul_f32_e32 v144, v134, v142
	v_cndmask_b32_e32 v122, v122, v123, vcc
	v_rsq_f32_e32 v122, v122
	v_mul_f32_e32 v146, v135, v142
	v_mul_f32_e32 v148, v136, v142
	v_mul_f32_e32 v135, v132, v142
	v_mul_f32_e32 v123, 0x45800000, v122
	v_mul_f32_e32 v132, v126, v142
	v_mul_f32_e32 v126, v129, v142
	v_cndmask_b32_e32 v129, v122, v123, vcc
	v_mul_f32_e32 v136, v102, v216
	v_mul_f32_e32 v102, v100, v216
	v_mul_f32_e32 v100, v101, v216
	ds_bpermute_b32 v101, v193, v144
	v_mul_f32_e32 v134, v137, v142
	v_mul_f32_e32 v137, v109, v129
	ds_bpermute_b32 v109, v195, v144
	v_mul_f32_e32 v131, v131, v142
	s_waitcnt lgkmcnt(1)
	v_cndmask_b32_e64 v145, v238, v101, s[10:11]
	v_mul_f32_e32 v133, v133, v142
	v_mul_f32_e32 v128, v128, v142
	v_mul_f32_e32 v151, v124, v142
	v_mul_f32_e32 v125, v125, v142
	v_mul_f32_e32 v122, v119, v129
	v_mul_f32_e32 v143, v115, v129
	v_mul_f32_e32 v119, v116, v129
	v_mul_f32_e32 v116, v110, v129
	v_mul_f32_e32 v115, v106, v129
	v_mul_f32_e32 v110, v112, v129
	v_mul_f32_e32 v142, v108, v129
	v_mul_f32_e32 v108, v113, v129
	v_mul_f32_e32 v113, v103, v216
	v_mul_f32_e32 v112, v104, v216
	v_mul_f32_e32 v104, v98, v216
	v_mul_f32_e32 v103, v99, v216
	s_waitcnt lgkmcnt(0)
	v_cndmask_b32_e64 v106, v239, v109, s[12:13]
	v_pk_mul_f32 v[98:99], v[166:167], v[144:145]
	v_mul_f32_e32 v124, v118, v129
	v_fma_f32 v99, v70, v106, v99
	v_add_f32_e32 v98, v98, v99
	v_mul_f32_e32 v99, 0xbfb8aa3b, v98
	v_exp_f32_e32 v99, v99
	v_mul_f32_e32 v118, v121, v129
	ds_bpermute_b32 v121, v193, v146
	ds_bpermute_b32 v144, v195, v146
	v_add_f32_e32 v99, 1.0, v99
	v_rcp_f32_e32 v99, v99
	v_mul_f32_e32 v123, v114, v129
	v_mul_f32_e32 v114, v111, v129
	v_mul_f32_e32 v111, v107, v129
	v_mul_f32_e32 v98, v98, v99
	v_mul_f32_e32 v106, v147, v98
	s_waitcnt lgkmcnt(1)
	v_cndmask_b32_e64 v147, v236, v121, s[10:11]
	s_waitcnt lgkmcnt(0)
	v_cndmask_b32_e64 v107, v237, v144, s[12:13]
	v_pk_mul_f32 v[98:99], v[158:159], v[146:147]
	ds_bpermute_b32 v145, v193, v148
	v_fma_f32 v99, v71, v107, v99
	v_add_f32_e32 v98, v98, v99
	v_mul_f32_e32 v99, 0xbfb8aa3b, v98
	v_exp_f32_e32 v99, v99
	ds_bpermute_b32 v146, v195, v148
	s_waitcnt lgkmcnt(1)
	v_cndmask_b32_e64 v149, v234, v145, s[10:11]
	v_mul_f32_e32 v120, v120, v129
	v_add_f32_e32 v99, 1.0, v99
	v_rcp_f32_e32 v99, v99
	v_mul_f32_e32 v117, v117, v129
	s_waitcnt lgkmcnt(0)
	v_cndmask_b32_e64 v129, v235, v146, s[12:13]
	ds_bpermute_b32 v152, v195, v132
	v_mul_f32_e32 v98, v98, v99
	v_mul_f32_e32 v107, v131, v98
	v_pk_mul_f32 v[98:99], v[162:163], v[148:149]
	ds_bpermute_b32 v148, v193, v134
	v_fma_f32 v99, v72, v129, v99
	v_add_f32_e32 v98, v98, v99
	v_mul_f32_e32 v99, 0xbfb8aa3b, v98
	v_exp_f32_e32 v99, v99
	ds_bpermute_b32 v149, v195, v134
	ds_bpermute_b32 v153, v193, v128
	ds_bpermute_b32 v178, v195, v128
	v_add_f32_e32 v99, 1.0, v99
	v_rcp_f32_e32 v99, v99
	s_waitcnt lgkmcnt(2)
	v_cndmask_b32_e64 v129, v233, v149, s[12:13]
	ds_bpermute_b32 v214, v195, v126
	v_mul_f32_e32 v98, v98, v99
	v_mul_f32_e32 v147, v135, v98
	v_cndmask_b32_e64 v135, v232, v148, s[10:11]
	v_pk_mul_f32 v[98:99], v[160:161], v[134:135]
	ds_bpermute_b32 v135, v193, v132
	v_fma_f32 v99, v73, v129, v99
	v_add_f32_e32 v98, v98, v99
	v_mul_f32_e32 v99, 0xbfb8aa3b, v98
	v_exp_f32_e32 v99, v99
	v_cndmask_b32_e64 v129, v231, v152, s[12:13]
	v_add_f32_e32 v99, 1.0, v99
	v_rcp_f32_e32 v99, v99
	s_nop 0
	v_mul_f32_e32 v98, v98, v99
	v_mul_f32_e32 v134, v133, v98
	s_waitcnt lgkmcnt(0)
	v_cndmask_b32_e64 v133, v230, v135, s[10:11]
	v_pk_mul_f32 v[98:99], v[164:165], v[132:133]
	ds_bpermute_b32 v133, v193, v130
	v_fma_f32 v99, v66, v129, v99
	v_add_f32_e32 v98, v98, v99
	v_mul_f32_e32 v99, 0xbfb8aa3b, v98
	v_exp_f32_e32 v99, v99
	s_waitcnt lgkmcnt(0)
	v_cndmask_b32_e64 v131, v227, v133, s[10:11]
	v_add_f32_e32 v99, 1.0, v99
	v_rcp_f32_e32 v99, v99
	s_nop 0
	v_mul_f32_e32 v98, v98, v99
	v_mul_f32_e32 v132, v150, v98
	ds_bpermute_b32 v150, v195, v130
	v_pk_mul_f32 v[98:99], v[154:155], v[130:131]
	s_waitcnt lgkmcnt(0)
; __device__ __forceinline__ unsigned cvt_pk_bf16(float lo, float hi) { unsigned r; asm volatile("v_cvt_pk_bf16_f32 %0, %1, %2" : "=v"(r) : "v"(lo), "v"(hi)); return r; }
; __device__ __forceinline__ float silu_f(float x) { return x * __builtin_amdgcn_rcpf(1.0f + __expf(-x)); }
;     __device__ __forceinline__ void operator()(const f32x4 (&acc)[2][2][4][2], const Unit& u, int wr, int wc, int fr, int fq) const {
;     ...
;             for (int m = 0; m < 4; ++m) {
;                 const int r = u.pm * BM + ai * HALF + wr * 64 + m * 16 + fr;
;                 float gate[8], a[8];
; #pragma unroll
;                 for (int j = 0; j < 8; ++j) {
;                     const float s1 = __shfl(gp[ai][m][j], src1), s2 = __shfl(gp[ai][m][j], src2);
;                     const float p1 = (fr >= 1) ? s1 : ps1[j], p2 = (fr >= 2) ? s2 : ps2[j];
;                     ps1[j] = s1; ps2[j] = s2;
;                     gate[j] = w0[j] * p2 + w1[j] * p1 + w2[j] * gp[ai][m][j];
;                     a[j] = silu_f(gate[j]) * up[ai][m][j];
;                 }
;                 u32x4 w; w.x = cvt_pk_bf16(a[0], a[1]); w.y = cvt_pk_bf16(a[2], a[3]); w.z = cvt_pk_bf16(a[4], a[5]); w.w = cvt_pk_bf16(a[6], a[7]);
;                 *(u32x4*)(ACT + (size_t)r * DFF + cg) = w;
	v_cndmask_b32_e64 v129, v228, v150, s[12:13]
	v_fma_f32 v99, v67, v129, v99
	v_add_f32_e32 v98, v98, v99
	v_mul_f32_e32 v99, 0xbfb8aa3b, v98
	v_exp_f32_e32 v99, v99
	v_cndmask_b32_e64 v129, v225, v153, s[10:11]
	v_add_f32_e32 v99, 1.0, v99
	v_rcp_f32_e32 v99, v99
	s_nop 0
	v_mul_f32_e32 v98, v98, v99
	v_mul_f32_e32 v130, v127, v98
	v_cndmask_b32_e64 v127, v226, v178, s[12:13]
	v_pk_mul_f32 v[98:99], v[168:169], v[128:129]
	v_cndmask_b32_e64 v128, v215, v214, s[12:13]
	v_fma_f32 v99, v68, v127, v99
	v_add_f32_e32 v98, v98, v99
	v_mul_f32_e32 v99, 0xbfb8aa3b, v98
	v_exp_f32_e32 v99, v99
	s_nop 0
	v_add_f32_e32 v99, 1.0, v99
	v_rcp_f32_e32 v99, v99
	s_nop 0
	v_mul_f32_e32 v98, v98, v99
	v_mul_f32_e32 v129, v151, v98
	ds_bpermute_b32 v151, v193, v126
	s_waitcnt lgkmcnt(0)
	v_cndmask_b32_e64 v127, v213, v151, s[10:11]
	v_pk_mul_f32 v[98:99], v[156:157], v[126:127]
	v_cvt_pk_bf16_f32 v126, v106, v107
	v_cvt_pk_bf16_f32 v127, v147, v134
	v_lshlrev_b64 v[106:107], 1, v[190:191]
	v_fma_f32 v99, v69, v128, v99
	v_add_f32_e32 v98, v98, v99
	v_mul_f32_e32 v99, 0xbfb8aa3b, v98
	v_exp_f32_e32 v99, v99
	v_cvt_pk_bf16_f32 v128, v132, v130
	ds_bpermute_b32 v132, v193, v110
	ds_bpermute_b32 v134, v193, v108
	v_add_f32_e32 v99, 1.0, v99
	v_rcp_f32_e32 v99, v99
	s_nop 0
	v_mul_f32_e32 v98, v98, v99
	v_mul_f32_e32 v98, v125, v98
	v_cvt_pk_bf16_f32 v129, v129, v98
	v_mov_b64_e32 v[98:99], s[44:45]
	v_mad_i64_i32 v[130:131], s[16:17], v212, s97, v[98:99]
	v_lshl_add_u64 v[130:131], v[130:131], 0, v[106:107]
	global_store_dwordx4 v[130:131], v[126:129], off sc1
	ds_bpermute_b32 v126, v193, v124
	ds_bpermute_b32 v127, v195, v124
	ds_bpermute_b32 v128, v195, v120
	ds_bpermute_b32 v129, v195, v118
	ds_bpermute_b32 v130, v195, v116
	s_waitcnt lgkmcnt(4)
	v_cndmask_b32_e64 v125, v101, v126, s[10:11]
	s_waitcnt lgkmcnt(3)
	v_cndmask_b32_e64 v101, v109, v127, s[12:13]
	v_pk_mul_f32 v[124:125], v[166:167], v[124:125]
	ds_bpermute_b32 v131, v195, v114
	v_fma_f32 v101, v70, v101, v125
	v_add_f32_e32 v101, v124, v101
	v_mul_f32_e32 v109, 0xbfb8aa3b, v101
	v_exp_f32_e32 v109, v109
	ds_bpermute_b32 v124, v193, v122
	ds_bpermute_b32 v125, v195, v122
	v_add_f32_e32 v109, 1.0, v109
	v_rcp_f32_e32 v109, v109
	s_nop 0
	v_mul_f32_e32 v101, v101, v109
	v_mul_f32_e32 v101, v123, v101
	s_waitcnt lgkmcnt(1)
	v_cndmask_b32_e64 v123, v121, v124, s[10:11]
	s_waitcnt lgkmcnt(0)
	v_cndmask_b32_e64 v109, v144, v125, s[12:13]
	v_pk_mul_f32 v[122:123], v[158:159], v[122:123]
	s_nop 0
	v_fma_f32 v109, v71, v109, v123
	v_add_f32_e32 v109, v122, v109
	v_mul_f32_e32 v121, 0xbfb8aa3b, v109
	v_exp_f32_e32 v121, v121
	ds_bpermute_b32 v123, v193, v120
	v_add_f32_e32 v121, 1.0, v121
	v_rcp_f32_e32 v121, v121
	s_nop 0
	v_mul_f32_e32 v109, v109, v121
	s_waitcnt lgkmcnt(0)
	v_cndmask_b32_e64 v121, v145, v123, s[10:11]
	v_mul_f32_e32 v122, v143, v109
	v_cndmask_b32_e64 v109, v146, v128, s[12:13]
	v_pk_mul_f32 v[120:121], v[162:163], v[120:121]
	s_nop 0
	v_fma_f32 v109, v72, v109, v121
	v_add_f32_e32 v109, v120, v109
	v_mul_f32_e32 v120, 0xbfb8aa3b, v109
	v_exp_f32_e32 v120, v120
	ds_bpermute_b32 v121, v193, v118
	v_add_f32_e32 v120, 1.0, v120
	v_rcp_f32_e32 v120, v120
	s_nop 0
	v_mul_f32_e32 v109, v109, v120
	v_mul_f32_e32 v120, v119, v109
	s_waitcnt lgkmcnt(0)
	v_cndmask_b32_e64 v119, v148, v121, s[10:11]
	v_cndmask_b32_e64 v109, v149, v129, s[12:13]
	v_pk_mul_f32 v[118:119], v[160:161], v[118:119]
	s_nop 0
	v_fma_f32 v109, v73, v109, v119
	v_add_f32_e32 v109, v118, v109
	v_mul_f32_e32 v118, 0xbfb8aa3b, v109
	v_exp_f32_e32 v118, v118
	ds_bpermute_b32 v119, v193, v116
	v_add_f32_e32 v118, 1.0, v118
	v_rcp_f32_e32 v118, v118
	s_nop 0
	v_mul_f32_e32 v109, v109, v118
	v_mul_f32_e32 v118, v117, v109
	s_waitcnt lgkmcnt(0)
	v_cndmask_b32_e64 v117, v135, v119, s[10:11]
	v_cndmask_b32_e64 v109, v152, v130, s[12:13]
	v_pk_mul_f32 v[116:117], v[164:165], v[116:117]
	ds_bpermute_b32 v135, v195, v108
	v_fma_f32 v109, v66, v109, v117
	v_add_f32_e32 v109, v116, v109
	v_mul_f32_e32 v116, 0xbfb8aa3b, v109
	v_exp_f32_e32 v116, v116
	ds_bpermute_b32 v117, v193, v114
	v_add_f32_e32 v116, 1.0, v116
	v_rcp_f32_e32 v116, v116
	s_nop 0
	v_mul_f32_e32 v109, v109, v116
	v_mul_f32_e32 v116, v115, v109
	s_waitcnt lgkmcnt(0)
	v_cndmask_b32_e64 v115, v133, v117, s[10:11]
	v_cndmask_b32_e64 v109, v150, v131, s[12:13]
	v_pk_mul_f32 v[114:115], v[154:155], v[114:115]
	ds_bpermute_b32 v133, v195, v110
	v_fma_f32 v109, v67, v109, v115
	v_add_f32_e32 v109, v114, v109
	v_mul_f32_e32 v114, 0xbfb8aa3b, v109
	v_exp_f32_e32 v114, v114
	s_nop 0
	v_add_f32_e32 v114, 1.0, v114
	v_rcp_f32_e32 v114, v114
	s_nop 0
	v_mul_f32_e32 v109, v109, v114
	v_mul_f32_e32 v114, v111, v109
	v_cndmask_b32_e64 v111, v153, v132, s[10:11]
	s_waitcnt lgkmcnt(0)
	v_cndmask_b32_e64 v109, v178, v133, s[12:13]
	v_pk_mul_f32 v[110:111], v[168:169], v[110:111]
	s_nop 0
	v_fma_f32 v109, v68, v109, v111
	v_add_f32_e32 v109, v110, v109
	v_mul_f32_e32 v110, 0xbfb8aa3b, v109
	v_exp_f32_e32 v110, v110
	s_nop 0
	v_add_f32_e32 v110, 1.0, v110
	v_rcp_f32_e32 v110, v110
	s_nop 0
	v_mul_f32_e32 v109, v109, v110
	v_mul_f32_e32 v111, v142, v109
	v_cndmask_b32_e64 v109, v151, v134, s[10:11]
	v_cndmask_b32_e64 v110, v214, v135, s[12:13]
	v_pk_mul_f32 v[108:109], v[156:157], v[108:109]
	s_nop 0
	v_fma_f32 v109, v69, v110, v109
	v_add_f32_e32 v108, v108, v109
	v_mul_f32_e32 v109, 0xbfb8aa3b, v108
	v_exp_f32_e32 v109, v109
	s_nop 0
	v_add_f32_e32 v109, 1.0, v109
	v_rcp_f32_e32 v109, v109
	s_nop 0
	v_mul_f32_e32 v108, v108, v109
	v_mul_f32_e32 v115, v137, v108
	v_cvt_pk_bf16_f32 v108, v101, v122
	v_cvt_pk_bf16_f32 v109, v120, v118
	v_cvt_pk_bf16_f32 v110, v116, v114
	v_cvt_pk_bf16_f32 v111, v111, v115
	v_mad_i64_i32 v[114:115], s[16:17], v210, s97, v[98:99]
	v_lshl_add_u64 v[114:115], v[114:115], 0, v[106:107]
	global_store_dwordx4 v[114:115], v[108:111], off sc1
	ds_bpermute_b32 v101, v193, v90
	ds_bpermute_b32 v108, v195, v90
	ds_bpermute_b32 v110, v195, v91
	ds_bpermute_b32 v111, v195, v92
	v_mad_i64_i32 v[98:99], s[16:17], v202, s97, v[98:99]
	s_waitcnt lgkmcnt(3)
; __device__ __forceinline__ unsigned cvt_pk_bf16(float lo, float hi) { unsigned r; asm volatile("v_cvt_pk_bf16_f32 %0, %1, %2" : "=v"(r) : "v"(lo), "v"(hi)); return r; }
;     __device__ __forceinline__ void operator()(const f32x4 (&acc)[2][2][4][2], const Unit& u, int wr, int wc, int fr, int fq) const {
;     ...
;             for (int m = 0; m < 4; ++m) {
;                 const int r = u.pm * BM + ai * HALF + wr * 64 + m * 16 + fr;
;                 float gate[8], a[8];
; #pragma unroll
;                 for (int j = 0; j < 8; ++j) {
;                     const float s1 = __shfl(gp[ai][m][j], src1), s2 = __shfl(gp[ai][m][j], src2);
;                     const float p1 = (fr >= 1) ? s1 : ps1[j], p2 = (fr >= 2) ? s2 : ps2[j];
;                     ps1[j] = s1; ps2[j] = s2;
;                     gate[j] = w0[j] * p2 + w1[j] * p1 + w2[j] * gp[ai][m][j];
;                     a[j] = silu_f(gate[j]) * up[ai][m][j];
;                 }
;                 u32x4 w; w.x = cvt_pk_bf16(a[0], a[1]); w.y = cvt_pk_bf16(a[2], a[3]); w.z = cvt_pk_bf16(a[4], a[5]); w.w = cvt_pk_bf16(a[6], a[7]);
;                 *(u32x4*)(ACT + (size_t)r * DFF + cg) = w;
;                 if (B == 0 && m == 0 && fr < 2 && (u.pm & 15) != 0) {
;                     float* fg = FIXG + ((size_t)u.pm * 2 + fr) * DFF + cg; float* fu = FIXU + ((size_t)u.pm * 2 + fr) * DFF + cg;
;                     *(f32x4*)fg = (f32x4){gate[0], gate[1], gate[2], gate[3]}; *(f32x4*)(fg + 4) = (f32x4){gate[4], gate[5], gate[6], gate[7]};
;                     *(f32x4*)fu = (f32x4){up[ai][m][0], up[ai][m][1], up[ai][m][2], up[ai][m][3]}; *(f32x4*)(fu + 4) = (f32x4){up[ai][m][4], up[ai][m][5], up[ai][m][6], up[ai][m][7]};
;                 }
;                 if (B == 3 && m == 3 && fr >= 14) {
;                     float* tp = TAIL + ((size_t)u.pm * 2 + (fr - 14)) * DFF + cg;
;                     *(f32x4*)tp = (f32x4){gp[ai][m][0], gp[ai][m][1], gp[ai][m][2], gp[ai][m][3]}; *(f32x4*)(tp + 4) = (f32x4){gp[ai][m][4], gp[ai][m][5], gp[ai][m][6], gp[ai][m][7]};
;                     if ((u.pm & 15) == 15) { float* op = outFconv + ((size_t)(u.pm >> 4) * 2 + (fr - 14)) * DFF + cg;
;                         *(f32x4*)op = (f32x4){gp[ai][m][0], gp[ai][m][1], gp[ai][m][2], gp[ai][m][3]}; *(f32x4*)(op + 4) = (f32x4){gp[ai][m][4], gp[ai][m][5], gp[ai][m][6], gp[ai][m][7]}; }
	v_cndmask_b32_e64 v109, v126, v101, s[10:11]
	s_waitcnt lgkmcnt(2)
	v_cndmask_b32_e64 v101, v127, v108, s[12:13]
	v_mov_b32_e32 v108, v90
	v_pk_mul_f32 v[108:109], v[166:167], v[108:109]
	s_waitcnt lgkmcnt(1)
	v_cndmask_b32_e64 v110, v125, v110, s[12:13]
	v_fma_f32 v101, v70, v101, v109
	v_add_f32_e32 v101, v108, v101
	v_mul_f32_e32 v108, 0xbfb8aa3b, v101
	v_exp_f32_e32 v108, v108
	s_waitcnt lgkmcnt(0)
	v_cndmask_b32_e64 v111, v128, v111, s[12:13]
	v_lshl_add_u64 v[98:99], v[98:99], 0, v[106:107]
	v_add_f32_e32 v108, 1.0, v108
	v_rcp_f32_e32 v108, v108
	s_nop 0
	v_mul_f32_e32 v101, v101, v108
	ds_bpermute_b32 v108, v193, v91
	v_mul_f32_e32 v101, v136, v101
	s_waitcnt lgkmcnt(0)
	v_cndmask_b32_e64 v109, v124, v108, s[10:11]
	v_mov_b32_e32 v108, v91
	v_pk_mul_f32 v[108:109], v[158:159], v[108:109]
	s_nop 0
	v_fma_f32 v109, v71, v110, v109
	v_add_f32_e32 v108, v108, v109
	v_mul_f32_e32 v109, 0xbfb8aa3b, v108
	v_exp_f32_e32 v109, v109
	s_nop 0
	v_add_f32_e32 v109, 1.0, v109
	v_rcp_f32_e32 v109, v109
	s_nop 0
	v_mul_f32_e32 v108, v108, v109
	v_mul_f32_e32 v110, v113, v108
	ds_bpermute_b32 v108, v193, v92
	s_waitcnt lgkmcnt(0)
	v_cndmask_b32_e64 v109, v123, v108, s[10:11]
	v_mov_b32_e32 v108, v92
	v_pk_mul_f32 v[108:109], v[162:163], v[108:109]
	s_nop 0
	v_fma_f32 v109, v72, v111, v109
	v_add_f32_e32 v108, v108, v109
	v_mul_f32_e32 v109, 0xbfb8aa3b, v108
	v_exp_f32_e32 v109, v109
	s_nop 0
	v_add_f32_e32 v109, 1.0, v109
	v_rcp_f32_e32 v109, v109
	s_nop 0
	v_mul_f32_e32 v108, v108, v109
	v_mul_f32_e32 v111, v112, v108
	ds_bpermute_b32 v108, v193, v93
	ds_bpermute_b32 v112, v195, v93
	s_waitcnt lgkmcnt(1)
	v_cndmask_b32_e64 v109, v121, v108, s[10:11]
	v_mov_b32_e32 v108, v93
	s_waitcnt lgkmcnt(0)
	v_cndmask_b32_e64 v112, v129, v112, s[12:13]
	v_pk_mul_f32 v[108:109], v[160:161], v[108:109]
	s_nop 0
	v_fma_f32 v109, v73, v112, v109
	v_add_f32_e32 v108, v108, v109
	v_mul_f32_e32 v109, 0xbfb8aa3b, v108
	v_exp_f32_e32 v109, v109
	s_nop 0
	v_add_f32_e32 v109, 1.0, v109
	v_rcp_f32_e32 v109, v109
	s_nop 0
	v_mul_f32_e32 v108, v108, v109
	v_mul_f32_e32 v112, v105, v108
	ds_bpermute_b32 v105, v193, v94
	ds_bpermute_b32 v108, v195, v94
	s_waitcnt lgkmcnt(1)
	v_cndmask_b32_e64 v109, v119, v105, s[10:11]
	s_waitcnt lgkmcnt(0)
	v_cndmask_b32_e64 v105, v130, v108, s[12:13]
	v_mov_b32_e32 v108, v94
	v_pk_mul_f32 v[108:109], v[164:165], v[108:109]
	s_nop 0
	v_fma_f32 v105, v66, v105, v109
	v_add_f32_e32 v105, v108, v105
	v_mul_f32_e32 v108, 0xbfb8aa3b, v105
	v_exp_f32_e32 v108, v108
	ds_bpermute_b32 v109, v195, v95
	v_add_f32_e32 v108, 1.0, v108
	v_rcp_f32_e32 v108, v108
	s_waitcnt lgkmcnt(0)
	v_cndmask_b32_e64 v109, v131, v109, s[12:13]
	v_mul_f32_e32 v105, v105, v108
	v_mul_f32_e32 v108, v104, v105
	ds_bpermute_b32 v104, v193, v95
	s_waitcnt lgkmcnt(0)
	v_cndmask_b32_e64 v105, v117, v104, s[10:11]
	v_mov_b32_e32 v104, v95
	v_pk_mul_f32 v[104:105], v[154:155], v[104:105]
	s_nop 0
	v_fma_f32 v105, v67, v109, v105
	v_add_f32_e32 v104, v104, v105
	v_mul_f32_e32 v105, 0xbfb8aa3b, v104
	v_exp_f32_e32 v105, v105
	s_nop 0
	v_add_f32_e32 v105, 1.0, v105
	v_rcp_f32_e32 v105, v105
	s_nop 0
	v_mul_f32_e32 v104, v104, v105
	v_mul_f32_e32 v109, v103, v104
	ds_bpermute_b32 v103, v193, v96
	ds_bpermute_b32 v104, v195, v96
	s_waitcnt lgkmcnt(1)
	v_cndmask_b32_e64 v105, v132, v103, s[10:11]
	s_waitcnt lgkmcnt(0)
	v_cndmask_b32_e64 v103, v133, v104, s[12:13]
	v_mov_b32_e32 v104, v96
	v_pk_mul_f32 v[104:105], v[168:169], v[104:105]
	s_nop 0
	v_fma_f32 v103, v68, v103, v105
	v_add_f32_e32 v103, v104, v103
	v_mul_f32_e32 v104, 0xbfb8aa3b, v103
	v_exp_f32_e32 v104, v104
	ds_bpermute_b32 v105, v195, v97
	v_add_f32_e32 v104, 1.0, v104
	v_rcp_f32_e32 v104, v104
	s_waitcnt lgkmcnt(0)
	v_cndmask_b32_e64 v105, v135, v105, s[12:13]
	v_mul_f32_e32 v103, v103, v104
	v_mul_f32_e32 v104, v102, v103
	ds_bpermute_b32 v102, v193, v97
	s_waitcnt lgkmcnt(0)
	v_cndmask_b32_e64 v103, v134, v102, s[10:11]
	v_mov_b32_e32 v102, v97
	v_pk_mul_f32 v[102:103], v[156:157], v[102:103]
	s_nop 0
	v_fma_f32 v103, v69, v105, v103
	v_add_f32_e32 v102, v102, v103
	v_mul_f32_e32 v103, 0xbfb8aa3b, v102
	v_exp_f32_e32 v103, v103
	s_nop 0
	v_add_f32_e32 v103, 1.0, v103
	v_rcp_f32_e32 v103, v103
	s_nop 0
	v_mul_f32_e32 v102, v102, v103
	v_mul_f32_e32 v103, v100, v102
	v_cvt_pk_bf16_f32 v100, v101, v110
	v_cvt_pk_bf16_f32 v101, v111, v112
	v_cvt_pk_bf16_f32 v102, v108, v109
	v_cvt_pk_bf16_f32 v103, v104, v103
	global_store_dwordx4 v[98:99], v[100:103], off sc1
	v_lshl_add_u64 v[98:99], s[46:47], 0, v[140:141]
	v_lshl_add_u64 v[108:109], v[190:191], 2, v[98:99]
	v_cndmask_b32_e64 v100, 0, 1, s[78:79]
	v_cmp_ne_u32_e64 s[16:17], 1, v100
	s_and_saveexec_b64 s[78:79], s[80:81]
	s_cbranch_execz .LBB0_1719
	s_and_b64 vcc, exec, s[16:17]
	global_store_dwordx4 v[108:109], v[90:93], off sc1
	global_store_dwordx4 v[108:109], v[94:97], off offset:16 sc1
	s_cbranch_vccnz .LBB0_1719
	v_lshl_add_u64 v[98:99], s[52:53], 0, v[138:139]
	v_lshl_add_u64 v[98:99], v[190:191], 2, v[98:99]
	global_store_dwordx4 v[98:99], v[90:93], off sc1
	global_store_dwordx4 v[98:99], v[94:97], off offset:16 sc1

; __device__ __forceinline__ unsigned cvt_pk_bf16(float lo, float hi) { unsigned r; asm volatile("v_cvt_pk_bf16_f32 %0, %1, %2" : "=v"(r) : "v"(lo), "v"(hi)); return r; }
; __device__ __forceinline__ float silu_f(float x) { return x * __builtin_amdgcn_rcpf(1.0f + __expf(-x)); }
;     __device__ __forceinline__ void operator()(const f32x4 (&acc)[2][2][4][2], const Unit& u, int wr, int wc, int fr, int fq) const {
;     ...
;             for (int m = 0; m < 4; ++m) {
;                 const int r = u.pm * BM + ai * HALF + wr * 64 + m * 16 + fr;
;                 float gate[8], a[8];
; #pragma unroll
;                 for (int j = 0; j < 8; ++j) {
;                     const float s1 = __shfl(gp[ai][m][j], src1), s2 = __shfl(gp[ai][m][j], src2);
;                     const float p1 = (fr >= 1) ? s1 : ps1[j], p2 = (fr >= 2) ? s2 : ps2[j];
;                     ps1[j] = s1; ps2[j] = s2;
;                     gate[j] = w0[j] * p2 + w1[j] * p1 + w2[j] * gp[ai][m][j];
;                     a[j] = silu_f(gate[j]) * up[ai][m][j];
;                 }
;                 u32x4 w; w.x = cvt_pk_bf16(a[0], a[1]); w.y = cvt_pk_bf16(a[2], a[3]); w.z = cvt_pk_bf16(a[4], a[5]); w.w = cvt_pk_bf16(a[6], a[7]);
;                 *(u32x4*)(ACT + (size_t)r * DFF + cg) = w;
;                 if (B == 0 && m == 0 && fr < 2 && (u.pm & 15) != 0) {
;                     float* fg = FIXG + ((size_t)u.pm * 2 + fr) * DFF + cg; float* fu = FIXU + ((size_t)u.pm * 2 + fr) * DFF + cg;
;                     *(f32x4*)fg = (f32x4){gate[0], gate[1], gate[2], gate[3]}; *(f32x4*)(fg + 4) = (f32x4){gate[4], gate[5], gate[6], gate[7]};
;                     *(f32x4*)fu = (f32x4){up[ai][m][0], up[ai][m][1], up[ai][m][2], up[ai][m][3]}; *(f32x4*)(fu + 4) = (f32x4){up[ai][m][4], up[ai][m][5], up[ai][m][6], up[ai][m][7]};
.LBB0_1721:
	v_fmamk_f32 v110, v203, 0x3a000000, v222
	v_mul_f32_e32 v111, 0x4b800000, v110
	v_cmp_gt_f32_e32 vcc, s95, v110
	s_waitcnt lgkmcnt(1)
	v_cndmask_b32_e64 v105, v97, v105, s[14:15]
	s_waitcnt lgkmcnt(0)
	v_cndmask_b32_e64 v98, v90, v98, s[14:15]
	v_cndmask_b32_e32 v110, v110, v111, vcc
	v_rsq_f32_e32 v110, v110
	v_cndmask_b32_e64 v99, v91, v99, s[14:15]
	v_cndmask_b32_e64 v100, v92, v100, s[14:15]
	v_cndmask_b32_e64 v101, v93, v101, s[14:15]
	v_mul_f32_e32 v111, 0x45800000, v110
	v_cndmask_b32_e32 v110, v110, v111, vcc
	v_pk_mul_f32 v[54:55], v[54:55], v[110:111] op_sel_hi:[1,0]
	v_pk_mul_f32 v[50:51], v[50:51], v[110:111] op_sel_hi:[1,0]
	v_pk_mul_f32 v[56:57], v[56:57], v[110:111] op_sel_hi:[1,0]
	v_pk_mul_f32 v[52:53], v[52:53], v[110:111] op_sel_hi:[1,0]
	v_pk_mul_f32 v[112:113], v[46:47], v[110:111] op_sel_hi:[1,0]
	v_pk_mul_f32 v[42:43], v[42:43], v[110:111] op_sel_hi:[1,0]
	v_pk_mul_f32 v[114:115], v[48:49], v[110:111] op_sel_hi:[1,0]
	v_pk_mul_f32 v[44:45], v[44:45], v[110:111] op_sel_hi:[1,0]
	v_cndmask_b32_e64 v49, v95, v103, s[14:15]
	ds_bpermute_b32 v103, v195, v55
	ds_bpermute_b32 v110, v195, v54
	v_cndmask_b32_e64 v48, v94, v102, s[14:15]
	v_cndmask_b32_e64 v111, v96, v104, s[14:15]
	ds_bpermute_b32 v102, v193, v55
	ds_bpermute_b32 v104, v193, v54
	s_waitcnt lgkmcnt(3)
	v_cndmask_b32_e64 v49, v49, v103, s[12:13]
	s_waitcnt lgkmcnt(2)
	v_cndmask_b32_e64 v48, v48, v110, s[12:13]
	v_pk_mul_f32 v[48:49], v[70:71], v[48:49]
	s_waitcnt lgkmcnt(1)
	v_cndmask_b32_e64 v47, v95, v102, s[10:11]
	s_waitcnt lgkmcnt(0)
	v_cndmask_b32_e64 v46, v94, v104, s[10:11]
	v_pk_fma_f32 v[46:47], v[82:83], v[46:47], v[48:49]
	ds_bpermute_b32 v95, v195, v56
	v_pk_fma_f32 v[46:47], v[86:87], v[54:55], v[46:47]
	ds_bpermute_b32 v87, v195, v57
	v_mul_f32_e32 v48, 0xbfb8aa3b, v46
	v_exp_f32_e32 v48, v48
	v_mul_f32_e32 v49, 0xbfb8aa3b, v47
	v_exp_f32_e32 v49, v49
	ds_bpermute_b32 v86, v193, v57
	v_add_f32_e32 v48, 1.0, v48
	v_rcp_f32_e32 v48, v48
	ds_bpermute_b32 v94, v193, v56
	s_waitcnt lgkmcnt(2)
	v_cndmask_b32_e64 v55, v105, v87, s[12:13]
	v_cndmask_b32_e64 v54, v111, v95, s[12:13]
	v_mul_f32_e32 v48, v46, v48
	v_mul_f32_e32 v116, v50, v48
	v_add_f32_e32 v48, 1.0, v49
	v_rcp_f32_e32 v48, v48
	s_waitcnt lgkmcnt(1)
	v_cndmask_b32_e64 v49, v97, v86, s[10:11]
	v_pk_mul_f32 v[54:55], v[72:73], v[54:55]
	ds_bpermute_b32 v83, v195, v113
	v_mul_f32_e32 v82, v47, v48
	s_waitcnt lgkmcnt(1)
	v_cndmask_b32_e64 v48, v96, v94, s[10:11]
	v_pk_fma_f32 v[48:49], v[84:85], v[48:49], v[54:55]
	ds_bpermute_b32 v85, v195, v112
	v_pk_fma_f32 v[48:49], v[88:89], v[56:57], v[48:49]
	v_mul_f32_e32 v96, v51, v82
	v_mul_f32_e32 v54, 0xbfb8aa3b, v48
	v_exp_f32_e32 v54, v54
	v_mul_f32_e32 v55, 0xbfb8aa3b, v49
	v_exp_f32_e32 v55, v55
	ds_bpermute_b32 v82, v193, v113
	ds_bpermute_b32 v84, v193, v112
	v_add_f32_e32 v54, 1.0, v54
	v_rcp_f32_e32 v88, v54
	v_add_f32_e32 v54, 1.0, v55
	s_waitcnt lgkmcnt(3)
	v_cndmask_b32_e64 v57, v99, v83, s[12:13]
	s_waitcnt lgkmcnt(2)
	v_cndmask_b32_e64 v56, v98, v85, s[12:13]
	v_rcp_f32_e32 v89, v54
	s_waitcnt lgkmcnt(1)
	v_cndmask_b32_e64 v55, v91, v82, s[10:11]
	s_waitcnt lgkmcnt(0)
	v_cndmask_b32_e64 v54, v90, v84, s[10:11]
	v_pk_mul_f32 v[56:57], v[66:67], v[56:57]
	s_nop 0
	v_pk_fma_f32 v[54:55], v[74:75], v[54:55], v[56:57]
	ds_bpermute_b32 v75, v195, v115
	v_pk_fma_f32 v[54:55], v[78:79], v[112:113], v[54:55]
	ds_bpermute_b32 v79, v195, v114
	v_mul_f32_e32 v56, 0xbfb8aa3b, v54
	v_exp_f32_e32 v56, v56
	v_mul_f32_e32 v74, 0xbfb8aa3b, v55
	v_exp_f32_e32 v74, v74
	ds_bpermute_b32 v78, v193, v114
	v_add_f32_e32 v56, 1.0, v56
	v_rcp_f32_e32 v56, v56
	v_mul_f32_e32 v57, v48, v88
	v_mul_f32_e32 v90, v52, v57
	v_mul_f32_e32 v57, v49, v89
	v_mul_f32_e32 v56, v54, v56
	v_mul_f32_e32 v97, v42, v56
	v_add_f32_e32 v56, 1.0, v74
	ds_bpermute_b32 v74, v193, v115
	s_waitcnt lgkmcnt(3)
	v_cndmask_b32_e64 v89, v101, v75, s[12:13]
	s_waitcnt lgkmcnt(2)
	v_cndmask_b32_e64 v88, v100, v79, s[12:13]
	v_mul_f32_e32 v91, v53, v57
	v_rcp_f32_e32 v98, v56
	s_waitcnt lgkmcnt(0)
	v_cndmask_b32_e64 v57, v93, v74, s[10:11]
	v_cndmask_b32_e64 v56, v92, v78, s[10:11]
	v_pk_mul_f32 v[88:89], v[68:69], v[88:89]
	s_nop 0
	v_pk_fma_f32 v[56:57], v[76:77], v[56:57], v[88:89]
	v_cvt_pk_bf16_f32 v88, v116, v96
	v_cvt_pk_bf16_f32 v89, v90, v91
	s_nop 0
	v_pk_fma_f32 v[56:57], v[80:81], v[114:115], v[56:57]
	v_mul_f32_e32 v80, v55, v98
	v_mul_f32_e32 v76, 0xbfb8aa3b, v56
	v_mul_f32_e32 v77, 0xbfb8aa3b, v57
	v_exp_f32_e32 v76, v76
	v_exp_f32_e32 v77, v77
	v_mul_f32_e32 v80, v43, v80
	v_cvt_pk_bf16_f32 v90, v97, v80
	v_add_f32_e32 v76, 1.0, v76
	v_add_f32_e32 v77, 1.0, v77
	v_rcp_f32_e32 v76, v76
	v_rcp_f32_e32 v77, v77
	v_mul_f32_e32 v76, v56, v76
	v_mul_f32_e32 v77, v57, v77
	v_mul_f32_e32 v76, v44, v76
	v_mul_f32_e32 v77, v45, v77
	v_cvt_pk_bf16_f32 v91, v76, v77
	v_mov_b64_e32 v[76:77], s[44:45]
	v_mad_i64_i32 v[76:77], s[14:15], v200, s97, v[76:77]
	s_or_b64 s[14:15], s[70:71], s[12:13]
	v_lshl_add_u64 v[76:77], v[190:191], 1, v[76:77]
	s_nor_b64 s[76:77], s[14:15], s[76:77]
	global_store_dwordx4 v[76:77], v[88:91], off sc1
	s_and_saveexec_b64 s[14:15], s[76:77]
	s_cbranch_execz .LBB0_1723
	v_lshl_add_u64 v[80:81], v[208:209], 0, v[204:205]
	v_lshl_add_u64 v[76:77], v[206:207], 0, v[204:205]
	global_store_dwordx4 v[80:81], v[46:49], off sc1
	global_store_dwordx4 v[80:81], v[54:57], off offset:16 sc1
	global_store_dwordx4 v[76:77], v[50:53], off sc1
	global_store_dwordx4 v[76:77], v[42:45], off offset:16 sc1
;     __device__ __forceinline__ void operator()(const f32x4 (&acc)[2][2][4][2], const Unit& u, int wr, int wc, int fr, int fq) const {
;     ...
;             for (int m = 0; m < 4; ++m) { const int r = u.pm * BM + ai * HALF + wr * 64 + m * 16 + fr; const float rs = rsqrtf(sumsq[r] * (1.0f / D) + EPS);
; #pragma unroll
;                 for (int n = 0; n < 2; ++n)
; #pragma unroll
;                     for (int j = 0; j < 4; ++j) { gp[ai][m][4 * n + j] = acc[ai][0][m][n][j] * rs; up[ai][m][4 * n + j] = acc[ai][1][m][n][j] * rs; } }
;         if (fr >= 14) {
; #pragma unroll
;             for (int ai = 0; ai < 2; ++ai) { PG8_LAS float* hp = halo + ((wc * 4 + (2 * ai + wr)) * 2 + (fr - 14)) * 32 + 8 * fq;
;                 *(PG8_LAS f32x4*)hp = (f32x4){gp[ai][3][0], gp[ai][3][1], gp[ai][3][2], gp[ai][3][3]}; *(PG8_LAS f32x4*)(hp + 4) = (f32x4){gp[ai][3][4], gp[ai][3][5], gp[ai][3][6], gp[ai][3][7]}; }
;         }
;         asm volatile("s_waitcnt lgkmcnt(0)" ::: "memory"); __builtin_amdgcn_s_barrier(); asm volatile("" ::: "memory");
;         const int src1 = (lane & 48) | ((fr - 1) & 15), src2 = (lane & 48) | ((fr - 2) & 15);
; #pragma unroll
;         for (int ai = 0; ai < 2; ++ai) {
;             const int B = 2 * ai + wr;
;             float h62[8], h63[8];
;             if (B > 0) { const PG8_LAS float* hp = halo + ((wc * 4 + (B - 1)) * 2) * 32 + 8 * fq;
;                 const f32x4 a0 = *(const PG8_LAS f32x4*)hp, a1 = *(const PG8_LAS f32x4*)(hp + 4), b0 = *(const PG8_LAS f32x4*)(hp + 32), b1 = *(const PG8_LAS f32x4*)(hp + 36);
; #pragma unroll
;                 for (int j = 0; j < 4; ++j) { h62[j] = a0[j]; h62[4 + j] = a1[j]; h63[j] = b0[j]; h63[4 + j] = b1[j]; } }
;             else {
; #pragma unroll
;                 for (int j = 0; j < 8; ++j) { h62[j] = 0.f; h63[j] = 0.f; } }
;             float ps1[8], ps2[8];
; #pragma unroll
;             for (int j = 0; j < 8; ++j) { ps1[j] = h63[j]; ps2[j] = (fr == 0) ? h62[j] : h63[j]; }
; #pragma unroll
;             for (int m = 0; m < 4; ++m) {
;                 const int r = u.pm * BM + ai * HALF + wr * 64 + m * 16 + fr;
;                 float gate[8], a[8];
; #pragma unroll
;                 for (int j = 0; j < 8; ++j) {
;                     const float s1 = __shfl(gp[ai][m][j], src1), s2 = __shfl(gp[ai][m][j], src2);
;                     const float p1 = (fr >= 1) ? s1 : ps1[j], p2 = (fr >= 2) ? s2 : ps2[j];
.LBB0_1723:
	s_or_b64 exec, exec, s[14:15]
	s_nop 0
	v_fmamk_f32 v42, v201, 0x3a000000, v222
	v_mul_f32_e32 v43, 0x4b800000, v42
	v_cmp_gt_f32_e32 vcc, s95, v42
	v_mul_f32_e32 v57, v8, v198
	v_mul_f32_e32 v76, v3, v198
	v_cndmask_b32_e32 v42, v42, v43, vcc
	v_rsq_f32_e32 v42, v42
	v_mul_f32_e32 v77, v4, v198
	v_mul_f32_e32 v80, v5, v198
	v_mul_f32_e32 v43, 0x45800000, v42
	v_cndmask_b32_e32 v42, v42, v43, vcc
	v_mul_f32_e32 v49, v27, v42
	v_fmamk_f32 v27, v197, 0x3a000000, v222
	v_mul_f32_e32 v48, v26, v42
	v_mul_f32_e32 v26, v31, v42
	v_mul_f32_e32 v31, 0x4b800000, v27
	v_cmp_gt_f32_e32 vcc, s95, v27
	v_mul_f32_e32 v51, v29, v42
	v_mul_f32_e32 v38, v38, v42
	v_cndmask_b32_e32 v27, v27, v31, vcc
	v_rsq_f32_e32 v27, v27
	v_mul_f32_e32 v43, v34, v42
	v_mul_f32_e32 v34, v39, v42
	v_mul_f32_e32 v40, v40, v42
	v_mul_f32_e32 v29, 0x45800000, v27
	v_cndmask_b32_e32 v27, v27, v29, vcc
	v_mul_f32_e32 v56, v11, v27
	ds_bpermute_b32 v11, v193, v38
	v_mul_f32_e32 v52, v18, v27
	v_mul_f32_e32 v18, v15, v27
	ds_bpermute_b32 v15, v195, v38
	v_mul_f32_e32 v53, v20, v27
	s_waitcnt lgkmcnt(1)
	v_cndmask_b32_e64 v39, v104, v11, s[10:11]
	v_mul_f32_e32 v20, v14, v27
	v_mul_f32_e32 v55, v10, v27
	v_mul_f32_e32 v14, v16, v27
	v_mul_f32_e32 v10, v17, v27
	v_mul_f32_e32 v16, v6, v198
	v_mul_f32_e32 v17, v7, v198
	s_waitcnt lgkmcnt(0)
	v_cndmask_b32_e64 v8, v110, v15, s[12:13]
	v_pk_mul_f32 v[6:7], v[166:167], v[38:39]
	v_mul_f32_e32 v54, v21, v27
	v_fma_f32 v7, v70, v8, v7
	v_add_f32_e32 v6, v6, v7
	v_mul_f32_e32 v7, 0xbfb8aa3b, v6
	v_exp_f32_e32 v7, v7
	ds_bpermute_b32 v21, v193, v34
	v_mul_f32_e32 v39, v2, v198
	v_mul_f32_e32 v44, v23, v27
	v_add_f32_e32 v2, 1.0, v7
	v_rcp_f32_e32 v2, v2
	ds_bpermute_b32 v23, v195, v34
	v_mul_f32_e32 v45, v35, v42
	v_mul_f32_e32 v46, v36, v42
	v_mul_f32_e32 v36, v41, v42
	v_mul_f32_e32 v47, v37, v42
	v_mul_f32_e32 v30, v30, v42
	v_mul_f32_e32 v32, v32, v42
	v_mul_f32_e32 v50, v28, v42
	v_mul_f32_e32 v28, v33, v42
	v_mul_f32_e32 v42, v22, v27
	v_mul_f32_e32 v22, v25, v27
	s_waitcnt lgkmcnt(1)
	v_cndmask_b32_e64 v35, v102, v21, s[10:11]
	ds_bpermute_b32 v25, v193, v40
	v_mul_f32_e32 v4, v6, v2
	v_pk_mul_f32 v[2:3], v[158:159], v[34:35]
	ds_bpermute_b32 v34, v195, v40
	s_waitcnt lgkmcnt(2)
	v_cndmask_b32_e64 v5, v103, v23, s[12:13]
	v_fma_f32 v3, v71, v5, v3
	v_add_f32_e32 v5, v2, v3
	v_mul_f32_e32 v2, 0xbfb8aa3b, v5
	s_waitcnt lgkmcnt(1)
	v_cndmask_b32_e64 v41, v94, v25, s[10:11]
	v_exp_f32_e32 v6, v2
	s_waitcnt lgkmcnt(0)
	v_cndmask_b32_e64 v7, v95, v34, s[12:13]
	v_pk_mul_f32 v[2:3], v[162:163], v[40:41]
	ds_bpermute_b32 v35, v193, v36
	v_fma_f32 v3, v72, v7, v3
	v_add_f32_e32 v2, v2, v3
	v_mul_f32_e32 v3, 0xbfb8aa3b, v2
	v_exp_f32_e32 v3, v3
	v_add_f32_e32 v6, 1.0, v6
	v_rcp_f32_e32 v6, v6
	ds_bpermute_b32 v40, v195, v36
	v_add_f32_e32 v3, 1.0, v3
	v_rcp_f32_e32 v3, v3
	s_waitcnt lgkmcnt(1)
	v_cndmask_b32_e64 v37, v86, v35, s[10:11]
	v_mul_f32_e32 v5, v5, v6
	s_waitcnt lgkmcnt(0)
	v_cndmask_b32_e64 v7, v87, v40, s[12:13]
	v_mul_f32_e32 v6, v2, v3
	v_pk_mul_f32 v[2:3], v[160:161], v[36:37]
	ds_bpermute_b32 v36, v193, v30
	ds_bpermute_b32 v37, v195, v30
	v_fma_f32 v3, v73, v7, v3
	v_add_f32_e32 v7, v2, v3
	v_mul_f32_e32 v2, 0xbfb8aa3b, v7
	s_waitcnt lgkmcnt(1)
	v_cndmask_b32_e64 v31, v84, v36, s[10:11]
	v_mul_f32_e32 v38, v9, v198
	v_exp_f32_e32 v8, v2
	s_waitcnt lgkmcnt(0)
	v_cndmask_b32_e64 v9, v85, v37, s[12:13]
	v_pk_mul_f32 v[2:3], v[164:165], v[30:31]
	ds_bpermute_b32 v30, v193, v26
	v_fma_f32 v3, v66, v9, v3
	v_add_f32_e32 v2, v2, v3
	v_mul_f32_e32 v3, 0xbfb8aa3b, v2
	v_exp_f32_e32 v3, v3
	v_add_f32_e32 v8, 1.0, v8
	ds_bpermute_b32 v31, v195, v26
	v_rcp_f32_e32 v8, v8
	v_add_f32_e32 v3, 1.0, v3
	v_rcp_f32_e32 v3, v3
	v_mul_f32_e32 v19, v19, v27
	v_mul_f32_e32 v24, v24, v27
	v_mul_f32_e32 v12, v12, v27
	v_mul_f32_e32 v13, v13, v27
	s_waitcnt lgkmcnt(1)
	v_cndmask_b32_e64 v27, v82, v30, s[10:11]
	v_mul_f32_e32 v7, v7, v8
	v_mul_f32_e32 v8, v2, v3
	s_waitcnt lgkmcnt(0)
	v_cndmask_b32_e64 v9, v83, v31, s[12:13]
	v_pk_mul_f32 v[2:3], v[154:155], v[26:27]
	ds_bpermute_b32 v26, v193, v32
	v_fma_f32 v3, v67, v9, v3
	v_add_f32_e32 v9, v2, v3
	v_mul_f32_e32 v2, 0xbfb8aa3b, v9
	v_exp_f32_e32 v2, v2
	ds_bpermute_b32 v27, v195, v32
	s_waitcnt lgkmcnt(1)
	v_cndmask_b32_e64 v33, v78, v26, s[10:11]
	v_mul_f32_e32 v4, v43, v4
	v_add_f32_e32 v2, 1.0, v2
	v_rcp_f32_e32 v41, v2
	v_pk_mul_f32 v[2:3], v[168:169], v[32:33]
	ds_bpermute_b32 v32, v193, v28
	ds_bpermute_b32 v33, v195, v28
	s_waitcnt lgkmcnt(2)
	v_cndmask_b32_e64 v29, v79, v27, s[12:13]
	v_fma_f32 v3, v68, v29, v3
	v_add_f32_e32 v43, v2, v3
	v_mul_f32_e32 v2, 0xbfb8aa3b, v43
	s_waitcnt lgkmcnt(1)
	v_cndmask_b32_e64 v29, v74, v32, s[10:11]
	v_mul_f32_e32 v5, v45, v5
	v_mul_f32_e32 v6, v46, v6
	v_exp_f32_e32 v45, v2
	s_waitcnt lgkmcnt(0)
	v_cndmask_b32_e64 v46, v75, v33, s[12:13]
	v_pk_mul_f32 v[2:3], v[156:157], v[28:29]
	ds_bpermute_b32 v29, v193, v42
	v_fma_f32 v3, v69, v46, v3
	v_add_f32_e32 v2, v2, v3
	v_mul_f32_e32 v3, 0xbfb8aa3b, v2
	v_exp_f32_e32 v3, v3
	v_add_f32_e32 v28, 1.0, v45
	v_mul_f32_e32 v9, v9, v41
	v_rcp_f32_e32 v28, v28
	v_add_f32_e32 v3, 1.0, v3
	v_rcp_f32_e32 v3, v3
	ds_bpermute_b32 v41, v195, v42
	v_mul_f32_e32 v7, v47, v7
	v_mul_f32_e32 v8, v48, v8
	v_mul_f32_e32 v2, v2, v3
	v_mul_f32_e32 v28, v43, v28
	v_mul_f32_e32 v2, v51, v2
	s_waitcnt lgkmcnt(1)
	v_cndmask_b32_e64 v43, v11, v29, s[10:11]
	v_mul_f32_e32 v9, v49, v9
	v_mul_f32_e32 v28, v50, v28
	v_cvt_pk_bf16_f32 v4, v4, v5
	v_cvt_pk_bf16_f32 v5, v6, v7
	v_cvt_pk_bf16_f32 v6, v8, v9
	v_cvt_pk_bf16_f32 v7, v28, v2
	s_waitcnt lgkmcnt(0)
; __device__ __forceinline__ unsigned cvt_pk_bf16(float lo, float hi) { unsigned r; asm volatile("v_cvt_pk_bf16_f32 %0, %1, %2" : "=v"(r) : "v"(lo), "v"(hi)); return r; }
; __device__ __forceinline__ float silu_f(float x) { return x * __builtin_amdgcn_rcpf(1.0f + __expf(-x)); }
;     __device__ __forceinline__ void operator()(const f32x4 (&acc)[2][2][4][2], const Unit& u, int wr, int wc, int fr, int fq) const {
;     ...
;             for (int m = 0; m < 4; ++m) {
;                 const int r = u.pm * BM + ai * HALF + wr * 64 + m * 16 + fr;
;                 float gate[8], a[8];
; #pragma unroll
;                 for (int j = 0; j < 8; ++j) {
;                     const float s1 = __shfl(gp[ai][m][j], src1), s2 = __shfl(gp[ai][m][j], src2);
;                     const float p1 = (fr >= 1) ? s1 : ps1[j], p2 = (fr >= 2) ? s2 : ps2[j];
;                     ps1[j] = s1; ps2[j] = s2;
;                     gate[j] = w0[j] * p2 + w1[j] * p1 + w2[j] * gp[ai][m][j];
;                     a[j] = silu_f(gate[j]) * up[ai][m][j];
;                 }
;                 u32x4 w; w.x = cvt_pk_bf16(a[0], a[1]); w.y = cvt_pk_bf16(a[2], a[3]); w.z = cvt_pk_bf16(a[4], a[5]); w.w = cvt_pk_bf16(a[6], a[7]);
;                 *(u32x4*)(ACT + (size_t)r * DFF + cg) = w;
	v_cndmask_b32_e64 v8, v15, v41, s[12:13]
	v_pk_mul_f32 v[2:3], v[166:167], v[42:43]
	ds_bpermute_b32 v28, v193, v44
	v_fma_f32 v3, v70, v8, v3
	v_add_f32_e32 v11, v2, v3
	v_mul_f32_e32 v2, 0xbfb8aa3b, v11
	ds_bpermute_b32 v42, v195, v44
	v_exp_f32_e32 v15, v2
	v_mov_b64_e32 v[2:3], s[44:45]
	v_mad_i64_i32 v[8:9], s[14:15], v196, s97, v[2:3]
	v_lshl_add_u64 v[8:9], v[8:9], 0, v[106:107]
	s_waitcnt lgkmcnt(1)
	v_cndmask_b32_e64 v45, v21, v28, s[10:11]
	ds_bpermute_b32 v43, v193, v24
	global_store_dwordx4 v[8:9], v[4:7], off sc1
	v_add_f32_e32 v15, 1.0, v15
	v_rcp_f32_e32 v15, v15
	v_pk_mul_f32 v[4:5], v[158:159], v[44:45]
	ds_bpermute_b32 v44, v195, v24
	s_waitcnt lgkmcnt(2)
	v_cndmask_b32_e64 v7, v23, v42, s[12:13]
	v_fma_f32 v5, v71, v7, v5
	v_add_f32_e32 v7, v4, v5
	v_mul_f32_e32 v4, 0xbfb8aa3b, v7
	s_waitcnt lgkmcnt(1)
	v_cndmask_b32_e64 v25, v25, v43, s[10:11]
	v_exp_f32_e32 v8, v4
	s_waitcnt lgkmcnt(0)
	v_cndmask_b32_e64 v9, v34, v44, s[12:13]
	v_pk_mul_f32 v[4:5], v[162:163], v[24:25]
	ds_bpermute_b32 v24, v193, v22
	v_fma_f32 v5, v72, v9, v5
	v_add_f32_e32 v4, v4, v5
	v_mul_f32_e32 v5, 0xbfb8aa3b, v4
	v_exp_f32_e32 v5, v5
	v_add_f32_e32 v8, 1.0, v8
	v_rcp_f32_e32 v8, v8
	ds_bpermute_b32 v25, v195, v22
	v_add_f32_e32 v5, 1.0, v5
	v_rcp_f32_e32 v5, v5
	s_waitcnt lgkmcnt(1)
	v_cndmask_b32_e64 v23, v35, v24, s[10:11]
	v_mul_f32_e32 v7, v7, v8
	s_waitcnt lgkmcnt(0)
	v_cndmask_b32_e64 v9, v40, v25, s[12:13]
	v_mul_f32_e32 v8, v4, v5
	v_pk_mul_f32 v[4:5], v[160:161], v[22:23]
	ds_bpermute_b32 v22, v193, v20
	ds_bpermute_b32 v23, v195, v20
	v_fma_f32 v5, v73, v9, v5
	v_add_f32_e32 v9, v4, v5
	v_mul_f32_e32 v4, 0xbfb8aa3b, v9
	s_waitcnt lgkmcnt(1)
	v_cndmask_b32_e64 v21, v36, v22, s[10:11]
	v_mul_f32_e32 v6, v11, v15
	v_exp_f32_e32 v11, v4
	s_waitcnt lgkmcnt(0)
	v_cndmask_b32_e64 v15, v37, v23, s[12:13]
	v_pk_mul_f32 v[4:5], v[164:165], v[20:21]
	ds_bpermute_b32 v20, v193, v18
	v_fma_f32 v5, v66, v15, v5
	v_add_f32_e32 v4, v4, v5
	v_mul_f32_e32 v5, 0xbfb8aa3b, v4
	v_exp_f32_e32 v5, v5
	v_add_f32_e32 v11, 1.0, v11
	ds_bpermute_b32 v21, v195, v18
	v_rcp_f32_e32 v11, v11
	v_add_f32_e32 v5, 1.0, v5
	v_rcp_f32_e32 v5, v5
	v_mul_f32_e32 v7, v19, v7
	s_waitcnt lgkmcnt(1)
	v_cndmask_b32_e64 v19, v30, v20, s[10:11]
	v_mul_f32_e32 v9, v9, v11
	v_mul_f32_e32 v11, v4, v5
	s_waitcnt lgkmcnt(0)
	v_cndmask_b32_e64 v15, v31, v21, s[12:13]
	v_pk_mul_f32 v[4:5], v[154:155], v[18:19]
	ds_bpermute_b32 v19, v193, v14
	v_fma_f32 v5, v67, v15, v5
	v_add_f32_e32 v18, v4, v5
	v_mul_f32_e32 v4, 0xbfb8aa3b, v18
	v_exp_f32_e32 v4, v4
	ds_bpermute_b32 v30, v195, v14
	s_waitcnt lgkmcnt(1)
	v_cndmask_b32_e64 v15, v26, v19, s[10:11]
	v_mul_f32_e32 v31, v55, v11
	v_add_f32_e32 v4, 1.0, v4
	v_rcp_f32_e32 v34, v4
	v_pk_mul_f32 v[4:5], v[168:169], v[14:15]
	ds_bpermute_b32 v14, v193, v10
	ds_bpermute_b32 v15, v195, v10
	s_waitcnt lgkmcnt(2)
	v_cndmask_b32_e64 v11, v27, v30, s[12:13]
	v_fma_f32 v5, v68, v11, v5
	v_add_f32_e32 v26, v4, v5
	v_mul_f32_e32 v4, 0xbfb8aa3b, v26
	s_waitcnt lgkmcnt(1)
	v_cndmask_b32_e64 v11, v32, v14, s[10:11]
	v_exp_f32_e32 v27, v4
	s_waitcnt lgkmcnt(0)
	v_cndmask_b32_e64 v32, v33, v15, s[12:13]
	v_pk_mul_f32 v[4:5], v[156:157], v[10:11]
	v_mul_f32_e32 v10, v18, v34
	v_fma_f32 v5, v69, v32, v5
	v_add_f32_e32 v4, v4, v5
	v_mul_f32_e32 v5, 0xbfb8aa3b, v4
	v_exp_f32_e32 v5, v5
	v_add_f32_e32 v11, 1.0, v27
	v_rcp_f32_e32 v11, v11
	ds_bpermute_b32 v18, v195, v58
	v_add_f32_e32 v5, 1.0, v5
	v_rcp_f32_e32 v5, v5
	v_mul_f32_e32 v11, v26, v11
	v_mul_f32_e32 v11, v12, v11
	v_mul_f32_e32 v8, v53, v8
	v_mul_f32_e32 v4, v4, v5
	v_mul_f32_e32 v12, v13, v4
	ds_bpermute_b32 v13, v193, v58
	v_mul_f32_e32 v9, v54, v9
	v_mul_f32_e32 v6, v52, v6
	v_cvt_pk_bf16_f32 v4, v6, v7
	v_cvt_pk_bf16_f32 v5, v8, v9
	s_waitcnt lgkmcnt(0)
	v_cndmask_b32_e64 v9, v29, v13, s[10:11]
	v_mov_b32_e32 v8, v58
	v_cndmask_b32_e64 v7, v41, v18, s[12:13]
	v_pk_mul_f32 v[8:9], v[166:167], v[8:9]
	v_mul_f32_e32 v10, v56, v10
	v_fma_f32 v7, v70, v7, v9
	v_cvt_pk_bf16_f32 v6, v31, v10
	v_add_f32_e32 v10, v8, v7
	v_mul_f32_e32 v7, 0xbfb8aa3b, v10
	v_exp_f32_e32 v13, v7
	v_cvt_pk_bf16_f32 v7, v11, v12
	ds_bpermute_b32 v12, v193, v59
	v_mad_i64_i32 v[8:9], s[14:15], v194, s97, v[2:3]
	v_add_f32_e32 v11, 1.0, v13
	ds_bpermute_b32 v13, v195, v59
	v_lshl_add_u64 v[8:9], v[8:9], 0, v[106:107]
	global_store_dwordx4 v[8:9], v[4:7], off sc1
	v_rcp_f32_e32 v11, v11
	ds_bpermute_b32 v8, v195, v60
	s_waitcnt lgkmcnt(2)
; __device__ __forceinline__ unsigned cvt_pk_bf16(float lo, float hi) { unsigned r; asm volatile("v_cvt_pk_bf16_f32 %0, %1, %2" : "=v"(r) : "v"(lo), "v"(hi)); return r; }
;     __device__ __forceinline__ void operator()(const f32x4 (&acc)[2][2][4][2], const Unit& u, int wr, int wc, int fr, int fq) const {
;     ...
;             for (int m = 0; m < 4; ++m) {
;                 const int r = u.pm * BM + ai * HALF + wr * 64 + m * 16 + fr;
;                 float gate[8], a[8];
; #pragma unroll
;                 for (int j = 0; j < 8; ++j) {
;                     const float s1 = __shfl(gp[ai][m][j], src1), s2 = __shfl(gp[ai][m][j], src2);
;                     const float p1 = (fr >= 1) ? s1 : ps1[j], p2 = (fr >= 2) ? s2 : ps2[j];
;                     ps1[j] = s1; ps2[j] = s2;
;                     gate[j] = w0[j] * p2 + w1[j] * p1 + w2[j] * gp[ai][m][j];
;                     a[j] = silu_f(gate[j]) * up[ai][m][j];
;                 }
;                 u32x4 w; w.x = cvt_pk_bf16(a[0], a[1]); w.y = cvt_pk_bf16(a[2], a[3]); w.z = cvt_pk_bf16(a[4], a[5]); w.w = cvt_pk_bf16(a[6], a[7]);
;                 *(u32x4*)(ACT + (size_t)r * DFF + cg) = w;
;                 if (B == 0 && m == 0 && fr < 2 && (u.pm & 15) != 0) {
;                     float* fg = FIXG + ((size_t)u.pm * 2 + fr) * DFF + cg; float* fu = FIXU + ((size_t)u.pm * 2 + fr) * DFF + cg;
;                     *(f32x4*)fg = (f32x4){gate[0], gate[1], gate[2], gate[3]}; *(f32x4*)(fg + 4) = (f32x4){gate[4], gate[5], gate[6], gate[7]};
;                     *(f32x4*)fu = (f32x4){up[ai][m][0], up[ai][m][1], up[ai][m][2], up[ai][m][3]}; *(f32x4*)(fu + 4) = (f32x4){up[ai][m][4], up[ai][m][5], up[ai][m][6], up[ai][m][7]};
;                 }
;                 if (B == 3 && m == 3 && fr >= 14) {
;                     float* tp = TAIL + ((size_t)u.pm * 2 + (fr - 14)) * DFF + cg;
;                     *(f32x4*)tp = (f32x4){gp[ai][m][0], gp[ai][m][1], gp[ai][m][2], gp[ai][m][3]}; *(f32x4*)(tp + 4) = (f32x4){gp[ai][m][4], gp[ai][m][5], gp[ai][m][6], gp[ai][m][7]};
;                     if ((u.pm & 15) == 15) { float* op = outFconv + ((size_t)(u.pm >> 4) * 2 + (fr - 14)) * DFF + cg;
;                         *(f32x4*)op = (f32x4){gp[ai][m][0], gp[ai][m][1], gp[ai][m][2], gp[ai][m][3]}; *(f32x4*)(op + 4) = (f32x4){gp[ai][m][4], gp[ai][m][5], gp[ai][m][6], gp[ai][m][7]}; }
	v_cndmask_b32_e64 v5, v28, v12, s[10:11]
	v_mov_b32_e32 v4, v59
	s_waitcnt lgkmcnt(1)
	v_cndmask_b32_e64 v7, v42, v13, s[12:13]
	v_pk_mul_f32 v[4:5], v[158:159], v[4:5]
	v_mul_f32_e32 v6, v10, v11
	v_fma_f32 v5, v71, v7, v5
	ds_bpermute_b32 v7, v193, v60
	v_add_f32_e32 v9, v4, v5
	v_mul_f32_e32 v4, 0xbfb8aa3b, v9
	v_exp_f32_e32 v10, v4
	v_mov_b32_e32 v4, v60
	s_waitcnt lgkmcnt(0)
	v_cndmask_b32_e64 v5, v43, v7, s[10:11]
	v_cndmask_b32_e64 v7, v44, v8, s[12:13]
	v_pk_mul_f32 v[4:5], v[162:163], v[4:5]
	ds_bpermute_b32 v8, v193, v61
	v_fma_f32 v5, v72, v7, v5
	v_add_f32_e32 v4, v4, v5
	v_mul_f32_e32 v5, 0xbfb8aa3b, v4
	v_exp_f32_e32 v5, v5
	v_add_f32_e32 v7, 1.0, v10
	v_rcp_f32_e32 v7, v7
	ds_bpermute_b32 v10, v195, v61
	v_add_f32_e32 v5, 1.0, v5
	v_rcp_f32_e32 v5, v5
	v_mul_f32_e32 v7, v9, v7
	v_mul_f32_e32 v6, v16, v6
	ds_bpermute_b32 v16, v195, v65
	v_mul_f32_e32 v9, v4, v5
	s_waitcnt lgkmcnt(2)
	v_cndmask_b32_e64 v5, v24, v8, s[10:11]
	v_mov_b32_e32 v4, v61
	s_waitcnt lgkmcnt(1)
	v_cndmask_b32_e64 v8, v25, v10, s[12:13]
	v_pk_mul_f32 v[4:5], v[160:161], v[4:5]
	ds_bpermute_b32 v10, v195, v62
	v_fma_f32 v5, v73, v8, v5
	ds_bpermute_b32 v8, v193, v62
	v_add_f32_e32 v11, v4, v5
	v_mul_f32_e32 v4, 0xbfb8aa3b, v11
	v_exp_f32_e32 v12, v4
	v_mov_b32_e32 v4, v62
	s_waitcnt lgkmcnt(0)
	v_cndmask_b32_e64 v5, v22, v8, s[10:11]
	v_cndmask_b32_e64 v8, v23, v10, s[12:13]
	v_pk_mul_f32 v[4:5], v[164:165], v[4:5]
	ds_bpermute_b32 v10, v193, v63
	v_fma_f32 v5, v66, v8, v5
	v_add_f32_e32 v4, v4, v5
	v_mul_f32_e32 v5, 0xbfb8aa3b, v4
	v_exp_f32_e32 v5, v5
	v_mul_f32_e32 v8, v57, v9
	v_add_f32_e32 v9, 1.0, v12
	v_rcp_f32_e32 v9, v9
	v_add_f32_e32 v5, 1.0, v5
	v_rcp_f32_e32 v5, v5
	ds_bpermute_b32 v12, v195, v63
	v_mul_f32_e32 v9, v11, v9
	v_mul_f32_e32 v7, v17, v7
	v_mul_f32_e32 v11, v4, v5
	s_waitcnt lgkmcnt(1)
	v_cndmask_b32_e64 v5, v20, v10, s[10:11]
	v_mov_b32_e32 v4, v63
	s_waitcnt lgkmcnt(0)
	v_cndmask_b32_e64 v10, v21, v12, s[12:13]
	v_pk_mul_f32 v[4:5], v[154:155], v[4:5]
	ds_bpermute_b32 v12, v195, v64
	v_fma_f32 v5, v67, v10, v5
	v_add_f32_e32 v10, v4, v5
	v_mul_f32_e32 v4, 0xbfb8aa3b, v10
	v_exp_f32_e32 v4, v4
	ds_bpermute_b32 v5, v193, v64
	s_waitcnt lgkmcnt(1)
	v_cndmask_b32_e64 v12, v30, v12, s[12:13]
	v_mul_f32_e32 v9, v38, v9
	v_add_f32_e32 v4, 1.0, v4
	v_rcp_f32_e32 v13, v4
	s_waitcnt lgkmcnt(0)
	v_cndmask_b32_e64 v5, v19, v5, s[10:11]
	v_mov_b32_e32 v4, v64
	v_pk_mul_f32 v[4:5], v[168:169], v[4:5]
	v_mul_f32_e32 v10, v10, v13
	v_fma_f32 v5, v68, v12, v5
	ds_bpermute_b32 v12, v193, v65
	v_add_f32_e32 v17, v4, v5
	v_mul_f32_e32 v4, 0xbfb8aa3b, v17
	v_exp_f32_e32 v18, v4
	v_mov_b32_e32 v4, v65
	s_waitcnt lgkmcnt(0)
	v_cndmask_b32_e64 v5, v14, v12, s[10:11]
	v_cndmask_b32_e64 v12, v15, v16, s[12:13]
	v_pk_mul_f32 v[4:5], v[156:157], v[4:5]
	v_mad_i64_i32 v[2:3], s[10:11], v192, s97, v[2:3]
	v_fma_f32 v5, v69, v12, v5
	v_add_f32_e32 v4, v4, v5
	v_mul_f32_e32 v5, 0xbfb8aa3b, v4
	v_exp_f32_e32 v5, v5
	v_add_f32_e32 v12, 1.0, v18
	v_rcp_f32_e32 v12, v12
	v_lshl_add_u64 v[2:3], v[2:3], 0, v[106:107]
	v_add_f32_e32 v5, 1.0, v5
	v_rcp_f32_e32 v5, v5
	v_mul_f32_e32 v12, v17, v12
	s_and_b64 s[10:11], s[68:69], s[8:9]
	v_mul_f32_e32 v11, v39, v11
	v_mul_f32_e32 v4, v4, v5
	v_mul_f32_e32 v10, v76, v10
	v_mul_f32_e32 v12, v77, v12
	v_mul_f32_e32 v13, v80, v4
	v_cvt_pk_bf16_f32 v4, v6, v7
	v_cvt_pk_bf16_f32 v5, v8, v9
	v_cvt_pk_bf16_f32 v6, v11, v10
	v_cvt_pk_bf16_f32 v7, v12, v13
	global_store_dwordx4 v[2:3], v[4:7], off sc1
	s_and_saveexec_b64 s[8:9], s[10:11]
	s_cbranch_execz .LBB0_1726
	s_and_b64 vcc, exec, s[16:17]
	global_store_dwordx4 v[108:109], v[58:61], off sc1
	global_store_dwordx4 v[108:109], v[62:65], off offset:16 sc1
	s_cbranch_vccnz .LBB0_1726
	v_lshl_add_u64 v[2:3], s[52:53], 0, v[138:139]
	v_lshl_add_u64 v[2:3], v[190:191], 2, v[2:3]
	global_store_dwordx4 v[2:3], v[58:61], off sc1
	global_store_dwordx4 v[2:3], v[62:65], off offset:16 sc1

; #define LAS __attribute__((address_space(3)))
; #define LDS_WAIT() asm volatile("s_waitcnt lgkmcnt(0)" ::: "memory")
; __device__ __forceinline__ void ti_store(const TItem& t, const f32x4 (&v)[16], const float (&sc)[16], LAS float* scr, int lane) {
;     const int n4 = (lane & 15) * 4, kq = lane >> 4;
; #pragma unroll
;     for (int i = 0; i < 16; ++i) { const int kk = 4 * i + kq; const f32x4 x = v[i] * sc[i]; LAS float* d = scr + kk * 65 + n4; d[0] = x.x; d[1] = x.y; d[2] = x.z; d[3] = x.w; }
;     LDS_WAIT(); asm volatile("" ::: "memory");
.LBB0_1814:
	s_waitcnt vmcnt(14)
	v_pk_mul_f32 v[194:195], v[2:3], v[34:35] op_sel_hi:[0,1]
	v_pk_mul_f32 v[166:167], v[2:3], v[36:37] op_sel_hi:[0,1]
	ds_write2_b32 v193, v194, v195 offset1:1
	ds_write2_b32 v193, v166, v167 offset0:2 offset1:3
	v_pk_mul_f32 v[194:195], v[2:3], v[38:39] op_sel:[1,0]
	v_add_u32_e32 v165, 0x410, v193
	v_pk_mul_f32 v[166:167], v[2:3], v[40:41] op_sel:[1,0]
	ds_write2_b32 v165, v194, v195 offset1:1
	v_add_u32_e32 v165, 0x418, v193
	ds_write2_b32 v165, v166, v167 offset1:1
	s_waitcnt vmcnt(12)
	v_pk_mul_f32 v[194:195], v[4:5], v[42:43] op_sel_hi:[0,1]
	v_add_u32_e32 v165, 0x820, v193
	v_pk_mul_f32 v[166:167], v[4:5], v[44:45] op_sel_hi:[0,1]
	ds_write2_b32 v165, v194, v195 offset1:1
	v_add_u32_e32 v165, 0x828, v193
	ds_write2_b32 v165, v166, v167 offset1:1
	v_mov_b32_e32 v166, v5
	v_pk_mul_f32 v[194:195], v[166:167], v[48:49] op_sel_hi:[0,1]
	v_pk_mul_f32 v[166:167], v[166:167], v[46:47] op_sel_hi:[0,1]
	v_add_u32_e32 v165, 0xc30, v193
	ds_write2_b32 v165, v166, v167 offset1:1
	v_add_u32_e32 v165, 0xc38, v193
	ds_write2_b32 v165, v194, v195 offset1:1
	s_waitcnt vmcnt(10)
	v_pk_mul_f32 v[194:195], v[6:7], v[50:51] op_sel_hi:[0,1]
	v_add_u32_e32 v165, 0x1040, v193
	v_pk_mul_f32 v[166:167], v[6:7], v[52:53] op_sel_hi:[0,1]
	ds_write2_b32 v165, v194, v195 offset1:1
	v_add_u32_e32 v165, 0x1048, v193
	ds_write2_b32 v165, v166, v167 offset1:1
	v_mov_b32_e32 v166, v7
	v_pk_mul_f32 v[194:195], v[166:167], v[56:57] op_sel_hi:[0,1]
	v_pk_mul_f32 v[166:167], v[166:167], v[54:55] op_sel_hi:[0,1]
	v_add_u32_e32 v165, 0x1450, v193
	ds_write2_b32 v165, v166, v167 offset1:1
	v_add_u32_e32 v165, 0x1458, v193
	ds_write2_b32 v165, v194, v195 offset1:1
	s_waitcnt vmcnt(8)
	v_pk_mul_f32 v[194:195], v[8:9], v[58:59] op_sel_hi:[0,1]
	v_add_u32_e32 v165, 0x1860, v193
	v_pk_mul_f32 v[166:167], v[8:9], v[60:61] op_sel_hi:[0,1]
	ds_write2_b32 v165, v194, v195 offset1:1
	v_add_u32_e32 v165, 0x1868, v193
	ds_write2_b32 v165, v166, v167 offset1:1
	v_mov_b32_e32 v166, v9
	v_pk_mul_f32 v[194:195], v[166:167], v[64:65] op_sel_hi:[0,1]
	v_pk_mul_f32 v[166:167], v[166:167], v[62:63] op_sel_hi:[0,1]
	v_add_u32_e32 v165, 0x1c70, v193
	ds_write2_b32 v165, v166, v167 offset1:1
	v_add_u32_e32 v165, 0x1c78, v193
	ds_write2_b32 v165, v194, v195 offset1:1
	s_waitcnt vmcnt(6)
	v_pk_mul_f32 v[194:195], v[10:11], v[66:67] op_sel_hi:[0,1]
	v_add_u32_e32 v165, 0x2080, v193
	v_pk_mul_f32 v[166:167], v[10:11], v[68:69] op_sel_hi:[0,1]
	ds_write2_b32 v165, v194, v195 offset1:1
	v_add_u32_e32 v165, 0x2088, v193
	ds_write2_b32 v165, v166, v167 offset1:1
	v_mov_b32_e32 v166, v11
	v_pk_mul_f32 v[194:195], v[166:167], v[72:73] op_sel_hi:[0,1]
	v_pk_mul_f32 v[166:167], v[166:167], v[70:71] op_sel_hi:[0,1]
	v_add_u32_e32 v165, 0x2490, v193
	ds_write2_b32 v165, v166, v167 offset1:1
	v_add_u32_e32 v165, 0x2498, v193
	ds_write2_b32 v165, v194, v195 offset1:1
	s_waitcnt vmcnt(4)
	v_pk_mul_f32 v[194:195], v[12:13], v[74:75] op_sel_hi:[0,1]
	v_add_u32_e32 v165, 0x28a0, v193
	v_pk_mul_f32 v[166:167], v[12:13], v[76:77] op_sel_hi:[0,1]
	ds_write2_b32 v165, v194, v195 offset1:1
	v_add_u32_e32 v165, 0x28a8, v193
	ds_write2_b32 v165, v166, v167 offset1:1
	v_mov_b32_e32 v166, v13
	v_pk_mul_f32 v[194:195], v[166:167], v[80:81] op_sel_hi:[0,1]
	v_pk_mul_f32 v[166:167], v[166:167], v[78:79] op_sel_hi:[0,1]
	v_add_u32_e32 v165, 0x2cb0, v193
	ds_write2_b32 v165, v166, v167 offset1:1
	v_add_u32_e32 v165, 0x2cb8, v193
	ds_write2_b32 v165, v194, v195 offset1:1
	s_waitcnt vmcnt(2)
	v_pk_mul_f32 v[194:195], v[14:15], v[82:83] op_sel_hi:[0,1]
	v_add_u32_e32 v165, 0x30c0, v193
	v_pk_mul_f32 v[166:167], v[14:15], v[84:85] op_sel_hi:[0,1]
	ds_write2_b32 v165, v194, v195 offset1:1
	v_add_u32_e32 v165, 0x30c8, v193
	ds_write2_b32 v165, v166, v167 offset1:1
	v_mov_b32_e32 v166, v15
	v_pk_mul_f32 v[194:195], v[88:89], v[166:167] op_sel_hi:[1,0]
	v_pk_mul_f32 v[166:167], v[86:87], v[166:167] op_sel_hi:[1,0]
	v_add_u32_e32 v165, 0x34d0, v193
	ds_write2_b32 v165, v166, v167 offset1:1
	v_add_u32_e32 v165, 0x34d8, v193
	ds_write2_b32 v165, v194, v195 offset1:1
	s_waitcnt vmcnt(0)
	v_pk_mul_f32 v[194:195], v[90:91], v[16:17] op_sel_hi:[1,0]
	v_add_u32_e32 v165, 0x38e0, v193
	v_pk_mul_f32 v[166:167], v[92:93], v[16:17] op_sel_hi:[1,0]
	ds_write2_b32 v165, v194, v195 offset1:1
	v_add_u32_e32 v165, 0x38e8, v193
	ds_write2_b32 v165, v166, v167 offset1:1
	v_mov_b32_e32 v166, v17
	v_pk_mul_f32 v[194:195], v[96:97], v[166:167] op_sel_hi:[1,0]
	v_pk_mul_f32 v[166:167], v[94:95], v[166:167] op_sel_hi:[1,0]
	v_add_u32_e32 v165, 0x3cf0, v193
	ds_write2_b32 v165, v166, v167 offset1:1
	v_add_u32_e32 v165, 0x3cf8, v193
	ds_write2_b32 v165, v194, v195 offset1:1
	s_waitcnt lgkmcnt(0)
	ds_read2_b32 v[166:167], v185 offset1:8
	ds_read2_b32 v[200:201], v185 offset0:65 offset1:73
	ds_read2_b32 v[202:203], v185 offset0:130 offset1:138
	ds_read2_b32 v[204:205], v185 offset0:195 offset1:203
	v_add_u32_e32 v198, 0x400, v185
	s_waitcnt lgkmcnt(3)
	v_bfe_u32 v165, v166, 16, 1
	v_add3_u32 v165, v166, v165, s23
	s_waitcnt lgkmcnt(2)
	v_bfe_u32 v166, v200, 16, 1
	ds_read2_b32 v[206:207], v198 offset0:4 offset1:12
	v_lshrrev_b32_e32 v165, 16, v165
	v_add3_u32 v166, v200, v166, s23
	ds_read2_b32 v[208:209], v198 offset0:69 offset1:77
	v_and_or_b32 v194, v166, s28, v165
	s_waitcnt lgkmcnt(3)
	v_bfe_u32 v165, v202, 16, 1
	v_add3_u32 v165, v202, v165, s23
	s_waitcnt lgkmcnt(2)
	v_bfe_u32 v166, v204, 16, 1
	ds_read2_b32 v[210:211], v198 offset0:134 offset1:142
	v_lshrrev_b32_e32 v165, 16, v165
	v_add3_u32 v166, v204, v166, s23
	ds_read2_b32 v[212:213], v198 offset0:199 offset1:207
	v_and_or_b32 v195, v166, s28, v165
	s_waitcnt lgkmcnt(3)
; #define LAS __attribute__((address_space(3)))
; #define LDS_WAIT() asm volatile("s_waitcnt lgkmcnt(0)" ::: "memory")
; __device__ __forceinline__ unsigned pk2(float lo, float hi) { return f2bf(lo) | (f2bf(hi) << 16); }
; __device__ __forceinline__ void ti_store(const TItem& t, const f32x4 (&v)[16], const float (&sc)[16], LAS float* scr, int lane) {
;     const int n4 = (lane & 15) * 4, kq = lane >> 4;
; #pragma unroll
;     for (int i = 0; i < 16; ++i) { const int kk = 4 * i + kq; const f32x4 x = v[i] * sc[i]; LAS float* d = scr + kk * 65 + n4; d[0] = x.x; d[1] = x.y; d[2] = x.z; d[3] = x.w; }
;     LDS_WAIT(); asm volatile("" ::: "memory");
;     const int c = lane & 7;
; #pragma unroll
;     for (int j = 0; j < 8; ++j) { const int n = (lane >> 3) + 8 * j; const LAS float* s = scr + (8 * c) * 65 + n;
;         v4u o; o.x = pk2(s[0 * 65], s[1 * 65]); o.y = pk2(s[2 * 65], s[3 * 65]); o.z = pk2(s[4 * 65], s[5 * 65]); o.w = pk2(s[6 * 65], s[7 * 65]);
;         *(v4u*)(t.WT + (size_t)(t.drow + n) * t.K + t.k0 + 8 * c) = o; }
	v_bfe_u32 v165, v206, 16, 1
	v_add3_u32 v165, v206, v165, s23
	s_waitcnt lgkmcnt(2)
	v_bfe_u32 v166, v208, 16, 1
	v_lshrrev_b32_e32 v165, 16, v165
	v_add3_u32 v166, v208, v166, s23
	v_and_or_b32 v196, v166, s28, v165
	s_waitcnt lgkmcnt(1)
	v_bfe_u32 v165, v210, 16, 1
	v_add3_u32 v165, v210, v165, s23
	s_waitcnt lgkmcnt(0)
	v_bfe_u32 v166, v212, 16, 1
	v_lshrrev_b32_e32 v165, 16, v165
	v_add3_u32 v166, v212, v166, s23
	v_and_or_b32 v197, v166, s28, v165
	v_add_u32_e32 v165, s22, v184
	v_mad_i64_i32 v[214:215], s[6:7], v165, s5, 0
	s_ashr_i32 s13, s12, 31
	v_lshl_add_u64 v[214:215], v[214:215], 1, s[14:15]
	s_lshl_b64 s[6:7], s[12:13], 1
	v_bfe_u32 v166, v167, 16, 1
	v_lshl_add_u64 v[214:215], v[214:215], 0, s[6:7]
	v_mov_b32_e32 v165, v163
	v_add3_u32 v166, v167, v166, s23
	v_bfe_u32 v167, v201, 16, 1
	v_lshl_add_u64 v[214:215], v[214:215], 0, v[164:165]
	v_lshrrev_b32_e32 v166, 16, v166
	v_add3_u32 v167, v201, v167, s23
	global_store_dwordx4 v[214:215], v[194:197], off sc1
	ds_read2_b32 v[200:201], v185 offset0:16 offset1:24
	s_andn2_b64 vcc, exec, s[38:39]
	v_and_or_b32 v194, v167, s28, v166
	v_bfe_u32 v166, v203, 16, 1
	v_add3_u32 v166, v203, v166, s23
	v_bfe_u32 v167, v205, 16, 1
	v_lshrrev_b32_e32 v166, 16, v166
	v_add3_u32 v167, v205, v167, s23
	v_and_or_b32 v195, v167, s28, v166
	v_bfe_u32 v166, v207, 16, 1
	v_add3_u32 v166, v207, v166, s23
	v_bfe_u32 v167, v209, 16, 1
	v_lshrrev_b32_e32 v166, 16, v166
	v_add3_u32 v167, v209, v167, s23
	v_and_or_b32 v196, v167, s28, v166
	v_bfe_u32 v166, v211, 16, 1
	v_add3_u32 v166, v211, v166, s23
	v_bfe_u32 v167, v213, 16, 1
	v_lshrrev_b32_e32 v166, 16, v166
	v_add3_u32 v167, v213, v167, s23
	v_and_or_b32 v197, v167, s28, v166
	v_add_u32_e32 v166, s22, v186
	v_mad_i64_i32 v[166:167], s[36:37], v166, s5, 0
	v_lshl_add_u64 v[166:167], v[166:167], 1, s[14:15]
	v_lshl_add_u64 v[166:167], v[166:167], 0, s[6:7]
	v_lshl_add_u64 v[166:167], v[166:167], 0, v[164:165]
	global_store_dwordx4 v[166:167], v[194:197], off sc1
	ds_read2_b32 v[166:167], v185 offset0:81 offset1:89
	ds_read2_b32 v[202:203], v185 offset0:146 offset1:154
	ds_read2_b32 v[204:205], v185 offset0:211 offset1:219
	s_waitcnt lgkmcnt(3)
	v_bfe_u32 v194, v200, 16, 1
	v_add3_u32 v194, v200, v194, s23
	s_waitcnt lgkmcnt(2)
	v_bfe_u32 v195, v166, 16, 1
	ds_read2_b32 v[206:207], v198 offset0:20 offset1:28
	v_lshrrev_b32_e32 v194, 16, v194
	v_add3_u32 v166, v166, v195, s23
	ds_read2_b32 v[208:209], v198 offset0:85 offset1:93
	v_and_or_b32 v194, v166, s28, v194
	s_waitcnt lgkmcnt(3)
	v_bfe_u32 v166, v202, 16, 1
	v_add3_u32 v166, v202, v166, s23
	s_waitcnt lgkmcnt(2)
	v_bfe_u32 v195, v204, 16, 1
	ds_read2_b32 v[210:211], v198 offset0:150 offset1:158
	v_lshrrev_b32_e32 v166, 16, v166
	v_add3_u32 v195, v204, v195, s23
	ds_read2_b32 v[212:213], v198 offset0:215 offset1:223
	v_and_or_b32 v195, v195, s28, v166
	s_waitcnt lgkmcnt(3)
	v_bfe_u32 v166, v206, 16, 1
	v_add3_u32 v166, v206, v166, s23
	s_waitcnt lgkmcnt(2)
	v_bfe_u32 v196, v208, 16, 1
	v_lshrrev_b32_e32 v166, 16, v166
	v_add3_u32 v196, v208, v196, s23
	v_and_or_b32 v196, v196, s28, v166
	s_waitcnt lgkmcnt(1)
	v_bfe_u32 v166, v210, 16, 1
	v_add3_u32 v166, v210, v166, s23
	s_waitcnt lgkmcnt(0)
	v_bfe_u32 v197, v212, 16, 1
	v_lshrrev_b32_e32 v166, 16, v166
	v_add3_u32 v197, v212, v197, s23
	v_and_or_b32 v197, v197, s28, v166
	v_add_u32_e32 v166, s22, v187
	v_mad_i64_i32 v[214:215], s[36:37], v166, s5, 0
	v_lshl_add_u64 v[214:215], v[214:215], 1, s[14:15]
	v_lshl_add_u64 v[214:215], v[214:215], 0, s[6:7]
	v_lshl_add_u64 v[214:215], v[214:215], 0, v[164:165]
	v_bfe_u32 v166, v201, 16, 1
	global_store_dwordx4 v[214:215], v[194:197], off sc1
	v_add3_u32 v166, v201, v166, s23
	v_lshrrev_b32_e32 v166, 16, v166
	v_bfe_u32 v194, v167, 16, 1
	v_add3_u32 v167, v167, v194, s23
	v_and_or_b32 v194, v167, s28, v166
	v_bfe_u32 v166, v203, 16, 1
	v_add3_u32 v166, v203, v166, s23
	v_bfe_u32 v167, v205, 16, 1
	v_lshrrev_b32_e32 v166, 16, v166
	v_add3_u32 v167, v205, v167, s23
	v_and_or_b32 v195, v167, s28, v166
	v_bfe_u32 v166, v207, 16, 1
	v_add3_u32 v166, v207, v166, s23
	v_bfe_u32 v167, v209, 16, 1
	v_lshrrev_b32_e32 v166, 16, v166
	v_add3_u32 v167, v209, v167, s23
	v_and_or_b32 v196, v167, s28, v166
	v_bfe_u32 v166, v211, 16, 1
	v_add3_u32 v166, v211, v166, s23
	v_bfe_u32 v167, v213, 16, 1
	v_lshrrev_b32_e32 v166, 16, v166
	v_add3_u32 v167, v213, v167, s23
	v_and_or_b32 v197, v167, s28, v166
	v_add_u32_e32 v166, s22, v188
	v_mad_i64_i32 v[166:167], s[36:37], v166, s5, 0
	v_lshl_add_u64 v[166:167], v[166:167], 1, s[14:15]
	v_lshl_add_u64 v[166:167], v[166:167], 0, s[6:7]
	ds_read2_b32 v[200:201], v185 offset0:32 offset1:40
	v_lshl_add_u64 v[166:167], v[166:167], 0, v[164:165]
	global_store_dwordx4 v[166:167], v[194:197], off sc1
	ds_read2_b32 v[166:167], v185 offset0:97 offset1:105
	ds_read2_b32 v[202:203], v185 offset0:162 offset1:170
	ds_read2_b32 v[204:205], v185 offset0:227 offset1:235
	s_waitcnt lgkmcnt(3)
	v_bfe_u32 v194, v200, 16, 1
	v_add3_u32 v194, v200, v194, s23
	s_waitcnt lgkmcnt(2)
	v_bfe_u32 v195, v166, 16, 1
	ds_read2_b32 v[206:207], v198 offset0:36 offset1:44
	v_lshrrev_b32_e32 v194, 16, v194
	v_add3_u32 v166, v166, v195, s23
	ds_read2_b32 v[208:209], v198 offset0:101 offset1:109
	v_and_or_b32 v194, v166, s28, v194
	s_waitcnt lgkmcnt(3)
	v_bfe_u32 v166, v202, 16, 1
	v_add3_u32 v166, v202, v166, s23
	s_waitcnt lgkmcnt(2)
	v_bfe_u32 v195, v204, 16, 1
	ds_read2_b32 v[210:211], v198 offset0:166 offset1:174
	v_lshrrev_b32_e32 v166, 16, v166
	v_add3_u32 v195, v204, v195, s23
	ds_read2_b32 v[212:213], v198 offset0:231 offset1:239
	v_and_or_b32 v195, v195, s28, v166
	s_waitcnt lgkmcnt(3)
; #define LAS __attribute__((address_space(3)))
; #define LDS_WAIT() asm volatile("s_waitcnt lgkmcnt(0)" ::: "memory")
; __device__ __forceinline__ unsigned pk2(float lo, float hi) { return f2bf(lo) | (f2bf(hi) << 16); }
; __device__ __forceinline__ void ti_store(const TItem& t, const f32x4 (&v)[16], const float (&sc)[16], LAS float* scr, int lane) {
;     ...
;     const int c = lane & 7;
; #pragma unroll
;     for (int j = 0; j < 8; ++j) { const int n = (lane >> 3) + 8 * j; const LAS float* s = scr + (8 * c) * 65 + n;
;         v4u o; o.x = pk2(s[0 * 65], s[1 * 65]); o.y = pk2(s[2 * 65], s[3 * 65]); o.z = pk2(s[4 * 65], s[5 * 65]); o.w = pk2(s[6 * 65], s[7 * 65]);
;         *(v4u*)(t.WT + (size_t)(t.drow + n) * t.K + t.k0 + 8 * c) = o; }
;     LDS_WAIT(); asm volatile("" ::: "memory");
; }
; __device__ __forceinline__ void convert_set(Frame& F, int set, int wv, int nw) {
;     if (wv < 0 || wv >= nw) return;
;     LAS float* scr = (LAS float*)(F.lds + RING_OFF + F.wave * 16640);
;     const int n = ti_count(set);
;     int it = wv; if (it >= n) return;
;     TItem cur, nxt; f32x4 vc[16], vn[16]; float sc[16], sn[16];
;     ti_decode(F, set, it, cur); ti_load(cur, vc, sc, F.lane);
;     for (;;) {
;         const int itn = it + nw; const bool hn = itn < n;
;         if (hn) { ti_decode(F, set, itn, nxt); ti_load(nxt, vn, sn, F.lane); }
;         ti_store(cur, vc, sc, scr, F.lane);
;         if (!hn) break;
;         cur = nxt; it = itn;
; #pragma unroll
;         for (int i = 0; i < 16; ++i) { vc[i] = vn[i]; sc[i] = sn[i]; }
	v_bfe_u32 v166, v206, 16, 1
	v_add3_u32 v166, v206, v166, s23
	s_waitcnt lgkmcnt(2)
	v_bfe_u32 v196, v208, 16, 1
	v_lshrrev_b32_e32 v166, 16, v166
	v_add3_u32 v196, v208, v196, s23
	v_and_or_b32 v196, v196, s28, v166
	s_waitcnt lgkmcnt(1)
	v_bfe_u32 v166, v210, 16, 1
	v_add3_u32 v166, v210, v166, s23
	s_waitcnt lgkmcnt(0)
	v_bfe_u32 v197, v212, 16, 1
	v_lshrrev_b32_e32 v166, 16, v166
	v_add3_u32 v197, v212, v197, s23
	v_and_or_b32 v197, v197, s28, v166
	v_add_u32_e32 v166, s22, v189
	v_mad_i64_i32 v[214:215], s[36:37], v166, s5, 0
	v_lshl_add_u64 v[214:215], v[214:215], 1, s[14:15]
	v_lshl_add_u64 v[214:215], v[214:215], 0, s[6:7]
	v_lshl_add_u64 v[214:215], v[214:215], 0, v[164:165]
	v_bfe_u32 v166, v201, 16, 1
	global_store_dwordx4 v[214:215], v[194:197], off sc1
	v_add3_u32 v166, v201, v166, s23
	v_lshrrev_b32_e32 v166, 16, v166
	v_bfe_u32 v194, v167, 16, 1
	v_add3_u32 v167, v167, v194, s23
	v_and_or_b32 v194, v167, s28, v166
	v_bfe_u32 v166, v203, 16, 1
	v_add3_u32 v166, v203, v166, s23
	v_bfe_u32 v167, v205, 16, 1
	v_lshrrev_b32_e32 v166, 16, v166
	v_add3_u32 v167, v205, v167, s23
	v_and_or_b32 v195, v167, s28, v166
	v_bfe_u32 v166, v207, 16, 1
	v_add3_u32 v166, v207, v166, s23
	v_bfe_u32 v167, v209, 16, 1
	v_lshrrev_b32_e32 v166, 16, v166
	v_add3_u32 v167, v209, v167, s23
	v_and_or_b32 v196, v167, s28, v166
	v_bfe_u32 v166, v211, 16, 1
	v_add3_u32 v166, v211, v166, s23
	v_bfe_u32 v167, v213, 16, 1
	v_lshrrev_b32_e32 v166, 16, v166
	v_add3_u32 v167, v213, v167, s23
	v_and_or_b32 v197, v167, s28, v166
	v_add_u32_e32 v166, s22, v190
	v_mad_i64_i32 v[166:167], s[36:37], v166, s5, 0
	v_lshl_add_u64 v[166:167], v[166:167], 1, s[14:15]
	v_lshl_add_u64 v[166:167], v[166:167], 0, s[6:7]
	ds_read2_b32 v[200:201], v185 offset0:48 offset1:56
	v_lshl_add_u64 v[166:167], v[166:167], 0, v[164:165]
	global_store_dwordx4 v[166:167], v[194:197], off sc1
	ds_read2_b32 v[166:167], v185 offset0:113 offset1:121
	ds_read2_b32 v[202:203], v185 offset0:178 offset1:186
	ds_read2_b32 v[204:205], v185 offset0:243 offset1:251
	s_waitcnt lgkmcnt(3)
	v_bfe_u32 v194, v200, 16, 1
	v_add3_u32 v194, v200, v194, s23
	s_waitcnt lgkmcnt(2)
	v_bfe_u32 v195, v166, 16, 1
	ds_read2_b32 v[206:207], v198 offset0:52 offset1:60
	v_lshrrev_b32_e32 v194, 16, v194
	v_add3_u32 v166, v166, v195, s23
	ds_read2_b32 v[208:209], v198 offset0:117 offset1:125
	v_and_or_b32 v194, v166, s28, v194
	s_waitcnt lgkmcnt(3)
	v_bfe_u32 v166, v202, 16, 1
	v_add3_u32 v166, v202, v166, s23
	s_waitcnt lgkmcnt(2)
	v_bfe_u32 v195, v204, 16, 1
	ds_read2_b32 v[210:211], v198 offset0:182 offset1:190
	v_lshrrev_b32_e32 v166, 16, v166
	v_add3_u32 v195, v204, v195, s23
	ds_read2_b32 v[212:213], v198 offset0:247 offset1:255
	v_and_or_b32 v195, v195, s28, v166
	s_waitcnt lgkmcnt(3)
	v_bfe_u32 v166, v206, 16, 1
	v_add3_u32 v166, v206, v166, s23
	s_waitcnt lgkmcnt(2)
	v_bfe_u32 v196, v208, 16, 1
	v_lshrrev_b32_e32 v166, 16, v166
	v_add3_u32 v196, v208, v196, s23
	v_and_or_b32 v196, v196, s28, v166
	s_waitcnt lgkmcnt(1)
	v_bfe_u32 v166, v210, 16, 1
	v_add3_u32 v166, v210, v166, s23
	s_waitcnt lgkmcnt(0)
	v_bfe_u32 v197, v212, 16, 1
	v_lshrrev_b32_e32 v166, 16, v166
	v_add3_u32 v197, v212, v197, s23
	v_and_or_b32 v197, v197, s28, v166
	v_add_u32_e32 v166, s22, v191
	v_mad_i64_i32 v[214:215], s[36:37], v166, s5, 0
	v_lshl_add_u64 v[214:215], v[214:215], 1, s[14:15]
	v_lshl_add_u64 v[214:215], v[214:215], 0, s[6:7]
	v_lshl_add_u64 v[214:215], v[214:215], 0, v[164:165]
	v_bfe_u32 v166, v201, 16, 1
	global_store_dwordx4 v[214:215], v[194:197], off sc1
	v_add3_u32 v166, v201, v166, s23
	v_lshrrev_b32_e32 v166, 16, v166
	v_bfe_u32 v194, v167, 16, 1
	v_add3_u32 v167, v167, v194, s23
	v_and_or_b32 v194, v167, s28, v166
	v_bfe_u32 v166, v203, 16, 1
	v_add3_u32 v166, v203, v166, s23
	v_bfe_u32 v167, v205, 16, 1
	v_lshrrev_b32_e32 v166, 16, v166
	v_add3_u32 v167, v205, v167, s23
	v_and_or_b32 v195, v167, s28, v166
	v_bfe_u32 v166, v207, 16, 1
	v_add3_u32 v166, v207, v166, s23
	v_bfe_u32 v167, v209, 16, 1
	v_lshrrev_b32_e32 v166, 16, v166
	v_add3_u32 v167, v209, v167, s23
	v_and_or_b32 v196, v167, s28, v166
	v_bfe_u32 v166, v211, 16, 1
	v_add3_u32 v166, v211, v166, s23
	v_bfe_u32 v167, v213, 16, 1
	v_lshrrev_b32_e32 v166, 16, v166
	v_add3_u32 v167, v213, v167, s23
	v_and_or_b32 v197, v167, s28, v166
	v_add_u32_e32 v166, s22, v192
	v_mad_i64_i32 v[166:167], s[36:37], v166, s5, 0
	v_lshl_add_u64 v[166:167], v[166:167], 1, s[14:15]
	v_lshl_add_u64 v[166:167], v[166:167], 0, s[6:7]
	v_lshl_add_u64 v[166:167], v[166:167], 0, v[164:165]
	global_store_dwordx4 v[166:167], v[194:197], off sc1
	s_waitcnt lgkmcnt(0)
	s_cbranch_vccnz .LBB0_1776
	v_mov_b64_e32 v[2:3], v[18:19]
	v_mov_b64_e32 v[94:95], v[158:159]
	v_mov_b64_e32 v[90:91], v[154:155]
	v_mov_b64_e32 v[86:87], v[150:151]
	v_mov_b64_e32 v[82:83], v[146:147]
	v_mov_b64_e32 v[78:79], v[142:143]
	v_mov_b64_e32 v[74:75], v[138:139]
	v_mov_b64_e32 v[70:71], v[134:135]
	v_mov_b64_e32 v[66:67], v[130:131]
	v_mov_b64_e32 v[62:63], v[126:127]
	v_mov_b64_e32 v[58:59], v[122:123]
	v_mov_b64_e32 v[54:55], v[118:119]
	v_mov_b64_e32 v[50:51], v[114:115]
	v_mov_b64_e32 v[46:47], v[110:111]
	v_mov_b64_e32 v[42:43], v[106:107]
	v_mov_b64_e32 v[38:39], v[102:103]
	v_mov_b64_e32 v[34:35], v[98:99]
	v_mov_b64_e32 v[4:5], v[20:21]
	v_mov_b64_e32 v[6:7], v[22:23]
	v_mov_b64_e32 v[8:9], v[24:25]
	v_mov_b64_e32 v[10:11], v[26:27]
	v_mov_b64_e32 v[12:13], v[28:29]
	v_mov_b64_e32 v[14:15], v[30:31]
	v_mov_b64_e32 v[16:17], v[32:33]
	v_mov_b64_e32 v[96:97], v[160:161]
	v_mov_b64_e32 v[92:93], v[156:157]
	v_mov_b64_e32 v[88:89], v[152:153]
	v_mov_b64_e32 v[84:85], v[148:149]
	v_mov_b64_e32 v[80:81], v[144:145]
	v_mov_b64_e32 v[76:77], v[140:141]
	v_mov_b64_e32 v[72:73], v[136:137]
	v_mov_b64_e32 v[68:69], v[132:133]
	v_mov_b64_e32 v[64:65], v[128:129]
	v_mov_b64_e32 v[60:61], v[124:125]
	v_mov_b64_e32 v[56:57], v[120:121]
	v_mov_b64_e32 v[52:53], v[116:117]
	v_mov_b64_e32 v[48:49], v[112:113]
	v_mov_b64_e32 v[44:45], v[108:109]
	v_mov_b64_e32 v[40:41], v[104:105]
	v_mov_b64_e32 v[36:37], v[100:101]
	s_mov_b32 s12, s29
	s_mov_b32 s22, s31
	s_mov_b32 s5, s30
	s_mov_b64 s[14:15], s[18:19]
	s_mov_b32 s4, s33
	s_branch .LBB0_1776

; __device__ __forceinline__ unsigned cvt_pk_bf16(float lo, float hi) { unsigned r; asm volatile("v_cvt_pk_bf16_f32 %0, %1, %2" : "=v"(r) : "v"(lo), "v"(hi)); return r; }
;     __device__ __forceinline__ void operator()(const f32x4 (&acc)[2][2][4][2], const Unit& u, int wr, int wc, int fr, int fq) const {
;     ...
;             for (int m = 0; m < 4; ++m) { const int r = u.pm * BM + ai * HALF + wr * 64 + m * 16 + fr; float ss = 0.f;
; #pragma unroll
;                 for (int bj = 0; bj < 2; ++bj) { const int c8 = u.pn * BM + bj * HALF + wc * 32 + 8 * fq; const size_t off = (size_t)r * ldc + c8;
;                     float b[8];
;                     if (BF) { const u32x4 w = *(const u32x4*)((const bf16_t*)base + off); b[0] = bflo(w.x); b[1] = bfhi(w.x); b[2] = bflo(w.y); b[3] = bfhi(w.y); b[4] = bflo(w.z); b[5] = bfhi(w.z); b[6] = bflo(w.w); b[7] = bfhi(w.w); }
;                     else { const f32x4 b0 = __builtin_nontemporal_load((const f32x4*)((const float*)base + off)), b1 = __builtin_nontemporal_load((const f32x4*)((const float*)base + off + 4)); b[0] = b0[0]; b[1] = b0[1]; b[2] = b0[2]; b[3] = b0[3]; b[4] = b1[0]; b[5] = b1[1]; b[6] = b1[2]; b[7] = b1[3]; }
;                     float h[8];
; #pragma unroll
;                     for (int j = 0; j < 4; ++j) { h[j] = b[j] + acc[ai][bj][m][0][j]; h[4 + j] = b[4 + j] + acc[ai][bj][m][1][j]; }
; #pragma unroll
;                     for (int j = 0; j < 8; ++j) ss += h[j] * h[j];
;                     u32x4 w; w.x = cvt_pk_bf16(h[0], h[1]); w.y = cvt_pk_bf16(h[2], h[3]); w.z = cvt_pk_bf16(h[4], h[5]); w.w = cvt_pk_bf16(h[6], h[7]);
;                     *(u32x4*)(Hb + off) = w; }
;                 ss += __shfl_xor(ss, 16); ss += __shfl_xor(ss, 32);
;                 if (fq == 0) unsafeAtomicAdd(sumsq + r, ss); }
.LBB0_1962:
	s_lshl_b32 s2, s62, 8
	v_mov_b32_e32 v146, v1
	v_mov_b32_e32 v168, v152
	s_add_i32 s2, s2, s54
	s_nop 0
	v_add_u32_e32 v148, s2, v146
	s_lshl_b32 s2, s61, 8
	s_or_b32 s2, s2, s55
	v_lshl_add_u32 v146, v168, 3, s2
	v_ashrrev_i32_e32 v149, 31, v148
	v_lshlrev_b64 v[162:163], 11, v[148:149]
	v_ashrrev_i32_e32 v147, 31, v146
	v_lshl_add_u64 v[150:151], v[162:163], 0, v[146:147]
	v_lshlrev_b64 v[164:165], 1, v[150:151]
	v_lshl_add_u64 v[150:151], s[18:19], 0, v[164:165]
	global_load_dwordx4 v[158:161], v[150:151], off
	v_add_u32_e32 v150, 0x80, v146
	v_ashrrev_i32_e32 v151, 31, v150
	v_lshl_add_u64 v[162:163], v[162:163], 0, v[150:151]
	v_lshlrev_b64 v[162:163], 1, v[162:163]
	v_lshl_add_u64 v[164:165], s[20:21], 0, v[164:165]
	v_lshl_add_u64 v[166:167], s[18:19], 0, v[162:163]
	v_cmp_eq_u32_e32 vcc, 0, v168
	s_waitcnt vmcnt(0)
	v_lshlrev_b32_e32 v169, 16, v158
	v_and_b32_e32 v158, 0xffff0000, v158
	v_lshlrev_b32_e32 v170, 16, v159
	v_and_b32_e32 v159, 0xffff0000, v159
	v_lshlrev_b32_e32 v171, 16, v160
	v_and_b32_e32 v160, 0xffff0000, v160
	v_lshlrev_b32_e32 v172, 16, v161
	v_and_b32_e32 v161, 0xffff0000, v161
	v_add_f32_e32 v169, v122, v169
	v_add_f32_e32 v171, v126, v171
	v_add_f32_e32 v158, v123, v158
	v_add_f32_e32 v160, v127, v160
	v_add_f32_e32 v170, v124, v170
	v_add_f32_e32 v128, v128, v172
	v_add_f32_e32 v159, v125, v159
	v_add_f32_e32 v129, v129, v161
	v_cvt_pk_bf16_f32 v122, v169, v158
	v_cvt_pk_bf16_f32 v123, v170, v159
	v_cvt_pk_bf16_f32 v124, v171, v160
	v_cvt_pk_bf16_f32 v125, v128, v129
	global_store_dwordx4 v[164:165], v[122:125], off sc1
	global_load_dwordx4 v[124:127], v[166:167], off
	v_mul_f32_e32 v158, v158, v158
	v_fmac_f32_e32 v158, v169, v169
	v_fmac_f32_e32 v158, v170, v170
	v_fmac_f32_e32 v158, v159, v159
	v_fmac_f32_e32 v158, v171, v171
	v_fmac_f32_e32 v158, v160, v160
	v_fmac_f32_e32 v158, v128, v128
	v_fmac_f32_e32 v158, v129, v129
	v_and_b32_e32 v123, 64, v157
	v_xor_b32_e32 v122, 16, v157
	v_add_u32_e32 v123, 64, v123
	v_cmp_lt_i32_e64 s[8:9], v122, v123
	v_xor_b32_e32 v161, 32, v157
	s_waitcnt vmcnt(0)
	v_lshlrev_b32_e32 v128, 16, v124
	v_and_b32_e32 v124, 0xffff0000, v124
	v_lshlrev_b32_e32 v159, 16, v126
	v_add_f32_e32 v118, v118, v128
	v_lshlrev_b32_e32 v129, 16, v125
	v_and_b32_e32 v126, 0xffff0000, v126
	v_add_f32_e32 v128, v114, v159
	v_add_f32_e32 v114, v119, v124
	v_fmac_f32_e32 v158, v118, v118
	v_and_b32_e32 v125, 0xffff0000, v125
	v_lshlrev_b32_e32 v160, 16, v127
	v_add_f32_e32 v124, v115, v126
	v_add_f32_e32 v115, v120, v129
	v_fmac_f32_e32 v158, v114, v114
	v_add_f32_e32 v126, v116, v160
	v_add_f32_e32 v116, v121, v125
	v_fmac_f32_e32 v158, v115, v115
	v_fmac_f32_e32 v158, v116, v116
	v_fmac_f32_e32 v158, v128, v128
	v_and_b32_e32 v127, 0xffff0000, v127
	v_fmac_f32_e32 v158, v124, v124
	v_cndmask_b32_e64 v122, v157, v122, s[8:9]
	v_add_f32_e32 v117, v117, v127
	v_fmac_f32_e32 v158, v126, v126
	v_lshlrev_b32_e32 v122, 2, v122
	v_fmac_f32_e32 v158, v117, v117
	ds_bpermute_b32 v120, v122, v158
	v_cmp_lt_i32_e64 s[8:9], v161, v123
	v_cvt_pk_bf16_f32 v118, v118, v114
	v_cvt_pk_bf16_f32 v119, v115, v116
	s_waitcnt lgkmcnt(0)
	v_add_f32_e32 v114, v158, v120
	v_cndmask_b32_e64 v121, v157, v161, s[8:9]
	v_lshlrev_b32_e32 v116, 2, v121
	ds_bpermute_b32 v115, v116, v114
	v_cvt_pk_bf16_f32 v120, v128, v124
	v_lshl_add_u64 v[124:125], s[20:21], 0, v[162:163]
	v_cvt_pk_bf16_f32 v121, v126, v117
	global_store_dwordx4 v[124:125], v[118:121], off sc1
	s_and_saveexec_b64 s[8:9], vcc
	s_cbranch_execz .LBB0_1964
	v_lshl_add_u64 v[118:119], v[148:149], 2, s[12:13]
	s_waitcnt lgkmcnt(0)
	v_add_f32_e32 v114, v114, v115
	global_atomic_add_f32 v[118:119], v114, off
.LBB0_1964:
	s_or_b64 exec, exec, s[8:9]
	v_add_u32_e32 v114, 16, v148
	s_waitcnt lgkmcnt(0)
	v_ashrrev_i32_e32 v115, 31, v114
	v_lshlrev_b64 v[124:125], 11, v[114:115]
	v_lshl_add_u64 v[118:119], v[124:125], 0, v[146:147]
	v_lshlrev_b64 v[126:127], 1, v[118:119]
	v_lshl_add_u64 v[118:119], s[18:19], 0, v[126:127]
	global_load_dwordx4 v[118:121], v[118:119], off
	v_lshl_add_u64 v[124:125], v[124:125], 0, v[150:151]
	v_lshlrev_b64 v[124:125], 1, v[124:125]
	v_lshl_add_u64 v[126:127], s[20:21], 0, v[126:127]
	v_lshl_add_u64 v[128:129], s[18:19], 0, v[124:125]
	s_waitcnt vmcnt(0)
	v_lshlrev_b32_e32 v117, 16, v118
	v_and_b32_e32 v118, 0xffff0000, v118
	v_lshlrev_b32_e32 v123, 16, v119
	v_and_b32_e32 v119, 0xffff0000, v119
	v_lshlrev_b32_e32 v149, 16, v120
	v_and_b32_e32 v120, 0xffff0000, v120
	v_lshlrev_b32_e32 v158, 16, v121
	v_and_b32_e32 v121, 0xffff0000, v121
	v_add_f32_e32 v110, v110, v117
	v_add_f32_e32 v117, v106, v149
	v_add_f32_e32 v111, v111, v118
	v_add_f32_e32 v118, v107, v120
	v_add_f32_e32 v112, v112, v123
	v_add_f32_e32 v120, v108, v158
	v_add_f32_e32 v113, v113, v119
	v_add_f32_e32 v119, v109, v121
	v_cvt_pk_bf16_f32 v106, v110, v111
	v_cvt_pk_bf16_f32 v107, v112, v113
	v_cvt_pk_bf16_f32 v108, v117, v118
	v_cvt_pk_bf16_f32 v109, v120, v119
	global_store_dwordx4 v[126:127], v[106:109], off sc1
	global_load_dwordx4 v[106:109], v[128:129], off
	v_mul_f32_e32 v111, v111, v111
	v_fmac_f32_e32 v111, v110, v110
	v_fmac_f32_e32 v111, v112, v112
	v_fmac_f32_e32 v111, v113, v113
	v_fmac_f32_e32 v111, v117, v117
	v_fmac_f32_e32 v111, v118, v118
	v_fmac_f32_e32 v111, v120, v120
	v_fmac_f32_e32 v111, v119, v119
	s_waitcnt vmcnt(0)
	v_lshlrev_b32_e32 v110, 16, v106
	v_and_b32_e32 v106, 0xffff0000, v106
	v_lshlrev_b32_e32 v113, 16, v108
	v_add_f32_e32 v102, v102, v110
	v_lshlrev_b32_e32 v112, 16, v107
	v_and_b32_e32 v108, 0xffff0000, v108
	v_add_f32_e32 v110, v98, v113
	v_add_f32_e32 v98, v103, v106
	v_fmac_f32_e32 v111, v102, v102
	v_and_b32_e32 v107, 0xffff0000, v107
	v_add_f32_e32 v103, v99, v108
	v_add_f32_e32 v99, v104, v112
	v_fmac_f32_e32 v111, v98, v98
	v_add_f32_e32 v105, v105, v107
	v_fmac_f32_e32 v111, v99, v99
	v_fmac_f32_e32 v111, v105, v105
	v_lshlrev_b32_e32 v117, 16, v109
	v_fmac_f32_e32 v111, v110, v110
	v_and_b32_e32 v109, 0xffff0000, v109
	v_add_f32_e32 v104, v100, v117
	v_fmac_f32_e32 v111, v103, v103
	v_add_f32_e32 v106, v101, v109
	v_fmac_f32_e32 v111, v104, v104
	v_fmac_f32_e32 v111, v106, v106
	ds_bpermute_b32 v107, v122, v111
	v_cvt_pk_bf16_f32 v100, v102, v98
	v_cvt_pk_bf16_f32 v101, v99, v105
	v_cvt_pk_bf16_f32 v102, v110, v103
	v_cvt_pk_bf16_f32 v103, v104, v106
	s_waitcnt lgkmcnt(0)
	v_add_f32_e32 v98, v111, v107
	ds_bpermute_b32 v99, v116, v98
	v_lshl_add_u64 v[104:105], s[20:21], 0, v[124:125]
	global_store_dwordx4 v[104:105], v[100:103], off sc1
	s_and_saveexec_b64 s[8:9], vcc
	s_cbranch_execz .LBB0_1966
	v_lshl_add_u64 v[100:101], v[114:115], 2, s[12:13]
	s_waitcnt lgkmcnt(0)
	v_add_f32_e32 v98, v98, v99
	global_atomic_add_f32 v[100:101], v98, off
; __device__ __forceinline__ unsigned cvt_pk_bf16(float lo, float hi) { unsigned r; asm volatile("v_cvt_pk_bf16_f32 %0, %1, %2" : "=v"(r) : "v"(lo), "v"(hi)); return r; }
;     __device__ __forceinline__ void operator()(const f32x4 (&acc)[2][2][4][2], const Unit& u, int wr, int wc, int fr, int fq) const {
;     ...
;             for (int m = 0; m < 4; ++m) { const int r = u.pm * BM + ai * HALF + wr * 64 + m * 16 + fr; float ss = 0.f;
; #pragma unroll
;                 for (int bj = 0; bj < 2; ++bj) { const int c8 = u.pn * BM + bj * HALF + wc * 32 + 8 * fq; const size_t off = (size_t)r * ldc + c8;
;                     float b[8];
;                     if (BF) { const u32x4 w = *(const u32x4*)((const bf16_t*)base + off); b[0] = bflo(w.x); b[1] = bfhi(w.x); b[2] = bflo(w.y); b[3] = bfhi(w.y); b[4] = bflo(w.z); b[5] = bfhi(w.z); b[6] = bflo(w.w); b[7] = bfhi(w.w); }
;                     else { const f32x4 b0 = __builtin_nontemporal_load((const f32x4*)((const float*)base + off)), b1 = __builtin_nontemporal_load((const f32x4*)((const float*)base + off + 4)); b[0] = b0[0]; b[1] = b0[1]; b[2] = b0[2]; b[3] = b0[3]; b[4] = b1[0]; b[5] = b1[1]; b[6] = b1[2]; b[7] = b1[3]; }
;                     float h[8];
; #pragma unroll
;                     for (int j = 0; j < 4; ++j) { h[j] = b[j] + acc[ai][bj][m][0][j]; h[4 + j] = b[4 + j] + acc[ai][bj][m][1][j]; }
; #pragma unroll
;                     for (int j = 0; j < 8; ++j) ss += h[j] * h[j];
;                     u32x4 w; w.x = cvt_pk_bf16(h[0], h[1]); w.y = cvt_pk_bf16(h[2], h[3]); w.z = cvt_pk_bf16(h[4], h[5]); w.w = cvt_pk_bf16(h[6], h[7]);
;                     *(u32x4*)(Hb + off) = w; }
;                 ss += __shfl_xor(ss, 16); ss += __shfl_xor(ss, 32);
;                 if (fq == 0) unsafeAtomicAdd(sumsq + r, ss); }
.LBB0_1966:
	s_or_b64 exec, exec, s[8:9]
	v_add_u32_e32 v98, 32, v148
	s_waitcnt lgkmcnt(0)
	v_ashrrev_i32_e32 v99, 31, v98
	v_lshlrev_b64 v[104:105], 11, v[98:99]
	v_lshl_add_u64 v[100:101], v[104:105], 0, v[146:147]
	v_lshlrev_b64 v[106:107], 1, v[100:101]
	v_lshl_add_u64 v[100:101], s[18:19], 0, v[106:107]
	global_load_dwordx4 v[100:103], v[100:101], off
	v_lshl_add_u64 v[104:105], v[104:105], 0, v[150:151]
	v_lshlrev_b64 v[104:105], 1, v[104:105]
	v_lshl_add_u64 v[106:107], s[20:21], 0, v[106:107]
	v_lshl_add_u64 v[108:109], s[18:19], 0, v[104:105]
	s_waitcnt vmcnt(0)
	v_lshlrev_b32_e32 v110, 16, v100
	v_and_b32_e32 v100, 0xffff0000, v100
	v_lshlrev_b32_e32 v111, 16, v101
	v_and_b32_e32 v101, 0xffff0000, v101
	v_lshlrev_b32_e32 v112, 16, v102
	v_and_b32_e32 v102, 0xffff0000, v102
	v_lshlrev_b32_e32 v113, 16, v103
	v_and_b32_e32 v103, 0xffff0000, v103
	v_add_f32_e32 v94, v94, v110
	v_add_f32_e32 v110, v90, v112
	v_add_f32_e32 v95, v95, v100
	v_add_f32_e32 v100, v91, v102
	v_add_f32_e32 v96, v96, v111
	v_add_f32_e32 v102, v92, v113
	v_add_f32_e32 v97, v97, v101
	v_add_f32_e32 v101, v93, v103
	v_cvt_pk_bf16_f32 v90, v94, v95
	v_cvt_pk_bf16_f32 v91, v96, v97
	v_cvt_pk_bf16_f32 v92, v110, v100
	v_cvt_pk_bf16_f32 v93, v102, v101
	global_store_dwordx4 v[106:107], v[90:93], off sc1
	global_load_dwordx4 v[90:93], v[108:109], off
	v_mul_f32_e32 v95, v95, v95
	v_fmac_f32_e32 v95, v94, v94
	v_fmac_f32_e32 v95, v96, v96
	v_fmac_f32_e32 v95, v97, v97
	v_fmac_f32_e32 v95, v110, v110
	v_fmac_f32_e32 v95, v100, v100
	v_fmac_f32_e32 v95, v102, v102
	v_fmac_f32_e32 v95, v101, v101
	s_waitcnt vmcnt(0)
	v_lshlrev_b32_e32 v94, 16, v90
	v_and_b32_e32 v90, 0xffff0000, v90
	v_lshlrev_b32_e32 v97, 16, v92
	v_add_f32_e32 v86, v86, v94
	v_lshlrev_b32_e32 v96, 16, v91
	v_and_b32_e32 v92, 0xffff0000, v92
	v_add_f32_e32 v94, v82, v97
	v_add_f32_e32 v82, v87, v90
	v_fmac_f32_e32 v95, v86, v86
	v_and_b32_e32 v91, 0xffff0000, v91
	v_add_f32_e32 v87, v83, v92
	v_add_f32_e32 v83, v88, v96
	v_fmac_f32_e32 v95, v82, v82
	v_add_f32_e32 v89, v89, v91
	v_fmac_f32_e32 v95, v83, v83
	v_fmac_f32_e32 v95, v89, v89
	v_lshlrev_b32_e32 v100, 16, v93
	v_fmac_f32_e32 v95, v94, v94
	v_and_b32_e32 v93, 0xffff0000, v93
	v_add_f32_e32 v88, v84, v100
	v_fmac_f32_e32 v95, v87, v87
	v_add_f32_e32 v90, v85, v93
	v_fmac_f32_e32 v95, v88, v88
	v_fmac_f32_e32 v95, v90, v90
	ds_bpermute_b32 v91, v122, v95
	v_cvt_pk_bf16_f32 v84, v86, v82
	v_cvt_pk_bf16_f32 v85, v83, v89
	v_cvt_pk_bf16_f32 v86, v94, v87
	v_cvt_pk_bf16_f32 v87, v88, v90
	s_waitcnt lgkmcnt(0)
	v_add_f32_e32 v82, v95, v91
	ds_bpermute_b32 v83, v116, v82
	v_lshl_add_u64 v[88:89], s[20:21], 0, v[104:105]
	global_store_dwordx4 v[88:89], v[84:87], off sc1
	s_and_saveexec_b64 s[8:9], vcc
	s_cbranch_execz .LBB0_1968
	v_lshl_add_u64 v[84:85], v[98:99], 2, s[12:13]
	s_waitcnt lgkmcnt(0)
	v_add_f32_e32 v82, v82, v83
	global_atomic_add_f32 v[84:85], v82, off
.LBB0_1968:
	s_or_b64 exec, exec, s[8:9]
	v_add_u32_e32 v82, 48, v148
	s_waitcnt lgkmcnt(0)
	v_ashrrev_i32_e32 v83, 31, v82
	v_lshlrev_b64 v[88:89], 11, v[82:83]
	v_lshl_add_u64 v[84:85], v[88:89], 0, v[146:147]
	v_lshlrev_b64 v[90:91], 1, v[84:85]
	v_lshl_add_u64 v[84:85], s[18:19], 0, v[90:91]
	global_load_dwordx4 v[84:87], v[84:85], off
	v_lshl_add_u64 v[88:89], v[88:89], 0, v[150:151]
	v_lshlrev_b64 v[88:89], 1, v[88:89]
	v_lshl_add_u64 v[90:91], s[20:21], 0, v[90:91]
	v_lshl_add_u64 v[92:93], s[18:19], 0, v[88:89]
	s_waitcnt vmcnt(0)
	v_lshlrev_b32_e32 v94, 16, v84
	v_and_b32_e32 v84, 0xffff0000, v84
	v_lshlrev_b32_e32 v95, 16, v85
	v_and_b32_e32 v85, 0xffff0000, v85
	v_lshlrev_b32_e32 v96, 16, v86
	v_and_b32_e32 v86, 0xffff0000, v86
	v_lshlrev_b32_e32 v97, 16, v87
	v_and_b32_e32 v87, 0xffff0000, v87
	v_add_f32_e32 v78, v78, v94
	v_add_f32_e32 v94, v74, v96
	v_add_f32_e32 v79, v79, v84
	v_add_f32_e32 v84, v75, v86
	v_add_f32_e32 v80, v80, v95
	v_add_f32_e32 v86, v76, v97
	v_add_f32_e32 v81, v81, v85
	v_add_f32_e32 v85, v77, v87
	v_cvt_pk_bf16_f32 v74, v78, v79
	v_cvt_pk_bf16_f32 v75, v80, v81
	v_cvt_pk_bf16_f32 v76, v94, v84
	v_cvt_pk_bf16_f32 v77, v86, v85
	global_store_dwordx4 v[90:91], v[74:77], off sc1
	global_load_dwordx4 v[74:77], v[92:93], off
	v_mul_f32_e32 v79, v79, v79
	v_fmac_f32_e32 v79, v78, v78
	v_fmac_f32_e32 v79, v80, v80
	v_fmac_f32_e32 v79, v81, v81
	v_fmac_f32_e32 v79, v94, v94
	v_fmac_f32_e32 v79, v84, v84
	v_fmac_f32_e32 v79, v86, v86
	v_fmac_f32_e32 v79, v85, v85
	s_waitcnt vmcnt(0)
	v_lshlrev_b32_e32 v78, 16, v74
	v_and_b32_e32 v74, 0xffff0000, v74
	v_lshlrev_b32_e32 v81, 16, v76
	v_add_f32_e32 v70, v70, v78
	v_lshlrev_b32_e32 v80, 16, v75
	v_and_b32_e32 v76, 0xffff0000, v76
	v_add_f32_e32 v78, v66, v81
	v_add_f32_e32 v66, v71, v74
	v_fmac_f32_e32 v79, v70, v70
	v_and_b32_e32 v75, 0xffff0000, v75
	v_add_f32_e32 v71, v67, v76
	v_add_f32_e32 v67, v72, v80
	v_fmac_f32_e32 v79, v66, v66
	v_add_f32_e32 v73, v73, v75
	v_fmac_f32_e32 v79, v67, v67
	v_fmac_f32_e32 v79, v73, v73
	v_lshlrev_b32_e32 v84, 16, v77
	v_fmac_f32_e32 v79, v78, v78
	v_and_b32_e32 v77, 0xffff0000, v77
	v_add_f32_e32 v72, v68, v84
	v_fmac_f32_e32 v79, v71, v71
	v_add_f32_e32 v74, v69, v77
	v_fmac_f32_e32 v79, v72, v72
	v_fmac_f32_e32 v79, v74, v74
	ds_bpermute_b32 v75, v122, v79
	v_cvt_pk_bf16_f32 v68, v70, v66
	v_cvt_pk_bf16_f32 v69, v67, v73
	v_cvt_pk_bf16_f32 v70, v78, v71
	v_cvt_pk_bf16_f32 v71, v72, v74
	s_waitcnt lgkmcnt(0)
	v_add_f32_e32 v66, v79, v75
	ds_bpermute_b32 v67, v116, v66
	v_lshl_add_u64 v[72:73], s[20:21], 0, v[88:89]
	global_store_dwordx4 v[72:73], v[68:71], off sc1
	s_and_saveexec_b64 s[8:9], vcc
	s_cbranch_execz .LBB0_1970
	v_lshl_add_u64 v[68:69], v[82:83], 2, s[12:13]
	s_waitcnt lgkmcnt(0)
	v_add_f32_e32 v66, v66, v67
	global_atomic_add_f32 v[68:69], v66, off
; __device__ __forceinline__ unsigned cvt_pk_bf16(float lo, float hi) { unsigned r; asm volatile("v_cvt_pk_bf16_f32 %0, %1, %2" : "=v"(r) : "v"(lo), "v"(hi)); return r; }
;     __device__ __forceinline__ void operator()(const f32x4 (&acc)[2][2][4][2], const Unit& u, int wr, int wc, int fr, int fq) const {
;     ...
;             for (int m = 0; m < 4; ++m) { const int r = u.pm * BM + ai * HALF + wr * 64 + m * 16 + fr; float ss = 0.f;
; #pragma unroll
;                 for (int bj = 0; bj < 2; ++bj) { const int c8 = u.pn * BM + bj * HALF + wc * 32 + 8 * fq; const size_t off = (size_t)r * ldc + c8;
;                     float b[8];
;                     if (BF) { const u32x4 w = *(const u32x4*)((const bf16_t*)base + off); b[0] = bflo(w.x); b[1] = bfhi(w.x); b[2] = bflo(w.y); b[3] = bfhi(w.y); b[4] = bflo(w.z); b[5] = bfhi(w.z); b[6] = bflo(w.w); b[7] = bfhi(w.w); }
;                     else { const f32x4 b0 = __builtin_nontemporal_load((const f32x4*)((const float*)base + off)), b1 = __builtin_nontemporal_load((const f32x4*)((const float*)base + off + 4)); b[0] = b0[0]; b[1] = b0[1]; b[2] = b0[2]; b[3] = b0[3]; b[4] = b1[0]; b[5] = b1[1]; b[6] = b1[2]; b[7] = b1[3]; }
;                     float h[8];
; #pragma unroll
;                     for (int j = 0; j < 4; ++j) { h[j] = b[j] + acc[ai][bj][m][0][j]; h[4 + j] = b[4 + j] + acc[ai][bj][m][1][j]; }
; #pragma unroll
;                     for (int j = 0; j < 8; ++j) ss += h[j] * h[j];
;                     u32x4 w; w.x = cvt_pk_bf16(h[0], h[1]); w.y = cvt_pk_bf16(h[2], h[3]); w.z = cvt_pk_bf16(h[4], h[5]); w.w = cvt_pk_bf16(h[6], h[7]);
;                     *(u32x4*)(Hb + off) = w; }
;                 ss += __shfl_xor(ss, 16); ss += __shfl_xor(ss, 32);
;                 if (fq == 0) unsafeAtomicAdd(sumsq + r, ss); }
.LBB0_1970:
	s_or_b64 exec, exec, s[8:9]
	v_add_u32_e32 v66, 0x80, v148
	s_waitcnt lgkmcnt(0)
	v_ashrrev_i32_e32 v67, 31, v66
	v_lshlrev_b64 v[72:73], 11, v[66:67]
	v_lshl_add_u64 v[68:69], v[72:73], 0, v[146:147]
	v_lshlrev_b64 v[74:75], 1, v[68:69]
	v_lshl_add_u64 v[68:69], s[18:19], 0, v[74:75]
	global_load_dwordx4 v[68:71], v[68:69], off
	v_lshl_add_u64 v[72:73], v[72:73], 0, v[150:151]
	v_lshlrev_b64 v[72:73], 1, v[72:73]
	v_lshl_add_u64 v[74:75], s[20:21], 0, v[74:75]
	v_lshl_add_u64 v[76:77], s[18:19], 0, v[72:73]
	s_waitcnt vmcnt(0)
	v_lshlrev_b32_e32 v78, 16, v68
	v_and_b32_e32 v68, 0xffff0000, v68
	v_lshlrev_b32_e32 v79, 16, v69
	v_and_b32_e32 v69, 0xffff0000, v69
	v_lshlrev_b32_e32 v80, 16, v70
	v_and_b32_e32 v70, 0xffff0000, v70
	v_lshlrev_b32_e32 v81, 16, v71
	v_and_b32_e32 v71, 0xffff0000, v71
	v_add_f32_e32 v62, v62, v78
	v_add_f32_e32 v78, v58, v80
	v_add_f32_e32 v63, v63, v68
	v_add_f32_e32 v68, v59, v70
	v_add_f32_e32 v64, v64, v79
	v_add_f32_e32 v70, v60, v81
	v_add_f32_e32 v65, v65, v69
	v_add_f32_e32 v69, v61, v71
	v_cvt_pk_bf16_f32 v58, v62, v63
	v_cvt_pk_bf16_f32 v59, v64, v65
	v_cvt_pk_bf16_f32 v60, v78, v68
	v_cvt_pk_bf16_f32 v61, v70, v69
	global_store_dwordx4 v[74:75], v[58:61], off sc1
	global_load_dwordx4 v[58:61], v[76:77], off
	v_mul_f32_e32 v63, v63, v63
	v_fmac_f32_e32 v63, v62, v62
	v_fmac_f32_e32 v63, v64, v64
	v_fmac_f32_e32 v63, v65, v65
	v_fmac_f32_e32 v63, v78, v78
	v_fmac_f32_e32 v63, v68, v68
	v_fmac_f32_e32 v63, v70, v70
	v_fmac_f32_e32 v63, v69, v69
	s_waitcnt vmcnt(0)
	v_lshlrev_b32_e32 v62, 16, v58
	v_and_b32_e32 v58, 0xffff0000, v58
	v_lshlrev_b32_e32 v65, 16, v60
	v_add_f32_e32 v54, v54, v62
	v_lshlrev_b32_e32 v64, 16, v59
	v_and_b32_e32 v60, 0xffff0000, v60
	v_add_f32_e32 v62, v50, v65
	v_add_f32_e32 v50, v55, v58
	v_fmac_f32_e32 v63, v54, v54
	v_and_b32_e32 v59, 0xffff0000, v59
	v_add_f32_e32 v55, v51, v60
	v_add_f32_e32 v51, v56, v64
	v_fmac_f32_e32 v63, v50, v50
	v_add_f32_e32 v57, v57, v59
	v_fmac_f32_e32 v63, v51, v51
	v_fmac_f32_e32 v63, v57, v57
	v_lshlrev_b32_e32 v68, 16, v61
	v_fmac_f32_e32 v63, v62, v62
	v_and_b32_e32 v61, 0xffff0000, v61
	v_add_f32_e32 v56, v52, v68
	v_fmac_f32_e32 v63, v55, v55
	v_add_f32_e32 v58, v53, v61
	v_fmac_f32_e32 v63, v56, v56
	v_fmac_f32_e32 v63, v58, v58
	ds_bpermute_b32 v59, v122, v63
	v_cvt_pk_bf16_f32 v52, v54, v50
	v_cvt_pk_bf16_f32 v53, v51, v57
	v_cvt_pk_bf16_f32 v54, v62, v55
	v_cvt_pk_bf16_f32 v55, v56, v58
	s_waitcnt lgkmcnt(0)
	v_add_f32_e32 v50, v63, v59
	ds_bpermute_b32 v51, v116, v50
	v_lshl_add_u64 v[56:57], s[20:21], 0, v[72:73]
	global_store_dwordx4 v[56:57], v[52:55], off sc1
	s_and_saveexec_b64 s[8:9], vcc
	s_cbranch_execz .LBB0_1972
	v_lshl_add_u64 v[52:53], v[66:67], 2, s[12:13]
	s_waitcnt lgkmcnt(0)
	v_add_f32_e32 v50, v50, v51
	global_atomic_add_f32 v[52:53], v50, off
.LBB0_1972:
	s_or_b64 exec, exec, s[8:9]
	v_add_u32_e32 v50, 0x90, v148
	s_waitcnt lgkmcnt(0)
	v_ashrrev_i32_e32 v51, 31, v50
	v_lshlrev_b64 v[56:57], 11, v[50:51]
	v_lshl_add_u64 v[52:53], v[56:57], 0, v[146:147]
	v_lshlrev_b64 v[58:59], 1, v[52:53]
	v_lshl_add_u64 v[52:53], s[18:19], 0, v[58:59]
	global_load_dwordx4 v[52:55], v[52:53], off
	v_lshl_add_u64 v[56:57], v[56:57], 0, v[150:151]
	v_lshlrev_b64 v[56:57], 1, v[56:57]
	v_lshl_add_u64 v[58:59], s[20:21], 0, v[58:59]
	v_lshl_add_u64 v[60:61], s[18:19], 0, v[56:57]
	s_waitcnt vmcnt(0)
	v_lshlrev_b32_e32 v62, 16, v52
	v_and_b32_e32 v52, 0xffff0000, v52
	v_lshlrev_b32_e32 v63, 16, v53
	v_and_b32_e32 v53, 0xffff0000, v53
	v_lshlrev_b32_e32 v64, 16, v54
	v_and_b32_e32 v54, 0xffff0000, v54
	v_lshlrev_b32_e32 v65, 16, v55
	v_and_b32_e32 v55, 0xffff0000, v55
	v_add_f32_e32 v46, v46, v62
	v_add_f32_e32 v62, v42, v64
	v_add_f32_e32 v47, v47, v52
	v_add_f32_e32 v52, v43, v54
	v_add_f32_e32 v48, v48, v63
	v_add_f32_e32 v54, v44, v65
	v_add_f32_e32 v49, v49, v53
	v_add_f32_e32 v53, v45, v55
	v_cvt_pk_bf16_f32 v42, v46, v47
	v_cvt_pk_bf16_f32 v43, v48, v49
	v_cvt_pk_bf16_f32 v44, v62, v52
	v_cvt_pk_bf16_f32 v45, v54, v53
	global_store_dwordx4 v[58:59], v[42:45], off sc1
	global_load_dwordx4 v[42:45], v[60:61], off
	v_mul_f32_e32 v47, v47, v47
	v_fmac_f32_e32 v47, v46, v46
	v_fmac_f32_e32 v47, v48, v48
	v_fmac_f32_e32 v47, v49, v49
	v_fmac_f32_e32 v47, v62, v62
	v_fmac_f32_e32 v47, v52, v52
	v_fmac_f32_e32 v47, v54, v54
	v_fmac_f32_e32 v47, v53, v53
	s_waitcnt vmcnt(0)
	v_lshlrev_b32_e32 v46, 16, v42
	v_and_b32_e32 v42, 0xffff0000, v42
	v_lshlrev_b32_e32 v49, 16, v44
	v_add_f32_e32 v38, v38, v46
	v_lshlrev_b32_e32 v48, 16, v43
	v_and_b32_e32 v44, 0xffff0000, v44
	v_add_f32_e32 v46, v34, v49
	v_add_f32_e32 v34, v39, v42
	v_fmac_f32_e32 v47, v38, v38
	v_and_b32_e32 v43, 0xffff0000, v43
	v_add_f32_e32 v39, v35, v44
	v_add_f32_e32 v35, v40, v48
	v_fmac_f32_e32 v47, v34, v34
	v_add_f32_e32 v41, v41, v43
	v_fmac_f32_e32 v47, v35, v35
	v_fmac_f32_e32 v47, v41, v41
	v_lshlrev_b32_e32 v52, 16, v45
	v_fmac_f32_e32 v47, v46, v46
	v_and_b32_e32 v45, 0xffff0000, v45
	v_add_f32_e32 v40, v36, v52
	v_fmac_f32_e32 v47, v39, v39
	v_add_f32_e32 v42, v37, v45
	v_fmac_f32_e32 v47, v40, v40
	v_fmac_f32_e32 v47, v42, v42
	ds_bpermute_b32 v43, v122, v47
	v_cvt_pk_bf16_f32 v36, v38, v34
	v_cvt_pk_bf16_f32 v37, v35, v41
	v_cvt_pk_bf16_f32 v38, v46, v39
	v_cvt_pk_bf16_f32 v39, v40, v42
	s_waitcnt lgkmcnt(0)
	v_add_f32_e32 v34, v47, v43
	ds_bpermute_b32 v35, v116, v34
	v_lshl_add_u64 v[40:41], s[20:21], 0, v[56:57]
	global_store_dwordx4 v[40:41], v[36:39], off sc1
	s_and_saveexec_b64 s[8:9], vcc
	s_cbranch_execz .LBB0_1974
	v_lshl_add_u64 v[36:37], v[50:51], 2, s[12:13]
	s_waitcnt lgkmcnt(0)
	v_add_f32_e32 v34, v34, v35
	global_atomic_add_f32 v[36:37], v34, off
; __device__ __forceinline__ unsigned cvt_pk_bf16(float lo, float hi) { unsigned r; asm volatile("v_cvt_pk_bf16_f32 %0, %1, %2" : "=v"(r) : "v"(lo), "v"(hi)); return r; }
;     __device__ __forceinline__ void operator()(const f32x4 (&acc)[2][2][4][2], const Unit& u, int wr, int wc, int fr, int fq) const {
;     ...
;             for (int m = 0; m < 4; ++m) { const int r = u.pm * BM + ai * HALF + wr * 64 + m * 16 + fr; float ss = 0.f;
; #pragma unroll
;                 for (int bj = 0; bj < 2; ++bj) { const int c8 = u.pn * BM + bj * HALF + wc * 32 + 8 * fq; const size_t off = (size_t)r * ldc + c8;
;                     float b[8];
;                     if (BF) { const u32x4 w = *(const u32x4*)((const bf16_t*)base + off); b[0] = bflo(w.x); b[1] = bfhi(w.x); b[2] = bflo(w.y); b[3] = bfhi(w.y); b[4] = bflo(w.z); b[5] = bfhi(w.z); b[6] = bflo(w.w); b[7] = bfhi(w.w); }
;                     else { const f32x4 b0 = __builtin_nontemporal_load((const f32x4*)((const float*)base + off)), b1 = __builtin_nontemporal_load((const f32x4*)((const float*)base + off + 4)); b[0] = b0[0]; b[1] = b0[1]; b[2] = b0[2]; b[3] = b0[3]; b[4] = b1[0]; b[5] = b1[1]; b[6] = b1[2]; b[7] = b1[3]; }
;                     float h[8];
; #pragma unroll
;                     for (int j = 0; j < 4; ++j) { h[j] = b[j] + acc[ai][bj][m][0][j]; h[4 + j] = b[4 + j] + acc[ai][bj][m][1][j]; }
; #pragma unroll
;                     for (int j = 0; j < 8; ++j) ss += h[j] * h[j];
;                     u32x4 w; w.x = cvt_pk_bf16(h[0], h[1]); w.y = cvt_pk_bf16(h[2], h[3]); w.z = cvt_pk_bf16(h[4], h[5]); w.w = cvt_pk_bf16(h[6], h[7]);
;                     *(u32x4*)(Hb + off) = w; }
;                 ss += __shfl_xor(ss, 16); ss += __shfl_xor(ss, 32);
;                 if (fq == 0) unsafeAtomicAdd(sumsq + r, ss); }
.LBB0_1974:
	s_or_b64 exec, exec, s[8:9]
	v_add_u32_e32 v34, 0xa0, v148
	s_waitcnt lgkmcnt(0)
	v_ashrrev_i32_e32 v35, 31, v34
	v_lshlrev_b64 v[40:41], 11, v[34:35]
	v_lshl_add_u64 v[36:37], v[40:41], 0, v[146:147]
	v_lshlrev_b64 v[42:43], 1, v[36:37]
	v_lshl_add_u64 v[36:37], s[18:19], 0, v[42:43]
	global_load_dwordx4 v[36:39], v[36:37], off
	v_lshl_add_u64 v[40:41], v[40:41], 0, v[150:151]
	v_lshlrev_b64 v[40:41], 1, v[40:41]
	v_lshl_add_u64 v[42:43], s[20:21], 0, v[42:43]
	v_lshl_add_u64 v[44:45], s[18:19], 0, v[40:41]
	s_waitcnt vmcnt(0)
	v_lshlrev_b32_e32 v46, 16, v36
	v_and_b32_e32 v36, 0xffff0000, v36
	v_lshlrev_b32_e32 v47, 16, v37
	v_and_b32_e32 v37, 0xffff0000, v37
	v_lshlrev_b32_e32 v48, 16, v38
	v_and_b32_e32 v38, 0xffff0000, v38
	v_lshlrev_b32_e32 v49, 16, v39
	v_and_b32_e32 v39, 0xffff0000, v39
	v_add_f32_e32 v30, v30, v46
	v_add_f32_e32 v46, v26, v48
	v_add_f32_e32 v31, v31, v36
	v_add_f32_e32 v36, v27, v38
	v_add_f32_e32 v32, v32, v47
	v_add_f32_e32 v38, v28, v49
	v_add_f32_e32 v33, v33, v37
	v_add_f32_e32 v37, v29, v39
	v_cvt_pk_bf16_f32 v26, v30, v31
	v_cvt_pk_bf16_f32 v27, v32, v33
	v_cvt_pk_bf16_f32 v28, v46, v36
	v_cvt_pk_bf16_f32 v29, v38, v37
	global_store_dwordx4 v[42:43], v[26:29], off sc1
	global_load_dwordx4 v[26:29], v[44:45], off
	v_mul_f32_e32 v31, v31, v31
	v_fmac_f32_e32 v31, v30, v30
	v_fmac_f32_e32 v31, v32, v32
	v_fmac_f32_e32 v31, v33, v33
	v_fmac_f32_e32 v31, v46, v46
	v_fmac_f32_e32 v31, v36, v36
	v_fmac_f32_e32 v31, v38, v38
	v_fmac_f32_e32 v31, v37, v37
	s_waitcnt vmcnt(0)
	v_lshlrev_b32_e32 v30, 16, v26
	v_and_b32_e32 v26, 0xffff0000, v26
	v_lshlrev_b32_e32 v33, 16, v28
	v_add_f32_e32 v22, v22, v30
	v_lshlrev_b32_e32 v32, 16, v27
	v_and_b32_e32 v28, 0xffff0000, v28
	v_add_f32_e32 v30, v18, v33
	v_add_f32_e32 v18, v23, v26
	v_fmac_f32_e32 v31, v22, v22
	v_and_b32_e32 v27, 0xffff0000, v27
	v_add_f32_e32 v23, v19, v28
	v_add_f32_e32 v19, v24, v32
	v_fmac_f32_e32 v31, v18, v18
	v_add_f32_e32 v25, v25, v27
	v_fmac_f32_e32 v31, v19, v19
	v_fmac_f32_e32 v31, v25, v25
	v_lshlrev_b32_e32 v36, 16, v29
	v_fmac_f32_e32 v31, v30, v30
	v_and_b32_e32 v29, 0xffff0000, v29
	v_add_f32_e32 v24, v20, v36
	v_fmac_f32_e32 v31, v23, v23
	v_add_f32_e32 v26, v21, v29
	v_fmac_f32_e32 v31, v24, v24
	v_fmac_f32_e32 v31, v26, v26
	ds_bpermute_b32 v27, v122, v31
	v_cvt_pk_bf16_f32 v20, v22, v18
	v_cvt_pk_bf16_f32 v21, v19, v25
	v_cvt_pk_bf16_f32 v22, v30, v23
	v_cvt_pk_bf16_f32 v23, v24, v26
	s_waitcnt lgkmcnt(0)
	v_add_f32_e32 v18, v31, v27
	ds_bpermute_b32 v19, v116, v18
	v_lshl_add_u64 v[24:25], s[20:21], 0, v[40:41]
	global_store_dwordx4 v[24:25], v[20:23], off sc1
	s_and_saveexec_b64 s[8:9], vcc
	s_cbranch_execz .LBB0_1976
	v_lshl_add_u64 v[20:21], v[34:35], 2, s[12:13]
	s_waitcnt lgkmcnt(0)
	v_add_f32_e32 v18, v18, v19
	global_atomic_add_f32 v[20:21], v18, off
.LBB0_1976:
	s_or_b64 exec, exec, s[8:9]
	v_add_u32_e32 v18, 0xb0, v148
	s_waitcnt lgkmcnt(0)
	v_ashrrev_i32_e32 v19, 31, v18
	v_lshlrev_b64 v[24:25], 11, v[18:19]
	v_lshl_add_u64 v[20:21], v[24:25], 0, v[146:147]
	v_lshlrev_b64 v[26:27], 1, v[20:21]
	v_lshl_add_u64 v[20:21], s[18:19], 0, v[26:27]
	global_load_dwordx4 v[20:23], v[20:21], off
	v_lshl_add_u64 v[24:25], v[24:25], 0, v[150:151]
	v_lshlrev_b64 v[24:25], 1, v[24:25]
	v_lshl_add_u64 v[26:27], s[20:21], 0, v[26:27]
	v_lshl_add_u64 v[28:29], s[18:19], 0, v[24:25]
	s_waitcnt vmcnt(0)
	v_lshlrev_b32_e32 v30, 16, v20
	v_and_b32_e32 v20, 0xffff0000, v20
	v_lshlrev_b32_e32 v31, 16, v21
	v_and_b32_e32 v21, 0xffff0000, v21
	v_lshlrev_b32_e32 v32, 16, v22
	v_and_b32_e32 v22, 0xffff0000, v22
	v_lshlrev_b32_e32 v33, 16, v23
	v_and_b32_e32 v23, 0xffff0000, v23
	v_add_f32_e32 v14, v14, v30
	v_add_f32_e32 v30, v10, v32
	v_add_f32_e32 v15, v15, v20
	v_add_f32_e32 v20, v11, v22
	v_add_f32_e32 v16, v16, v31
	v_add_f32_e32 v22, v12, v33
	v_add_f32_e32 v17, v17, v21
	v_add_f32_e32 v21, v13, v23
	v_cvt_pk_bf16_f32 v10, v14, v15
	v_cvt_pk_bf16_f32 v11, v16, v17
	v_cvt_pk_bf16_f32 v12, v30, v20
	v_cvt_pk_bf16_f32 v13, v22, v21
	global_store_dwordx4 v[26:27], v[10:13], off sc1
	global_load_dwordx4 v[10:13], v[28:29], off
	v_mul_f32_e32 v15, v15, v15
	v_fmac_f32_e32 v15, v14, v14
	v_fmac_f32_e32 v15, v16, v16
	v_fmac_f32_e32 v15, v17, v17
	v_fmac_f32_e32 v15, v30, v30
	v_fmac_f32_e32 v15, v20, v20
	v_fmac_f32_e32 v15, v22, v22
	v_fmac_f32_e32 v15, v21, v21
	s_waitcnt vmcnt(0)
	v_lshlrev_b32_e32 v14, 16, v10
	v_and_b32_e32 v10, 0xffff0000, v10
	v_lshlrev_b32_e32 v17, 16, v12
	v_add_f32_e32 v6, v6, v14
	v_lshlrev_b32_e32 v16, 16, v11
	v_and_b32_e32 v12, 0xffff0000, v12
	v_add_f32_e32 v14, v2, v17
	v_add_f32_e32 v2, v7, v10
	v_fmac_f32_e32 v15, v6, v6
	v_and_b32_e32 v11, 0xffff0000, v11
	v_add_f32_e32 v7, v3, v12
	v_add_f32_e32 v3, v8, v16
	v_fmac_f32_e32 v15, v2, v2
	v_add_f32_e32 v9, v9, v11
	v_fmac_f32_e32 v15, v3, v3
	v_fmac_f32_e32 v15, v9, v9
	v_lshlrev_b32_e32 v20, 16, v13
	v_fmac_f32_e32 v15, v14, v14
	v_and_b32_e32 v13, 0xffff0000, v13
	v_add_f32_e32 v8, v4, v20
	v_fmac_f32_e32 v15, v7, v7
	v_add_f32_e32 v10, v5, v13
	v_fmac_f32_e32 v15, v8, v8
	v_fmac_f32_e32 v15, v10, v10
	ds_bpermute_b32 v11, v122, v15
	v_cvt_pk_bf16_f32 v4, v6, v2
	v_cvt_pk_bf16_f32 v5, v3, v9
	v_cvt_pk_bf16_f32 v6, v14, v7
	v_cvt_pk_bf16_f32 v7, v8, v10
	s_waitcnt lgkmcnt(0)
	v_add_f32_e32 v2, v15, v11
	ds_bpermute_b32 v3, v116, v2
	v_lshl_add_u64 v[8:9], s[20:21], 0, v[24:25]
	global_store_dwordx4 v[8:9], v[4:7], off sc1
	s_and_saveexec_b64 s[8:9], vcc
	s_cbranch_execz .LBB0_1978
	v_lshl_add_u64 v[4:5], v[18:19], 2, s[12:13]
	s_waitcnt lgkmcnt(0)
	v_add_f32_e32 v2, v2, v3
	global_atomic_add_f32 v[4:5], v2, off
